# diff v2 (12 MFMA shadow, permlane max), diff unit prologue loads batched, P5 relu single max, SB cross-half exchange via permlane32_swap
# speedup vs baseline: 1.0247x; 1.0064x over previous
; #define LAS __attribute__((address_space(3)))
; __device__ __forceinline__ void diff_unit(const Frame& F, int b, int h, int qi, float lam, int dry) {
;     ...
;     { const bf16* qp = QA + (rowbase + tq) * 1024 + 128 * h + 64 * map + 8 * hi;
; #pragma unroll
;       for (int ks = 0; ks < 4; ++ks) qf[ks] = *(const bf16x8*)(qp + 16 * ks); }
;     const int srow = tid >> 4, sc16 = tid & 15;
;     const bf16* kg = KA + (rowbase + srow) * 1024 + 128 * h + sc16 * 8;
;     const bf16* vg = VA + (rowbase + srow) * 1024 + 128 * h + sc16 * 8;
;     const int klds = D_KOFF + srow * DK_STR + sc16 * 16, vlds = D_VOFF + srow * DV_STR + sc16 * 16;
;     u32x4 st0, st1, st2, st3;
;     ...
;     const int nt = 2 * qi + 3;
;     __syncthreads();
;     D_LOAD(0); D_STORE(0);
;     __syncthreads();
;     ...
;         if (it + 1 < nt) D_LOAD(NMETA + 64 * it);
;         const bool meta = (it == 0);
;         if (meta || key0 <= tqw + 31) {
;             const LAS unsigned char* kb = lds + kra + (it & 1) * DK_BUF;
;             const LAS unsigned char* vb = lds + vra + (it & 1) * DV_BUF;
;             f32x16 s0, s1;
; #pragma unroll
;             for (int r = 0; r < 16; ++r) { s0[r] = 0.f; s1[r] = 0.f; }
;             bf16x8 vpre0 = VFRAG(vb, 0, DV_STR), vpre1 = VFRAG(vb, 64, DV_STR), vpre2 = VFRAG(vb, 128, DV_STR), vpre3 = VFRAG(vb, 192, DV_STR);
;             bf16x8 vprf0 = VFRAG(vb, 16 * DV_STR, DV_STR), vprf1 = VFRAG(vb, 16 * DV_STR + 64, DV_STR);
;             __builtin_amdgcn_s_setprio(1);
; #pragma unroll
;             for (int ks = 0; ks < 4; ++ks) { const bf16x8 k0 = *(const LAS bf16x8*)(kb + ks * 32); s0 = MFMA32(k0, qf[ks], s0); }
;             if (!meta) {
; #pragma unroll
;                 for (int ks = 0; ks < 4; ++ks) { const bf16x8 k1 = *(const LAS bf16x8*)(kb + 32 * DK_STR + ks * 32); s1 = MFMA32(k1, qf[ks], s1); }
;             }
;             __builtin_amdgcn_s_setprio(0);
;             if (meta) {
; #pragma unroll
;                 for (int r = 8; r < 16; ++r) s0[r] = -INFINITY;
; #pragma unroll
;                 for (int r = 0; r < 16; ++r) s1[r] = -INFINITY;
;             } else if (key0 + 63 > tqw) {
; #pragma unroll
;                 for (int r = 0; r < 16; ++r) { const int c = (r & 3) + 8 * (r >> 2), lim = tq - key0 - 4 * hi; if (c > lim) s0[r] = -INFINITY; if (c + 32 > lim) s1[r] = -INFINITY; }
;             }
;             float mx = fmaxf(s0[0], s1[0]);
; #pragma unroll
.LBB0_292:
	s_and_b32 s90, s83, 15
	s_lshl_b32 s1, s90, 7
	v_readlane_b32 s2, v254, 56
	s_or_b32 s70, s2, s1
	s_or_b32 s1, s70, 16
	s_ashr_i32 s0, s83, 7
	v_add_u32_e32 v158, s1, v204
	v_writelane_b32 v254, s1, 63
	v_mad_i64_i32 v[0:1], s[2:3], s0, v220, v[158:159]
	v_readlane_b32 s2, v254, 32
	s_lshl_b32 s1, s83, 3
	v_lshlrev_b64 v[0:1], 11, v[0:1]
	v_readlane_b32 s3, v254, 33
	s_and_b32 s1, s1, 0x380
	s_lshl_b32 s74, s1, 1
	v_lshl_add_u64 v[0:1], s[2:3], 0, v[0:1]
	v_lshl_add_u64 v[0:1], v[0:1], 0, s[74:75]
	s_mov_b32 s95, s75
	v_lshl_add_u64 v[0:1], v[0:1], 0, s[94:95]
	v_mov_b32_e32 v153, v159
	v_lshl_add_u64 v[0:1], v[0:1], 0, v[152:153]
	global_load_dwordx4 v[96:99], v[0:1], off
	global_load_dwordx4 v[100:103], v[0:1], off offset:32
	global_load_dwordx4 v[104:107], v[0:1], off offset:64
	global_load_dwordx4 v[108:111], v[0:1], off offset:96
	v_mad_i64_i32 v[0:1], s[2:3], s0, v220, v[160:161]
	v_readlane_b32 s2, v254, 47
	v_lshlrev_b64 v[0:1], 11, v[0:1]
	v_readlane_b32 s3, v254, 48
	v_mov_b32_e32 v185, v159
	s_mov_b32 s1, 0x10000
	v_lshl_add_u64 v[2:3], s[2:3], 0, v[0:1]
	v_readlane_b32 s2, v254, 49
	v_readlane_b32 s3, v254, 50
	v_lshl_add_u64 v[2:3], v[2:3], 0, s[74:75]
	v_lshl_add_u64 v[188:189], v[2:3], 0, v[184:185]
	v_lshl_add_u64 v[0:1], s[2:3], 0, v[0:1]
	v_lshl_add_u64 v[0:1], v[0:1], 0, s[74:75]
	v_lshl_add_u64 v[190:191], v[0:1], 0, v[184:185]
	v_add_co_u32_e32 v0, vcc, s1, v188
	s_nop 1
	v_addc_co_u32_e32 v1, vcc, 0, v189, vcc
	global_load_dwordx4 v[0:3], v[0:1], off
	s_nop 0
	global_load_dwordx4 v[4:7], v[188:189], off
	global_load_dwordx4 v[8:11], v[190:191], off
	v_add_co_u32_e32 v12, vcc, s1, v190
	s_mov_b32 s1, 0x8000
	s_nop 0
	v_addc_co_u32_e32 v13, vcc, 0, v191, vcc
	global_load_dwordx4 v[12:15], v[12:13], off
	v_add_co_u32_e32 v16, vcc, s1, v188
	s_mov_b32 s2, 0x18000
	s_nop 0
	v_addc_co_u32_e32 v17, vcc, 0, v189, vcc
	v_add_co_u32_e32 v18, vcc, s2, v188
	s_nop 1
	v_addc_co_u32_e32 v19, vcc, 0, v189, vcc
	v_add_co_u32_e32 v20, vcc, s1, v190
	s_nop 1
	v_addc_co_u32_e32 v21, vcc, 0, v191, vcc
	v_add_co_u32_e32 v22, vcc, s2, v190
	s_nop 1
	v_addc_co_u32_e32 v23, vcc, 0, v191, vcc
	global_load_dwordx4 v[112:115], v[16:17], off
	global_load_dwordx4 v[116:119], v[18:19], off
	global_load_dwordx4 v[120:123], v[20:21], off
	global_load_dwordx4 v[124:127], v[22:23], off
	s_barrier
	s_waitcnt vmcnt(6)
	ds_write_b128 v209, v[4:7]
	ds_write_b128 v209, v[0:3] offset:8704
	s_waitcnt vmcnt(5)
	ds_write_b128 v210, v[8:11] offset:34816
	s_waitcnt vmcnt(4)
	ds_write_b128 v210, v[12:15] offset:45056
	s_waitcnt lgkmcnt(0)
	s_barrier
	ds_read_b64_tr_b16 v[32:33], v213 offset:34816
	ds_read_b64_tr_b16 v[64:65], v213 offset:34880
	ds_read_b64_tr_b16 v[72:73], v213 offset:34944
	ds_read_b64_tr_b16 v[68:69], v213 offset:35008
	ds_read_b64_tr_b16 v[34:35], v213 offset:37376
	ds_read_b64_tr_b16 v[66:67], v213 offset:37440
	ds_read_b64_tr_b16 v[74:75], v213 offset:37504
	ds_read_b64_tr_b16 v[70:71], v213 offset:37568
	s_setprio 1
	ds_read_b128 v[0:3], v212
	ds_read_b128 v[4:7], v212 offset:32
	s_waitcnt lgkmcnt(1)
	v_mfma_f32_32x32x16_bf16 v[16:31], v[0:3], v[96:99], 0
	s_waitcnt lgkmcnt(0)
	v_mfma_f32_32x32x16_bf16 v[16:31], v[4:7], v[100:103], v[16:31]
	ds_read_b128 v[0:3], v212 offset:64
	ds_read_b128 v[4:7], v212 offset:96
	s_waitcnt lgkmcnt(1)
	v_mfma_f32_32x32x16_bf16 v[16:31], v[0:3], v[104:107], v[16:31]
	s_waitcnt lgkmcnt(0)
	v_mfma_f32_32x32x16_bf16 v[16:31], v[4:7], v[108:111], v[16:31]
	s_setprio 0
	s_nop 10
	v_max_f32_e32 v0, v16, v16
	v_max_f32_e32 v1, v17, v17
	v_max_f32_e32 v2, v18, v18
	v_max_f32_e32 v0, 0xff800000, v0
	v_max_f32_e32 v1, 0xff800000, v1
	v_max_f32_e32 v2, 0xff800000, v2
	v_max3_f32 v0, v0, v1, v2
	v_max_f32_e32 v1, v19, v19
	v_max_f32_e32 v2, v20, v20
	v_max_f32_e32 v1, 0xff800000, v1
	v_max_f32_e32 v2, 0xff800000, v2
	v_max3_f32 v0, v0, v1, v2
	v_max_f32_e32 v1, v21, v21
	v_max_f32_e32 v2, v22, v22
	v_max_f32_e32 v1, 0xff800000, v1
	v_max_f32_e32 v2, 0xff800000, v2
	v_max3_f32 v0, v0, v1, v2
	v_max_f32_e32 v1, v23, v23
	v_max_f32_e32 v1, 0xff800000, v1
	s_mov_b32 s1, 0xff800000
	v_max3_f32 v0, v0, v1, s1
	ds_bpermute_b32 v1, v155, v0
	s_waitcnt lgkmcnt(0)
	v_max_f32_e32 v1, v1, v1
	v_max_f32_e32 v0, v0, v1
	v_mul_f32_e32 v0, 0x3fb8aa3b, v0
	v_cmp_neq_f32_e32 vcc, s1, v0
	s_cbranch_vccz .LBB0_294
	v_max_f32_e32 v0, v0, v0
	v_max_f32_e32 v185, 0xff800000, v0
	v_sub_f32_e32 v0, 0xff800000, v185
	v_exp_f32_e32 v0, v0
	s_nop 0
	v_mul_f32_e32 v1, 0, v0
	v_mov_b32_e32 v0, v1
	s_branch .LBB0_295

; #define LAS __attribute__((address_space(3)))
; #define MFMA32(a, b, c) __builtin_amdgcn_mfma_f32_32x32x16_bf16((a), (b), (c), 0, 0, 0)
; #define VFRAG(ptr, off0, STR) ({ const s16x4 lo_ = vtr((ptr) + (off0)); const s16x4 hi_ = vtr((ptr) + (off0) + 8 * (STR)); (bf16x8){lo_[0], lo_[1], lo_[2], lo_[3], hi_[0], hi_[1], hi_[2], hi_[3]}; })
; __device__ __forceinline__ void diff_unit(const Frame& F, int b, int h, int qi, float lam, int dry) {
;     ...
;             const LAS unsigned char* kb = lds + kra + (it & 1) * DK_BUF;
;             const LAS unsigned char* vb = lds + vra + (it & 1) * DV_BUF;
;             f32x16 s0, s1;
; #pragma unroll
;             for (int r = 0; r < 16; ++r) { s0[r] = 0.f; s1[r] = 0.f; }
;             bf16x8 vpre0 = VFRAG(vb, 0, DV_STR), vpre1 = VFRAG(vb, 64, DV_STR), vpre2 = VFRAG(vb, 128, DV_STR), vpre3 = VFRAG(vb, 192, DV_STR);
;             bf16x8 vprf0 = VFRAG(vb, 16 * DV_STR, DV_STR), vprf1 = VFRAG(vb, 16 * DV_STR + 64, DV_STR);
;             __builtin_amdgcn_s_setprio(1);
; #pragma unroll
;             for (int ks = 0; ks < 4; ++ks) { const bf16x8 k0 = *(const LAS bf16x8*)(kb + ks * 32); s0 = MFMA32(k0, qf[ks], s0); }
;             if (!meta) {
; #pragma unroll
;                 for (int ks = 0; ks < 4; ++ks) { const bf16x8 k1 = *(const LAS bf16x8*)(kb + 32 * DK_STR + ks * 32); s1 = MFMA32(k1, qf[ks], s1); }
;             }
;             __builtin_amdgcn_s_setprio(0);
;             if (meta) {
; #pragma unroll
;                 for (int r = 8; r < 16; ++r) s0[r] = -INFINITY;
; #pragma unroll
;                 for (int r = 0; r < 16; ++r) s1[r] = -INFINITY;
;             } else if (key0 + 63 > tqw) {
; #pragma unroll
;                 for (int r = 0; r < 16; ++r) { const int c = (r & 3) + 8 * (r >> 2), lim = tq - key0 - 4 * hi; if (c > lim) s0[r] = -INFINITY; if (c + 32 > lim) s1[r] = -INFINITY; }
;             }
.LBB0_301:
	s_add_i32 s0, s71, -1
	s_and_b32 s0, s0, 1
	s_mul_i32 s1, s0, 0x5000
	s_mulk_i32 s0, 0x4400
	v_add_u32_e32 v223, s0, v212
	v_add_u32_e32 v222, s1, v213
	ds_read_b128 v[64:67], v223
	ds_read_b128 v[68:71], v223 offset:32
	ds_read_b64_tr_b16 v[148:149], v222 offset:34816
	ds_read_b64_tr_b16 v[144:145], v222 offset:34880
	ds_read_b64_tr_b16 v[140:141], v222 offset:34944
	ds_read_b64_tr_b16 v[136:137], v222 offset:35008
	ds_read_b64_tr_b16 v[150:151], v222 offset:37376
	ds_read_b64_tr_b16 v[146:147], v222 offset:37440
	ds_read_b64_tr_b16 v[142:143], v222 offset:37504
	ds_read_b64_tr_b16 v[138:139], v222 offset:37568
	ds_read_b64_tr_b16 v[128:129], v222 offset:39936
	ds_read_b64_tr_b16 v[130:131], v222 offset:42496
	ds_read_b64_tr_b16 v[134:135], v222 offset:42560
	ds_read_b64_tr_b16 v[132:133], v222 offset:40000
	s_setprio 1
	s_waitcnt lgkmcnt(13)
	v_mfma_f32_32x32x16_bf16 v[80:95], v[64:67], v[96:99], 0
	s_waitcnt lgkmcnt(12)
	v_mfma_f32_32x32x16_bf16 v[80:95], v[68:71], v[100:103], v[80:95]
	ds_read_b128 v[64:67], v223 offset:64
	ds_read_b128 v[68:71], v223 offset:96
	s_waitcnt lgkmcnt(1)
	v_mfma_f32_32x32x16_bf16 v[80:95], v[64:67], v[104:107], v[80:95]
	ds_read_b128 v[64:67], v223 offset:8704
	ds_read_b128 v[224:227], v223 offset:8736
	s_waitcnt lgkmcnt(2)
	v_mfma_f32_32x32x16_bf16 v[80:95], v[68:71], v[108:111], v[80:95]
	s_waitcnt lgkmcnt(1)
	v_mfma_f32_32x32x16_bf16 v[64:79], v[64:67], v[96:99], 0
	s_waitcnt lgkmcnt(0)
	v_mfma_f32_32x32x16_bf16 v[64:79], v[224:227], v[100:103], v[64:79]
	ds_read_b128 v[224:227], v223 offset:8768
	ds_read_b128 v[228:231], v223 offset:8800
	s_waitcnt lgkmcnt(1)
	v_mfma_f32_32x32x16_bf16 v[64:79], v[224:227], v[104:107], v[64:79]
	s_waitcnt lgkmcnt(0)
	v_mfma_f32_32x32x16_bf16 v[64:79], v[228:231], v[108:111], v[64:79]
	s_setprio 0
	s_cmp_le_u32 s91, s10
	s_cbranch_scc1 .LBB0_303
	v_cmp_gt_i32_e64 s[60:61], s80, v153
	v_cmp_gt_i32_e64 s[62:63], s81, v153
	v_cmp_gt_i32_e64 s[58:59], s69, v153
	s_and_b64 s[60:61], s[62:63], s[60:61]
	v_cmp_gt_i32_e64 s[56:57], s68, v153
	s_and_b64 s[58:59], s[60:61], s[58:59]
	v_cmp_gt_i32_e64 s[54:55], s87, v153
	s_and_b64 s[56:57], s[58:59], s[56:57]
	v_cmp_gt_i32_e64 s[52:53], s86, v153
	s_and_b64 s[54:55], s[56:57], s[54:55]
	v_cmp_gt_i32_e64 s[50:51], s85, v153
	s_and_b64 s[52:53], s[54:55], s[52:53]
	v_cmp_gt_i32_e64 s[48:49], s79, v153
	s_and_b64 s[50:51], s[52:53], s[50:51]
	v_cmp_gt_i32_e64 s[46:47], s78, v153
	s_and_b64 s[48:49], s[50:51], s[48:49]
	v_cmp_gt_i32_e64 s[44:45], s77, v153
	s_and_b64 s[46:47], s[48:49], s[46:47]
	v_cmp_gt_i32_e64 s[42:43], s76, v153
	s_and_b64 s[44:45], s[46:47], s[44:45]
	v_cmp_gt_i32_e64 s[40:41], s96, v153
	s_and_b64 s[42:43], s[44:45], s[42:43]
	v_cmp_gt_i32_e64 s[38:39], s97, v153
	s_and_b64 s[40:41], s[42:43], s[40:41]
	v_cmp_gt_i32_e64 s[36:37], s93, v153
	s_and_b64 s[38:39], s[40:41], s[38:39]
	v_cmp_gt_i32_e64 s[34:35], s92, v153
	s_and_b64 s[36:37], s[38:39], s[36:37]
	v_cmp_gt_i32_e64 s[30:31], s11, v153
	s_and_b64 s[34:35], s[36:37], s[34:35]
	s_and_b64 s[30:31], s[34:35], s[30:31]
	v_cmp_gt_i32_e64 s[28:29], 10, v153
	v_cndmask_b32_e64 v80, v80, v221, s[30:31]
	v_cmp_gt_i32_e64 s[30:31], 11, v153
	v_cmp_gt_i32_e64 s[26:27], 9, v153
	s_and_b64 s[28:29], s[30:31], s[28:29]
	v_cmp_gt_i32_e64 s[24:25], 8, v153
	s_and_b64 s[26:27], s[28:29], s[26:27]
	v_cmp_gt_i32_e64 s[22:23], 3, v153
	s_and_b64 s[24:25], s[26:27], s[24:25]
	v_cmp_gt_i32_e64 s[20:21], 2, v153
	s_and_b64 s[22:23], s[24:25], s[22:23]
	v_cmp_gt_i32_e64 s[18:19], 1, v153
	s_and_b64 s[20:21], s[22:23], s[20:21]
	v_cmp_lt_u32_e64 s[16:17], s84, v153
	s_and_b64 s[18:19], s[20:21], s[18:19]
	v_cmp_gt_i32_e64 s[14:15], -5, v153
	s_and_b64 s[16:17], s[18:19], s[16:17]
	v_cmp_gt_i32_e64 s[12:13], -6, v153
	s_and_b64 s[14:15], s[16:17], s[14:15]
	v_cmp_gt_i32_e64 s[8:9], -7, v153
	s_and_b64 s[12:13], s[14:15], s[12:13]
	v_cmp_gt_i32_e64 s[6:7], -8, v153
	s_and_b64 s[8:9], s[12:13], s[8:9]
	v_cmp_gt_i32_e64 s[4:5], -13, v153
	s_and_b64 s[6:7], s[8:9], s[6:7]
	v_cmp_gt_i32_e64 s[2:3], -14, v153
	s_and_b64 s[4:5], s[6:7], s[4:5]
	v_cmp_gt_i32_e64 s[0:1], -15, v153
	s_and_b64 s[2:3], s[4:5], s[2:3]
	v_cmp_gt_i32_e32 vcc, -16, v153
	s_and_b64 s[0:1], s[2:3], s[0:1]
	s_and_b64 vcc, s[0:1], vcc
	v_cndmask_b32_e64 v95, v95, v221, s[62:63]
	v_cndmask_b32_e64 v94, v94, v221, s[60:61]
	v_cndmask_b32_e64 v93, v93, v221, s[58:59]
	v_cndmask_b32_e64 v92, v92, v221, s[56:57]
	v_cndmask_b32_e64 v91, v91, v221, s[54:55]
	v_cndmask_b32_e64 v90, v90, v221, s[52:53]
	v_cndmask_b32_e64 v89, v89, v221, s[50:51]
	v_cndmask_b32_e64 v88, v88, v221, s[48:49]
	v_cndmask_b32_e64 v87, v87, v221, s[46:47]
	v_cndmask_b32_e64 v86, v86, v221, s[44:45]
	v_cndmask_b32_e64 v85, v85, v221, s[42:43]
	v_cndmask_b32_e64 v84, v84, v221, s[40:41]
	v_cndmask_b32_e64 v83, v83, v221, s[38:39]
	v_cndmask_b32_e64 v82, v82, v221, s[36:37]
	v_cndmask_b32_e64 v81, v81, v221, s[34:35]
	v_cndmask_b32_e64 v79, v79, v221, s[30:31]
	v_cndmask_b32_e64 v78, v78, v221, s[28:29]
	v_cndmask_b32_e64 v77, v77, v221, s[26:27]
	v_cndmask_b32_e64 v76, v76, v221, s[24:25]
	v_cndmask_b32_e64 v75, v75, v221, s[22:23]
	v_cndmask_b32_e64 v74, v74, v221, s[20:21]
	v_cndmask_b32_e64 v73, v73, v221, s[18:19]
	v_cndmask_b32_e64 v72, v72, v221, s[16:17]
	v_cndmask_b32_e64 v71, v71, v221, s[14:15]
	v_cndmask_b32_e64 v70, v70, v221, s[12:13]
	v_cndmask_b32_e64 v69, v69, v221, s[8:9]
	v_cndmask_b32_e64 v68, v68, v221, s[6:7]
	v_cndmask_b32_e64 v67, v67, v221, s[4:5]
	v_cndmask_b32_e64 v66, v66, v221, s[2:3]
	v_cndmask_b32_e64 v65, v65, v221, s[0:1]
	v_cndmask_b32_e32 v64, v64, v221, vcc
; __device__ __forceinline__ void diff_unit(const Frame& F, int b, int h, int qi, float lam, int dry) {
;     ...
;             float mx = fmaxf(s0[0], s1[0]);
; #pragma unroll
;             for (int r = 1; r < 16; ++r) mx = fmaxf(mx, fmaxf(s0[r], s1[r]));
;             mx = fmaxf(mx, __shfl_xor(mx, 32));
;             const float mxs = mx * LOG2E;
;             if (__any(mxs > ms + 8.0f)) {
;                 const float msn = fmaxf(ms, mxs); const float f = __builtin_amdgcn_exp2f(ms - msn); lsum *= f; ms = msn;
; #pragma unroll
;                 for (int dt = 0; dt < 4; ++dt)
; #pragma unroll
;                     for (int r = 0; r < 16; ++r) O[dt][r] *= f;
;             }
.LBB0_303:
	v_max3_f32 v223, v80, v81, v82
	v_max3_f32 v223, v223, v83, v84
	v_max3_f32 v223, v223, v85, v86
	v_max3_f32 v223, v223, v87, v88
	v_max3_f32 v223, v223, v89, v90
	v_max3_f32 v223, v223, v91, v92
	v_max3_f32 v223, v223, v93, v94
	s_nop 2
	v_max3_f32 v224, v64, v65, v66
	v_max3_f32 v224, v224, v67, v68
	v_max3_f32 v224, v224, v69, v70
	v_max3_f32 v224, v224, v71, v72
	v_max3_f32 v224, v224, v73, v74
	v_max3_f32 v224, v224, v75, v76
	v_max3_f32 v224, v224, v77, v78
	v_max3_f32 v223, v223, v224, v95
	v_max_f32_e32 v223, v223, v79
	v_mov_b32_e32 v224, v223
	s_nop 1
	v_permlane32_swap_b32_e32 v223, v224
	v_max_f32_e32 v223, v223, v224
	v_mul_f32_e32 v223, 0x3fb8aa3b, v223
	v_add_f32_e32 v224, 0x41000000, v185
	v_cmp_gt_f32_e32 vcc, v223, v224
	s_cbranch_vccz .LBB0_305
	v_max_f32_e32 v223, v223, v223
	v_max_f32_e32 v224, v185, v185
	v_max_f32_e32 v223, v224, v223
	v_sub_f32_e32 v185, v185, v223
	v_exp_f32_e32 v224, v185
	v_mov_b32_e32 v185, v223
	v_pk_mul_f32 v[62:63], v[62:63], v[224:225] op_sel_hi:[1,0]
	v_pk_mul_f32 v[60:61], v[60:61], v[224:225] op_sel_hi:[1,0]
	v_pk_mul_f32 v[58:59], v[58:59], v[224:225] op_sel_hi:[1,0]
	v_pk_mul_f32 v[56:57], v[56:57], v[224:225] op_sel_hi:[1,0]
	v_pk_mul_f32 v[54:55], v[54:55], v[224:225] op_sel_hi:[1,0]
	v_pk_mul_f32 v[52:53], v[52:53], v[224:225] op_sel_hi:[1,0]
	v_pk_mul_f32 v[50:51], v[50:51], v[224:225] op_sel_hi:[1,0]
	v_pk_mul_f32 v[48:49], v[48:49], v[224:225] op_sel_hi:[1,0]
	v_pk_mul_f32 v[46:47], v[46:47], v[224:225] op_sel_hi:[1,0]
	v_pk_mul_f32 v[44:45], v[44:45], v[224:225] op_sel_hi:[1,0]
	v_pk_mul_f32 v[42:43], v[42:43], v[224:225] op_sel_hi:[1,0]
	v_pk_mul_f32 v[40:41], v[40:41], v[224:225] op_sel_hi:[1,0]
	v_pk_mul_f32 v[38:39], v[38:39], v[224:225] op_sel_hi:[1,0]
	v_pk_mul_f32 v[36:37], v[36:37], v[224:225] op_sel_hi:[1,0]
	v_pk_mul_f32 v[34:35], v[34:35], v[224:225] op_sel_hi:[1,0]
	v_pk_mul_f32 v[32:33], v[32:33], v[224:225] op_sel_hi:[1,0]
	v_pk_mul_f32 v[30:31], v[30:31], v[224:225] op_sel_hi:[1,0]
	v_pk_mul_f32 v[28:29], v[28:29], v[224:225] op_sel_hi:[1,0]
	v_pk_mul_f32 v[26:27], v[26:27], v[224:225] op_sel_hi:[1,0]
	v_pk_mul_f32 v[24:25], v[24:25], v[224:225] op_sel_hi:[1,0]
	v_pk_mul_f32 v[22:23], v[22:23], v[224:225] op_sel_hi:[1,0]
	v_pk_mul_f32 v[20:21], v[20:21], v[224:225] op_sel_hi:[1,0]
	v_pk_mul_f32 v[18:19], v[18:19], v[224:225] op_sel_hi:[1,0]
	v_pk_mul_f32 v[16:17], v[16:17], v[224:225] op_sel_hi:[1,0]
	v_pk_mul_f32 v[14:15], v[14:15], v[224:225] op_sel_hi:[1,0]
	v_pk_mul_f32 v[12:13], v[12:13], v[224:225] op_sel_hi:[1,0]
	v_pk_mul_f32 v[10:11], v[10:11], v[224:225] op_sel_hi:[1,0]
	v_pk_mul_f32 v[8:9], v[8:9], v[224:225] op_sel_hi:[1,0]
	v_pk_mul_f32 v[6:7], v[6:7], v[224:225] op_sel_hi:[1,0]
	v_pk_mul_f32 v[4:5], v[4:5], v[224:225] op_sel_hi:[1,0]
	v_pk_mul_f32 v[2:3], v[2:3], v[224:225] op_sel_hi:[1,0]
	v_pk_mul_f32 v[0:1], v[0:1], v[224:225] op_sel_hi:[1,0]
	v_mul_f32_e32 v158, v158, v224
; #define MFMA32(a, b, c) __builtin_amdgcn_mfma_f32_32x32x16_bf16((a), (b), (c), 0, 0, 0)
; #define VFRAG(ptr, off0, STR) ({ const s16x4 lo_ = vtr((ptr) + (off0)); const s16x4 hi_ = vtr((ptr) + (off0) + 8 * (STR)); (bf16x8){lo_[0], lo_[1], lo_[2], lo_[3], hi_[0], hi_[1], hi_[2], hi_[3]}; })
; __device__ __forceinline__ void diff_unit(const Frame& F, int b, int h, int qi, float lam, int dry) {
;     ...
;             float ps = 0.f;
; #pragma unroll
;             for (int r = 0; r < 16; ++r) { s0[r] = __builtin_amdgcn_exp2f(s0[r] * LOG2E - ms); ps += s0[r]; }
;             if (!meta) {
; #pragma unroll
;                 for (int r = 0; r < 16; ++r) { s1[r] = __builtin_amdgcn_exp2f(s1[r] * LOG2E - ms); ps += s1[r]; }
;             }
;             lsum += ps;
;             __builtin_amdgcn_s_setprio(1);
;             { const bf16x8 pf = pack_step(s0, 0);
;               O[0] = MFMA32(vpre0, pf, O[0]); O[1] = MFMA32(vpre1, pf, O[1]); O[2] = MFMA32(vpre2, pf, O[2]); O[3] = MFMA32(vpre3, pf, O[3]); }
;             if (!meta) {
;                 { const bf16x8 pf = pack_step(s0, 1);
;                   O[0] = MFMA32(vprf0, pf, O[0]); O[1] = MFMA32(vprf1, pf, O[1]);
; #pragma unroll
;                   for (int dt = 2; dt < 4; ++dt) { const bf16x8 vf = VFRAG(vb, 16 * DV_STR + 64 * dt, DV_STR); O[dt] = MFMA32(vf, pf, O[dt]); } }
; #pragma unroll
;                 for (int s2 = 0; s2 < 2; ++s2) { const bf16x8 pf = pack_step(s1, s2);
; #pragma unroll
;                     for (int dt = 0; dt < 4; ++dt) { const bf16x8 vf = VFRAG(vb, (32 + 16 * s2) * DV_STR + 64 * dt, DV_STR); O[dt] = MFMA32(vf, pf, O[dt]); } }
;             }
;             __builtin_amdgcn_s_setprio(0);
.LBB0_305:
	ds_read_b64_tr_b16 v[224:225], v222 offset:40064
	ds_read_b64_tr_b16 v[226:227], v222 offset:42624
	ds_read_b64_tr_b16 v[228:229], v222 offset:40128
	ds_read_b64_tr_b16 v[230:231], v222 offset:42688
	v_fma_f32 v80, v80, s88, -v185
	v_fma_f32 v81, v81, s88, -v185
	v_fma_f32 v82, v82, s88, -v185
	v_fma_f32 v83, v83, s88, -v185
	v_exp_f32_e32 v80, v80
	v_exp_f32_e32 v81, v81
	v_exp_f32_e32 v82, v82
	v_exp_f32_e32 v83, v83
	v_fma_f32 v84, v84, s88, -v185
	v_fma_f32 v85, v85, s88, -v185
	v_fma_f32 v86, v86, s88, -v185
	v_fma_f32 v87, v87, s88, -v185
	v_exp_f32_e32 v84, v84
	v_exp_f32_e32 v85, v85
	v_exp_f32_e32 v86, v86
	v_exp_f32_e32 v87, v87
	v_pk_add_f32 v[236:237], v[80:81], v[82:83]
	s_setprio 1
	v_cvt_pk_bf16_f32 v232, v80, v81
	v_cvt_pk_bf16_f32 v233, v82, v83
	v_cvt_pk_bf16_f32 v234, v84, v85
	v_cvt_pk_bf16_f32 v235, v86, v87
	v_pk_add_f32 v[236:237], v[236:237], v[84:85]
	v_pk_add_f32 v[236:237], v[236:237], v[86:87]
	v_mfma_f32_32x32x16_bf16 v[48:63], v[148:151], v[232:235], v[48:63]
	ds_read_b64_tr_b16 v[148:149], v222 offset:45056
	ds_read_b64_tr_b16 v[150:151], v222 offset:47616
	v_fma_f32 v88, v88, s88, -v185
	v_fma_f32 v89, v89, s88, -v185
	v_exp_f32_e32 v88, v88
	v_exp_f32_e32 v89, v89
	v_mfma_f32_32x32x16_bf16 v[32:47], v[144:147], v[232:235], v[32:47]
	ds_read_b64_tr_b16 v[144:145], v222 offset:45120
	ds_read_b64_tr_b16 v[146:147], v222 offset:47680
	v_fma_f32 v90, v90, s88, -v185
	v_fma_f32 v91, v91, s88, -v185
	v_exp_f32_e32 v90, v90
	v_exp_f32_e32 v91, v91
	v_pk_add_f32 v[236:237], v[236:237], v[88:89]
	v_cvt_pk_bf16_f32 v80, v88, v89
	v_mfma_f32_32x32x16_bf16 v[16:31], v[140:143], v[232:235], v[16:31]
	ds_read_b64_tr_b16 v[140:141], v222 offset:45184
	ds_read_b64_tr_b16 v[142:143], v222 offset:47744
	v_fma_f32 v92, v92, s88, -v185
	v_fma_f32 v93, v93, s88, -v185
	v_exp_f32_e32 v92, v92
	v_exp_f32_e32 v93, v93
	v_pk_add_f32 v[236:237], v[236:237], v[90:91]
	v_cvt_pk_bf16_f32 v81, v90, v91
	v_mfma_f32_32x32x16_bf16 v[0:15], v[136:139], v[232:235], v[0:15]
	ds_read_b64_tr_b16 v[136:137], v222 offset:45248
	ds_read_b64_tr_b16 v[138:139], v222 offset:47808
	v_fma_f32 v94, v94, s88, -v185
	v_fma_f32 v95, v95, s88, -v185
	v_exp_f32_e32 v94, v94
	v_exp_f32_e32 v95, v95
	v_pk_add_f32 v[236:237], v[236:237], v[92:93]
	v_cvt_pk_bf16_f32 v82, v92, v93
	v_cvt_pk_bf16_f32 v83, v94, v95
	v_pk_add_f32 v[236:237], v[236:237], v[94:95]
	s_nop 0
	v_mfma_f32_32x32x16_bf16 v[48:63], v[128:131], v[80:83], v[48:63]
	ds_read_b64_tr_b16 v[128:129], v222 offset:50176
	ds_read_b64_tr_b16 v[130:131], v222 offset:52736
	v_fma_f32 v64, v64, s88, -v185
	v_fma_f32 v65, v65, s88, -v185
	v_exp_f32_e32 v64, v64
	v_exp_f32_e32 v65, v65
	v_mfma_f32_32x32x16_bf16 v[32:47], v[132:135], v[80:83], v[32:47]
	ds_read_b64_tr_b16 v[132:133], v222 offset:50240
	ds_read_b64_tr_b16 v[134:135], v222 offset:52800
	v_fma_f32 v66, v66, s88, -v185
	v_fma_f32 v67, v67, s88, -v185
	v_exp_f32_e32 v66, v66
	v_exp_f32_e32 v67, v67
	v_pk_add_f32 v[236:237], v[236:237], v[64:65]
	v_cvt_pk_bf16_f32 v84, v64, v65
	s_waitcnt lgkmcnt(14)
	v_mfma_f32_32x32x16_bf16 v[16:31], v[224:227], v[80:83], v[16:31]
	ds_read_b64_tr_b16 v[224:225], v222 offset:50304
	ds_read_b64_tr_b16 v[226:227], v222 offset:52864
	v_fma_f32 v68, v68, s88, -v185
	v_fma_f32 v69, v69, s88, -v185
	v_exp_f32_e32 v68, v68
	v_exp_f32_e32 v69, v69
	v_pk_add_f32 v[236:237], v[236:237], v[66:67]
	v_cvt_pk_bf16_f32 v85, v66, v67
	s_waitcnt lgkmcnt(14)
	v_mfma_f32_32x32x16_bf16 v[0:15], v[228:231], v[80:83], v[0:15]
	ds_read_b64_tr_b16 v[228:229], v222 offset:50368
	ds_read_b64_tr_b16 v[230:231], v222 offset:52928
	v_fma_f32 v70, v70, s88, -v185
	v_fma_f32 v71, v71, s88, -v185
	v_exp_f32_e32 v70, v70
	v_exp_f32_e32 v71, v71
	v_pk_add_f32 v[236:237], v[236:237], v[68:69]
	v_cvt_pk_bf16_f32 v86, v68, v69
	v_cvt_pk_bf16_f32 v87, v70, v71
	v_pk_add_f32 v[236:237], v[236:237], v[70:71]
	s_nop 0
	s_waitcnt lgkmcnt(14)
	v_mfma_f32_32x32x16_bf16 v[48:63], v[148:151], v[84:87], v[48:63]
	v_fma_f32 v72, v72, s88, -v185
	v_fma_f32 v73, v73, s88, -v185
	v_exp_f32_e32 v72, v72
	v_exp_f32_e32 v73, v73
	s_waitcnt lgkmcnt(12)
	v_mfma_f32_32x32x16_bf16 v[32:47], v[144:147], v[84:87], v[32:47]
	v_fma_f32 v74, v74, s88, -v185
	v_fma_f32 v75, v75, s88, -v185
	v_exp_f32_e32 v74, v74
	v_exp_f32_e32 v75, v75
	v_pk_add_f32 v[236:237], v[236:237], v[72:73]
	v_cvt_pk_bf16_f32 v232, v72, v73
	s_waitcnt lgkmcnt(10)
	v_mfma_f32_32x32x16_bf16 v[16:31], v[140:143], v[84:87], v[16:31]
	v_fma_f32 v76, v76, s88, -v185
	v_fma_f32 v77, v77, s88, -v185
	v_exp_f32_e32 v76, v76
	v_exp_f32_e32 v77, v77
	v_pk_add_f32 v[236:237], v[236:237], v[74:75]
	v_cvt_pk_bf16_f32 v233, v74, v75
	s_waitcnt lgkmcnt(8)
	v_mfma_f32_32x32x16_bf16 v[0:15], v[136:139], v[84:87], v[0:15]
	v_fma_f32 v78, v78, s88, -v185
	v_fma_f32 v79, v79, s88, -v185
	v_exp_f32_e32 v78, v78
	v_exp_f32_e32 v79, v79
	v_pk_add_f32 v[236:237], v[236:237], v[76:77]
	v_cvt_pk_bf16_f32 v234, v76, v77
	v_cvt_pk_bf16_f32 v235, v78, v79
	v_pk_add_f32 v[236:237], v[236:237], v[78:79]
	v_add_f32_e32 v223, v236, v237
	v_add_f32_e32 v158, v158, v223
	s_waitcnt lgkmcnt(6)
	v_mfma_f32_32x32x16_bf16 v[48:63], v[128:131], v[232:235], v[48:63]
	s_waitcnt lgkmcnt(4)
	v_mfma_f32_32x32x16_bf16 v[32:47], v[132:135], v[232:235], v[32:47]
	s_waitcnt lgkmcnt(2)
	v_mfma_f32_32x32x16_bf16 v[16:31], v[224:227], v[232:235], v[16:31]
	s_waitcnt lgkmcnt(0)
	v_mfma_f32_32x32x16_bf16 v[0:15], v[228:231], v[232:235], v[0:15]
	s_setprio 0
	s_andn2_b64 vcc, exec, s[66:67]
	s_cbranch_vccnz .LBB0_296

; #define LAS __attribute__((address_space(3)))
; __device__ __forceinline__ void diff_unit(const Frame& F, int b, int h, int qi, float lam, int dry) {
;     ...
;     { const bf16* qp = QA + (rowbase + tq) * 1024 + 128 * h + 64 * map + 8 * hi;
; #pragma unroll
;       for (int ks = 0; ks < 4; ++ks) qf[ks] = *(const bf16x8*)(qp + 16 * ks); }
;     const int srow = tid >> 4, sc16 = tid & 15;
;     const bf16* kg = KA + (rowbase + srow) * 1024 + 128 * h + sc16 * 8;
;     const bf16* vg = VA + (rowbase + srow) * 1024 + 128 * h + sc16 * 8;
;     const int klds = D_KOFF + srow * DK_STR + sc16 * 16, vlds = D_VOFF + srow * DV_STR + sc16 * 16;
;     u32x4 st0, st1, st2, st3;
;     ...
;     const int nt = 2 * qi + 3;
;     __syncthreads();
;     D_LOAD(0); D_STORE(0);
;     __syncthreads();
;     ...
;         if (it + 1 < nt) D_LOAD(NMETA + 64 * it);
;         const bool meta = (it == 0);
;         if (meta || key0 <= tqw + 31) {
;             const LAS unsigned char* kb = lds + kra + (it & 1) * DK_BUF;
;             const LAS unsigned char* vb = lds + vra + (it & 1) * DV_BUF;
;             f32x16 s0, s1;
; #pragma unroll
;             for (int r = 0; r < 16; ++r) { s0[r] = 0.f; s1[r] = 0.f; }
;             bf16x8 vpre0 = VFRAG(vb, 0, DV_STR), vpre1 = VFRAG(vb, 64, DV_STR), vpre2 = VFRAG(vb, 128, DV_STR), vpre3 = VFRAG(vb, 192, DV_STR);
;             bf16x8 vprf0 = VFRAG(vb, 16 * DV_STR, DV_STR), vprf1 = VFRAG(vb, 16 * DV_STR + 64, DV_STR);
;             __builtin_amdgcn_s_setprio(1);
; #pragma unroll
;             for (int ks = 0; ks < 4; ++ks) { const bf16x8 k0 = *(const LAS bf16x8*)(kb + ks * 32); s0 = MFMA32(k0, qf[ks], s0); }
;             if (!meta) {
; #pragma unroll
;                 for (int ks = 0; ks < 4; ++ks) { const bf16x8 k1 = *(const LAS bf16x8*)(kb + 32 * DK_STR + ks * 32); s1 = MFMA32(k1, qf[ks], s1); }
;             }
;             __builtin_amdgcn_s_setprio(0);
;             if (meta) {
; #pragma unroll
;                 for (int r = 8; r < 16; ++r) s0[r] = -INFINITY;
; #pragma unroll
;                 for (int r = 0; r < 16; ++r) s1[r] = -INFINITY;
;             } else if (key0 + 63 > tqw) {
; #pragma unroll
;                 for (int r = 0; r < 16; ++r) { const int c = (r & 3) + 8 * (r >> 2), lim = tq - key0 - 4 * hi; if (c > lim) s0[r] = -INFINITY; if (c + 32 > lim) s1[r] = -INFINITY; }
;             }
;             float mx = fmaxf(s0[0], s1[0]);
; #pragma unroll
.LBB0_311:
	s_xor_b32 s1, s90, 31
	s_lshl_b32 s0, s1, 7
	v_readlane_b32 s2, v254, 56
	s_or_b32 s71, s2, s0
	s_or_b32 s89, s71, 16
	v_add_u32_e32 v158, s89, v204
	v_lshl_add_u64 v[0:1], s[72:73], 0, v[158:159]
	v_readlane_b32 s2, v254, 32
	v_lshlrev_b64 v[0:1], 11, v[0:1]
	v_readlane_b32 s3, v254, 33
	s_mov_b32 s95, s75
	v_mov_b32_e32 v153, v159
	v_lshl_add_u64 v[0:1], s[2:3], 0, v[0:1]
	v_lshl_add_u64 v[0:1], v[0:1], 0, s[74:75]
	v_lshl_add_u64 v[0:1], v[0:1], 0, s[94:95]
	v_lshl_add_u64 v[0:1], v[0:1], 0, v[152:153]
	global_load_dwordx4 v[96:99], v[0:1], off
	global_load_dwordx4 v[100:103], v[0:1], off offset:32
	global_load_dwordx4 v[104:107], v[0:1], off offset:64
	global_load_dwordx4 v[108:111], v[0:1], off offset:96
	global_load_dwordx4 v[0:3], v[188:189], off
	global_load_dwordx4 v[4:7], v[200:201], off
	global_load_dwordx4 v[8:11], v[190:191], off
	global_load_dwordx4 v[12:15], v[202:203], off
	global_load_dwordx4 v[112:115], v[192:193], off
	global_load_dwordx4 v[116:119], v[194:195], off
	global_load_dwordx4 v[120:123], v[196:197], off
	global_load_dwordx4 v[124:127], v[198:199], off
	s_barrier
	s_waitcnt vmcnt(7)
	ds_write_b128 v209, v[0:3]
	s_waitcnt vmcnt(6)
	ds_write_b128 v209, v[4:7] offset:8704
	s_waitcnt vmcnt(5)
	ds_write_b128 v210, v[8:11] offset:34816
	s_waitcnt vmcnt(4)
	ds_write_b128 v210, v[12:15] offset:45056
	s_waitcnt lgkmcnt(0)
	s_barrier
	ds_read_b64_tr_b16 v[32:33], v213 offset:34816
	ds_read_b64_tr_b16 v[64:65], v213 offset:34880
	ds_read_b64_tr_b16 v[72:73], v213 offset:34944
	ds_read_b64_tr_b16 v[68:69], v213 offset:35008
	ds_read_b64_tr_b16 v[34:35], v213 offset:37376
	ds_read_b64_tr_b16 v[66:67], v213 offset:37440
	ds_read_b64_tr_b16 v[74:75], v213 offset:37504
	ds_read_b64_tr_b16 v[70:71], v213 offset:37568
	s_setprio 1
	ds_read_b128 v[0:3], v212
	ds_read_b128 v[4:7], v212 offset:32
	s_waitcnt lgkmcnt(1)
	v_mfma_f32_32x32x16_bf16 v[16:31], v[0:3], v[96:99], 0
	s_waitcnt lgkmcnt(0)
	v_mfma_f32_32x32x16_bf16 v[16:31], v[4:7], v[100:103], v[16:31]
	ds_read_b128 v[0:3], v212 offset:64
	ds_read_b128 v[4:7], v212 offset:96
	s_waitcnt lgkmcnt(1)
	v_mfma_f32_32x32x16_bf16 v[16:31], v[0:3], v[104:107], v[16:31]
	s_waitcnt lgkmcnt(0)
	v_mfma_f32_32x32x16_bf16 v[16:31], v[4:7], v[108:111], v[16:31]
	s_setprio 0
	s_nop 10
	v_max_f32_e32 v0, v16, v16
	v_max_f32_e32 v1, v17, v17
	v_max_f32_e32 v2, v18, v18
	v_max_f32_e32 v0, 0xff800000, v0
	v_max_f32_e32 v1, 0xff800000, v1
	v_max_f32_e32 v2, 0xff800000, v2
	v_max3_f32 v0, v0, v1, v2
	v_max_f32_e32 v1, v19, v19
	v_max_f32_e32 v2, v20, v20
	v_max_f32_e32 v1, 0xff800000, v1
	v_max_f32_e32 v2, 0xff800000, v2
	v_max3_f32 v0, v0, v1, v2
	v_max_f32_e32 v1, v21, v21
	v_max_f32_e32 v2, v22, v22
	v_max_f32_e32 v1, 0xff800000, v1
	v_max_f32_e32 v2, 0xff800000, v2
	v_max3_f32 v0, v0, v1, v2
	v_max_f32_e32 v1, v23, v23
	v_max_f32_e32 v1, 0xff800000, v1
	s_mov_b32 s2, 0xff800000
	v_max3_f32 v0, v0, v1, s2
	ds_bpermute_b32 v1, v155, v0
	s_waitcnt lgkmcnt(0)
	v_max_f32_e32 v1, v1, v1
	v_max_f32_e32 v0, v0, v1
	v_mul_f32_e32 v0, 0x3fb8aa3b, v0
	v_cmp_neq_f32_e32 vcc, s2, v0
	s_cbranch_vccz .LBB0_313
	v_max_f32_e32 v0, v0, v0
	v_max_f32_e32 v158, 0xff800000, v0
	v_sub_f32_e32 v0, 0xff800000, v158
	v_exp_f32_e32 v0, v0
	s_nop 0
	v_mul_f32_e32 v1, 0, v0
	v_mov_b32_e32 v0, v1
	s_branch .LBB0_314

; #define LAS __attribute__((address_space(3)))
; #define MFMA32(a, b, c) __builtin_amdgcn_mfma_f32_32x32x16_bf16((a), (b), (c), 0, 0, 0)
; #define VFRAG(ptr, off0, STR) ({ const s16x4 lo_ = vtr((ptr) + (off0)); const s16x4 hi_ = vtr((ptr) + (off0) + 8 * (STR)); (bf16x8){lo_[0], lo_[1], lo_[2], lo_[3], hi_[0], hi_[1], hi_[2], hi_[3]}; })
; __device__ __forceinline__ void diff_unit(const Frame& F, int b, int h, int qi, float lam, int dry) {
;     ...
;             const LAS unsigned char* kb = lds + kra + (it & 1) * DK_BUF;
;             const LAS unsigned char* vb = lds + vra + (it & 1) * DV_BUF;
;             f32x16 s0, s1;
; #pragma unroll
;             for (int r = 0; r < 16; ++r) { s0[r] = 0.f; s1[r] = 0.f; }
;             bf16x8 vpre0 = VFRAG(vb, 0, DV_STR), vpre1 = VFRAG(vb, 64, DV_STR), vpre2 = VFRAG(vb, 128, DV_STR), vpre3 = VFRAG(vb, 192, DV_STR);
;             bf16x8 vprf0 = VFRAG(vb, 16 * DV_STR, DV_STR), vprf1 = VFRAG(vb, 16 * DV_STR + 64, DV_STR);
;             __builtin_amdgcn_s_setprio(1);
; #pragma unroll
;             for (int ks = 0; ks < 4; ++ks) { const bf16x8 k0 = *(const LAS bf16x8*)(kb + ks * 32); s0 = MFMA32(k0, qf[ks], s0); }
;             if (!meta) {
; #pragma unroll
;                 for (int ks = 0; ks < 4; ++ks) { const bf16x8 k1 = *(const LAS bf16x8*)(kb + 32 * DK_STR + ks * 32); s1 = MFMA32(k1, qf[ks], s1); }
;             }
;             __builtin_amdgcn_s_setprio(0);
;             if (meta) {
; #pragma unroll
;                 for (int r = 8; r < 16; ++r) s0[r] = -INFINITY;
; #pragma unroll
;                 for (int r = 0; r < 16; ++r) s1[r] = -INFINITY;
;             } else if (key0 + 63 > tqw) {
; #pragma unroll
;                 for (int r = 0; r < 16; ++r) { const int c = (r & 3) + 8 * (r >> 2), lim = tq - key0 - 4 * hi; if (c > lim) s0[r] = -INFINITY; if (c + 32 > lim) s1[r] = -INFINITY; }
;             }
.LBB0_320:
	s_add_i32 s0, s2, -1
	s_and_b32 s0, s0, 1
	s_mul_i32 s1, s0, 0x5000
	s_mulk_i32 s0, 0x4400
	v_add_u32_e32 v189, s0, v212
	v_add_u32_e32 v188, s1, v213
	ds_read_b128 v[64:67], v189
	ds_read_b128 v[68:71], v189 offset:32
	ds_read_b64_tr_b16 v[148:149], v188 offset:34816
	ds_read_b64_tr_b16 v[144:145], v188 offset:34880
	ds_read_b64_tr_b16 v[140:141], v188 offset:34944
	ds_read_b64_tr_b16 v[136:137], v188 offset:35008
	ds_read_b64_tr_b16 v[150:151], v188 offset:37376
	ds_read_b64_tr_b16 v[146:147], v188 offset:37440
	ds_read_b64_tr_b16 v[142:143], v188 offset:37504
	ds_read_b64_tr_b16 v[138:139], v188 offset:37568
	ds_read_b64_tr_b16 v[128:129], v188 offset:39936
	ds_read_b64_tr_b16 v[130:131], v188 offset:42496
	ds_read_b64_tr_b16 v[134:135], v188 offset:42560
	ds_read_b64_tr_b16 v[132:133], v188 offset:40000
	s_setprio 1
	s_waitcnt lgkmcnt(13)
	v_mfma_f32_32x32x16_bf16 v[80:95], v[64:67], v[96:99], 0
	s_waitcnt lgkmcnt(12)
	v_mfma_f32_32x32x16_bf16 v[80:95], v[68:71], v[100:103], v[80:95]
	ds_read_b128 v[64:67], v189 offset:64
	ds_read_b128 v[68:71], v189 offset:96
	s_waitcnt lgkmcnt(1)
	v_mfma_f32_32x32x16_bf16 v[80:95], v[64:67], v[104:107], v[80:95]
	ds_read_b128 v[64:67], v189 offset:8704
	ds_read_b128 v[190:193], v189 offset:8736
	s_waitcnt lgkmcnt(2)
	v_mfma_f32_32x32x16_bf16 v[80:95], v[68:71], v[108:111], v[80:95]
	s_waitcnt lgkmcnt(1)
	v_mfma_f32_32x32x16_bf16 v[64:79], v[64:67], v[96:99], 0
	s_waitcnt lgkmcnt(0)
	v_mfma_f32_32x32x16_bf16 v[64:79], v[190:193], v[100:103], v[64:79]
	ds_read_b128 v[190:193], v189 offset:8768
	ds_read_b128 v[194:197], v189 offset:8800
	s_waitcnt lgkmcnt(1)
	v_mfma_f32_32x32x16_bf16 v[64:79], v[190:193], v[104:107], v[64:79]
	s_waitcnt lgkmcnt(0)
	v_mfma_f32_32x32x16_bf16 v[64:79], v[194:197], v[108:111], v[64:79]
	s_setprio 0
	s_cmp_le_u32 s3, s70
	s_cbranch_scc1 .LBB0_322
	v_cmp_gt_i32_e64 s[62:63], s80, v185
	v_cmp_gt_i32_e64 s[64:65], s81, v185
	v_cmp_gt_i32_e64 s[60:61], s69, v185
	s_and_b64 s[62:63], s[64:65], s[62:63]
	v_cmp_gt_i32_e64 s[58:59], s68, v185
	s_and_b64 s[60:61], s[62:63], s[60:61]
	v_cmp_gt_i32_e64 s[56:57], s87, v185
	s_and_b64 s[58:59], s[60:61], s[58:59]
	v_cmp_gt_i32_e64 s[54:55], s86, v185
	s_and_b64 s[56:57], s[58:59], s[56:57]
	v_cmp_gt_i32_e64 s[52:53], s85, v185
	s_and_b64 s[54:55], s[56:57], s[54:55]
	v_cmp_gt_i32_e64 s[50:51], s79, v185
	s_and_b64 s[52:53], s[54:55], s[52:53]
	v_cmp_gt_i32_e64 s[48:49], s78, v185
	s_and_b64 s[50:51], s[52:53], s[50:51]
	v_cmp_gt_i32_e64 s[46:47], s77, v185
	s_and_b64 s[48:49], s[50:51], s[48:49]
	v_cmp_gt_i32_e64 s[44:45], s76, v185
	s_and_b64 s[46:47], s[48:49], s[46:47]
	v_cmp_gt_i32_e64 s[42:43], s96, v185
	s_and_b64 s[44:45], s[46:47], s[44:45]
	v_cmp_gt_i32_e64 s[40:41], s97, v185
	s_and_b64 s[42:43], s[44:45], s[42:43]
	v_cmp_gt_i32_e64 s[38:39], s93, v185
	s_and_b64 s[40:41], s[42:43], s[40:41]
	v_cmp_gt_i32_e64 s[36:37], s92, v185
	s_and_b64 s[38:39], s[40:41], s[38:39]
	v_cmp_gt_i32_e64 s[34:35], s11, v185
	s_and_b64 s[36:37], s[38:39], s[36:37]
	s_and_b64 s[34:35], s[36:37], s[34:35]
	v_cmp_gt_i32_e64 s[30:31], 10, v185
	v_cndmask_b32_e64 v80, v80, v221, s[34:35]
	v_cmp_gt_i32_e64 s[34:35], 11, v185
	v_cmp_gt_i32_e64 s[28:29], 9, v185
	s_and_b64 s[30:31], s[34:35], s[30:31]
	v_cmp_gt_i32_e64 s[26:27], 8, v185
	s_and_b64 s[28:29], s[30:31], s[28:29]
	v_cmp_gt_i32_e64 s[24:25], 3, v185
	s_and_b64 s[26:27], s[28:29], s[26:27]
	v_cmp_gt_i32_e64 s[22:23], 2, v185
	s_and_b64 s[24:25], s[26:27], s[24:25]
	v_cmp_gt_i32_e64 s[20:21], 1, v185
	s_and_b64 s[22:23], s[24:25], s[22:23]
	v_cmp_lt_u32_e64 s[18:19], s84, v185
	s_and_b64 s[20:21], s[22:23], s[20:21]
	v_cmp_gt_i32_e64 s[16:17], -5, v185
	s_and_b64 s[18:19], s[20:21], s[18:19]
	v_cmp_gt_i32_e64 s[14:15], -6, v185
	s_and_b64 s[16:17], s[18:19], s[16:17]
	v_cmp_gt_i32_e64 s[12:13], -7, v185
	s_and_b64 s[14:15], s[16:17], s[14:15]
	v_cmp_gt_i32_e64 s[8:9], -8, v185
	s_and_b64 s[12:13], s[14:15], s[12:13]
	v_cmp_gt_i32_e64 s[6:7], -13, v185
	s_and_b64 s[8:9], s[12:13], s[8:9]
	v_cmp_gt_i32_e64 s[4:5], -14, v185
	s_and_b64 s[6:7], s[8:9], s[6:7]
	v_cmp_gt_i32_e64 s[0:1], -15, v185
	s_and_b64 s[4:5], s[6:7], s[4:5]
	v_cmp_gt_i32_e32 vcc, -16, v185
	s_and_b64 s[0:1], s[4:5], s[0:1]
	s_and_b64 vcc, s[0:1], vcc
	v_cndmask_b32_e64 v95, v95, v221, s[64:65]
	v_cndmask_b32_e64 v94, v94, v221, s[62:63]
	v_cndmask_b32_e64 v93, v93, v221, s[60:61]
	v_cndmask_b32_e64 v92, v92, v221, s[58:59]
	v_cndmask_b32_e64 v91, v91, v221, s[56:57]
	v_cndmask_b32_e64 v90, v90, v221, s[54:55]
	v_cndmask_b32_e64 v89, v89, v221, s[52:53]
	v_cndmask_b32_e64 v88, v88, v221, s[50:51]
	v_cndmask_b32_e64 v87, v87, v221, s[48:49]
	v_cndmask_b32_e64 v86, v86, v221, s[46:47]
	v_cndmask_b32_e64 v85, v85, v221, s[44:45]
	v_cndmask_b32_e64 v84, v84, v221, s[42:43]
	v_cndmask_b32_e64 v83, v83, v221, s[40:41]
	v_cndmask_b32_e64 v82, v82, v221, s[38:39]
	v_cndmask_b32_e64 v81, v81, v221, s[36:37]
	v_cndmask_b32_e64 v79, v79, v221, s[34:35]
	v_cndmask_b32_e64 v78, v78, v221, s[30:31]
	v_cndmask_b32_e64 v77, v77, v221, s[28:29]
	v_cndmask_b32_e64 v76, v76, v221, s[26:27]
	v_cndmask_b32_e64 v75, v75, v221, s[24:25]
	v_cndmask_b32_e64 v74, v74, v221, s[22:23]
	v_cndmask_b32_e64 v73, v73, v221, s[20:21]
	v_cndmask_b32_e64 v72, v72, v221, s[18:19]
	v_cndmask_b32_e64 v71, v71, v221, s[16:17]
	v_cndmask_b32_e64 v70, v70, v221, s[14:15]
	v_cndmask_b32_e64 v69, v69, v221, s[12:13]
	v_cndmask_b32_e64 v68, v68, v221, s[8:9]
	v_cndmask_b32_e64 v67, v67, v221, s[6:7]
	v_cndmask_b32_e64 v66, v66, v221, s[4:5]
	v_cndmask_b32_e64 v65, v65, v221, s[0:1]
	v_cndmask_b32_e32 v64, v64, v221, vcc
; __device__ __forceinline__ void diff_unit(const Frame& F, int b, int h, int qi, float lam, int dry) {
;     ...
;             float mx = fmaxf(s0[0], s1[0]);
; #pragma unroll
;             for (int r = 1; r < 16; ++r) mx = fmaxf(mx, fmaxf(s0[r], s1[r]));
;             mx = fmaxf(mx, __shfl_xor(mx, 32));
;             const float mxs = mx * LOG2E;
;             if (__any(mxs > ms + 8.0f)) {
;                 const float msn = fmaxf(ms, mxs); const float f = __builtin_amdgcn_exp2f(ms - msn); lsum *= f; ms = msn;
; #pragma unroll
;                 for (int dt = 0; dt < 4; ++dt)
; #pragma unroll
;                     for (int r = 0; r < 16; ++r) O[dt][r] *= f;
;             }
.LBB0_322:
	v_max3_f32 v189, v80, v81, v82
	v_max3_f32 v189, v189, v83, v84
	v_max3_f32 v189, v189, v85, v86
	v_max3_f32 v189, v189, v87, v88
	v_max3_f32 v189, v189, v89, v90
	v_max3_f32 v189, v189, v91, v92
	v_max3_f32 v189, v189, v93, v94
	s_nop 2
	v_max3_f32 v190, v64, v65, v66
	v_max3_f32 v190, v190, v67, v68
	v_max3_f32 v190, v190, v69, v70
	v_max3_f32 v190, v190, v71, v72
	v_max3_f32 v190, v190, v73, v74
	v_max3_f32 v190, v190, v75, v76
	v_max3_f32 v190, v190, v77, v78
	v_max3_f32 v189, v189, v190, v95
	v_max_f32_e32 v189, v189, v79
	v_mov_b32_e32 v190, v189
	s_nop 1
	v_permlane32_swap_b32_e32 v189, v190
	v_max_f32_e32 v189, v189, v190
	v_mul_f32_e32 v189, 0x3fb8aa3b, v189
	v_add_f32_e32 v190, 0x41000000, v158
	v_cmp_gt_f32_e32 vcc, v189, v190
	s_cbranch_vccz .LBB0_324
	v_max_f32_e32 v189, v189, v189
	v_max_f32_e32 v190, v158, v158
	v_max_f32_e32 v189, v190, v189
	v_sub_f32_e32 v158, v158, v189
	v_exp_f32_e32 v158, v158
	s_nop 0
	v_pk_mul_f32 v[62:63], v[62:63], v[158:159] op_sel_hi:[1,0]
	v_pk_mul_f32 v[60:61], v[60:61], v[158:159] op_sel_hi:[1,0]
	v_pk_mul_f32 v[58:59], v[58:59], v[158:159] op_sel_hi:[1,0]
	v_pk_mul_f32 v[56:57], v[56:57], v[158:159] op_sel_hi:[1,0]
	v_pk_mul_f32 v[54:55], v[54:55], v[158:159] op_sel_hi:[1,0]
	v_pk_mul_f32 v[52:53], v[52:53], v[158:159] op_sel_hi:[1,0]
	v_pk_mul_f32 v[50:51], v[50:51], v[158:159] op_sel_hi:[1,0]
	v_pk_mul_f32 v[48:49], v[48:49], v[158:159] op_sel_hi:[1,0]
	v_pk_mul_f32 v[46:47], v[46:47], v[158:159] op_sel_hi:[1,0]
	v_pk_mul_f32 v[44:45], v[44:45], v[158:159] op_sel_hi:[1,0]
	v_pk_mul_f32 v[42:43], v[42:43], v[158:159] op_sel_hi:[1,0]
	v_pk_mul_f32 v[40:41], v[40:41], v[158:159] op_sel_hi:[1,0]
	v_pk_mul_f32 v[38:39], v[38:39], v[158:159] op_sel_hi:[1,0]
	v_pk_mul_f32 v[36:37], v[36:37], v[158:159] op_sel_hi:[1,0]
	v_pk_mul_f32 v[34:35], v[34:35], v[158:159] op_sel_hi:[1,0]
	v_pk_mul_f32 v[32:33], v[32:33], v[158:159] op_sel_hi:[1,0]
	v_pk_mul_f32 v[30:31], v[30:31], v[158:159] op_sel_hi:[1,0]
	v_pk_mul_f32 v[28:29], v[28:29], v[158:159] op_sel_hi:[1,0]
	v_pk_mul_f32 v[26:27], v[26:27], v[158:159] op_sel_hi:[1,0]
	v_pk_mul_f32 v[24:25], v[24:25], v[158:159] op_sel_hi:[1,0]
	v_pk_mul_f32 v[22:23], v[22:23], v[158:159] op_sel_hi:[1,0]
	v_pk_mul_f32 v[20:21], v[20:21], v[158:159] op_sel_hi:[1,0]
	v_pk_mul_f32 v[18:19], v[18:19], v[158:159] op_sel_hi:[1,0]
	v_pk_mul_f32 v[16:17], v[16:17], v[158:159] op_sel_hi:[1,0]
	v_pk_mul_f32 v[14:15], v[14:15], v[158:159] op_sel_hi:[1,0]
	v_pk_mul_f32 v[12:13], v[12:13], v[158:159] op_sel_hi:[1,0]
	v_pk_mul_f32 v[10:11], v[10:11], v[158:159] op_sel_hi:[1,0]
	v_pk_mul_f32 v[8:9], v[8:9], v[158:159] op_sel_hi:[1,0]
	v_pk_mul_f32 v[6:7], v[6:7], v[158:159] op_sel_hi:[1,0]
	v_pk_mul_f32 v[4:5], v[4:5], v[158:159] op_sel_hi:[1,0]
	v_pk_mul_f32 v[2:3], v[2:3], v[158:159] op_sel_hi:[1,0]
	v_pk_mul_f32 v[0:1], v[0:1], v[158:159] op_sel_hi:[1,0]
	v_mul_f32_e32 v153, v153, v158
	v_mov_b32_e32 v158, v189
; #define MFMA32(a, b, c) __builtin_amdgcn_mfma_f32_32x32x16_bf16((a), (b), (c), 0, 0, 0)
; #define VFRAG(ptr, off0, STR) ({ const s16x4 lo_ = vtr((ptr) + (off0)); const s16x4 hi_ = vtr((ptr) + (off0) + 8 * (STR)); (bf16x8){lo_[0], lo_[1], lo_[2], lo_[3], hi_[0], hi_[1], hi_[2], hi_[3]}; })
; __device__ __forceinline__ void diff_unit(const Frame& F, int b, int h, int qi, float lam, int dry) {
;     ...
;             float ps = 0.f;
; #pragma unroll
;             for (int r = 0; r < 16; ++r) { s0[r] = __builtin_amdgcn_exp2f(s0[r] * LOG2E - ms); ps += s0[r]; }
;             if (!meta) {
; #pragma unroll
;                 for (int r = 0; r < 16; ++r) { s1[r] = __builtin_amdgcn_exp2f(s1[r] * LOG2E - ms); ps += s1[r]; }
;             }
;             lsum += ps;
;             __builtin_amdgcn_s_setprio(1);
;             { const bf16x8 pf = pack_step(s0, 0);
;               O[0] = MFMA32(vpre0, pf, O[0]); O[1] = MFMA32(vpre1, pf, O[1]); O[2] = MFMA32(vpre2, pf, O[2]); O[3] = MFMA32(vpre3, pf, O[3]); }
;             if (!meta) {
;                 { const bf16x8 pf = pack_step(s0, 1);
;                   O[0] = MFMA32(vprf0, pf, O[0]); O[1] = MFMA32(vprf1, pf, O[1]);
; #pragma unroll
;                   for (int dt = 2; dt < 4; ++dt) { const bf16x8 vf = VFRAG(vb, 16 * DV_STR + 64 * dt, DV_STR); O[dt] = MFMA32(vf, pf, O[dt]); } }
; #pragma unroll
;                 for (int s2 = 0; s2 < 2; ++s2) { const bf16x8 pf = pack_step(s1, s2);
; #pragma unroll
;                     for (int dt = 0; dt < 4; ++dt) { const bf16x8 vf = VFRAG(vb, (32 + 16 * s2) * DV_STR + 64 * dt, DV_STR); O[dt] = MFMA32(vf, pf, O[dt]); } }
;             }
;             __builtin_amdgcn_s_setprio(0);
.LBB0_324:
	ds_read_b64_tr_b16 v[190:191], v188 offset:40064
	ds_read_b64_tr_b16 v[192:193], v188 offset:42624
	ds_read_b64_tr_b16 v[194:195], v188 offset:40128
	ds_read_b64_tr_b16 v[196:197], v188 offset:42688
	v_fma_f32 v80, v80, s88, -v158
	v_fma_f32 v81, v81, s88, -v158
	v_fma_f32 v82, v82, s88, -v158
	v_fma_f32 v83, v83, s88, -v158
	v_exp_f32_e32 v80, v80
	v_exp_f32_e32 v81, v81
	v_exp_f32_e32 v82, v82
	v_exp_f32_e32 v83, v83
	v_fma_f32 v84, v84, s88, -v158
	v_fma_f32 v85, v85, s88, -v158
	v_fma_f32 v86, v86, s88, -v158
	v_fma_f32 v87, v87, s88, -v158
	v_exp_f32_e32 v84, v84
	v_exp_f32_e32 v85, v85
	v_exp_f32_e32 v86, v86
	v_exp_f32_e32 v87, v87
	v_pk_add_f32 v[202:203], v[80:81], v[82:83]
	s_setprio 1
	v_cvt_pk_bf16_f32 v198, v80, v81
	v_cvt_pk_bf16_f32 v199, v82, v83
	v_cvt_pk_bf16_f32 v200, v84, v85
	v_cvt_pk_bf16_f32 v201, v86, v87
	v_pk_add_f32 v[202:203], v[202:203], v[84:85]
	v_pk_add_f32 v[202:203], v[202:203], v[86:87]
	v_mfma_f32_32x32x16_bf16 v[48:63], v[148:151], v[198:201], v[48:63]
	ds_read_b64_tr_b16 v[148:149], v188 offset:45056
	ds_read_b64_tr_b16 v[150:151], v188 offset:47616
	v_fma_f32 v88, v88, s88, -v158
	v_fma_f32 v89, v89, s88, -v158
	v_exp_f32_e32 v88, v88
	v_exp_f32_e32 v89, v89
	v_mfma_f32_32x32x16_bf16 v[32:47], v[144:147], v[198:201], v[32:47]
	ds_read_b64_tr_b16 v[144:145], v188 offset:45120
	ds_read_b64_tr_b16 v[146:147], v188 offset:47680
	v_fma_f32 v90, v90, s88, -v158
	v_fma_f32 v91, v91, s88, -v158
	v_exp_f32_e32 v90, v90
	v_exp_f32_e32 v91, v91
	v_pk_add_f32 v[202:203], v[202:203], v[88:89]
	v_cvt_pk_bf16_f32 v80, v88, v89
	v_mfma_f32_32x32x16_bf16 v[16:31], v[140:143], v[198:201], v[16:31]
	ds_read_b64_tr_b16 v[140:141], v188 offset:45184
	ds_read_b64_tr_b16 v[142:143], v188 offset:47744
	v_fma_f32 v92, v92, s88, -v158
	v_fma_f32 v93, v93, s88, -v158
	v_exp_f32_e32 v92, v92
	v_exp_f32_e32 v93, v93
	v_pk_add_f32 v[202:203], v[202:203], v[90:91]
	v_cvt_pk_bf16_f32 v81, v90, v91
	v_mfma_f32_32x32x16_bf16 v[0:15], v[136:139], v[198:201], v[0:15]
	ds_read_b64_tr_b16 v[136:137], v188 offset:45248
	ds_read_b64_tr_b16 v[138:139], v188 offset:47808
	v_fma_f32 v94, v94, s88, -v158
	v_fma_f32 v95, v95, s88, -v158
	v_exp_f32_e32 v94, v94
	v_exp_f32_e32 v95, v95
	v_pk_add_f32 v[202:203], v[202:203], v[92:93]
	v_cvt_pk_bf16_f32 v82, v92, v93
	v_cvt_pk_bf16_f32 v83, v94, v95
	v_pk_add_f32 v[202:203], v[202:203], v[94:95]
	s_nop 0
	v_mfma_f32_32x32x16_bf16 v[48:63], v[128:131], v[80:83], v[48:63]
	ds_read_b64_tr_b16 v[128:129], v188 offset:50176
	ds_read_b64_tr_b16 v[130:131], v188 offset:52736
	v_fma_f32 v64, v64, s88, -v158
	v_fma_f32 v65, v65, s88, -v158
	v_exp_f32_e32 v64, v64
	v_exp_f32_e32 v65, v65
	v_mfma_f32_32x32x16_bf16 v[32:47], v[132:135], v[80:83], v[32:47]
	ds_read_b64_tr_b16 v[132:133], v188 offset:50240
	ds_read_b64_tr_b16 v[134:135], v188 offset:52800
	v_fma_f32 v66, v66, s88, -v158
	v_fma_f32 v67, v67, s88, -v158
	v_exp_f32_e32 v66, v66
	v_exp_f32_e32 v67, v67
	v_pk_add_f32 v[202:203], v[202:203], v[64:65]
	v_cvt_pk_bf16_f32 v84, v64, v65
	s_waitcnt lgkmcnt(14)
	v_mfma_f32_32x32x16_bf16 v[16:31], v[190:193], v[80:83], v[16:31]
	ds_read_b64_tr_b16 v[190:191], v188 offset:50304
	ds_read_b64_tr_b16 v[192:193], v188 offset:52864
	v_fma_f32 v68, v68, s88, -v158
	v_fma_f32 v69, v69, s88, -v158
	v_exp_f32_e32 v68, v68
	v_exp_f32_e32 v69, v69
	v_pk_add_f32 v[202:203], v[202:203], v[66:67]
	v_cvt_pk_bf16_f32 v85, v66, v67
	s_waitcnt lgkmcnt(14)
	v_mfma_f32_32x32x16_bf16 v[0:15], v[194:197], v[80:83], v[0:15]
	ds_read_b64_tr_b16 v[194:195], v188 offset:50368
	ds_read_b64_tr_b16 v[196:197], v188 offset:52928
	v_fma_f32 v70, v70, s88, -v158
	v_fma_f32 v71, v71, s88, -v158
	v_exp_f32_e32 v70, v70
	v_exp_f32_e32 v71, v71
	v_pk_add_f32 v[202:203], v[202:203], v[68:69]
	v_cvt_pk_bf16_f32 v86, v68, v69
	v_cvt_pk_bf16_f32 v87, v70, v71
	v_pk_add_f32 v[202:203], v[202:203], v[70:71]
	s_nop 0
	s_waitcnt lgkmcnt(14)
	v_mfma_f32_32x32x16_bf16 v[48:63], v[148:151], v[84:87], v[48:63]
	v_fma_f32 v72, v72, s88, -v158
	v_fma_f32 v73, v73, s88, -v158
	v_exp_f32_e32 v72, v72
	v_exp_f32_e32 v73, v73
	s_waitcnt lgkmcnt(12)
	v_mfma_f32_32x32x16_bf16 v[32:47], v[144:147], v[84:87], v[32:47]
	v_fma_f32 v74, v74, s88, -v158
	v_fma_f32 v75, v75, s88, -v158
	v_exp_f32_e32 v74, v74
	v_exp_f32_e32 v75, v75
	v_pk_add_f32 v[202:203], v[202:203], v[72:73]
	v_cvt_pk_bf16_f32 v198, v72, v73
	s_waitcnt lgkmcnt(10)
	v_mfma_f32_32x32x16_bf16 v[16:31], v[140:143], v[84:87], v[16:31]
	v_fma_f32 v76, v76, s88, -v158
	v_fma_f32 v77, v77, s88, -v158
	v_exp_f32_e32 v76, v76
	v_exp_f32_e32 v77, v77
	v_pk_add_f32 v[202:203], v[202:203], v[74:75]
	v_cvt_pk_bf16_f32 v199, v74, v75
	s_waitcnt lgkmcnt(8)
	v_mfma_f32_32x32x16_bf16 v[0:15], v[136:139], v[84:87], v[0:15]
	v_fma_f32 v78, v78, s88, -v158
	v_fma_f32 v79, v79, s88, -v158
	v_exp_f32_e32 v78, v78
	v_exp_f32_e32 v79, v79
	v_pk_add_f32 v[202:203], v[202:203], v[76:77]
	v_cvt_pk_bf16_f32 v200, v76, v77
	v_cvt_pk_bf16_f32 v201, v78, v79
	v_pk_add_f32 v[202:203], v[202:203], v[78:79]
	v_add_f32_e32 v189, v202, v203
	v_add_f32_e32 v153, v153, v189
	s_waitcnt lgkmcnt(6)
	v_mfma_f32_32x32x16_bf16 v[48:63], v[128:131], v[198:201], v[48:63]
	s_waitcnt lgkmcnt(4)
	v_mfma_f32_32x32x16_bf16 v[32:47], v[132:135], v[198:201], v[32:47]
	s_waitcnt lgkmcnt(2)
	v_mfma_f32_32x32x16_bf16 v[16:31], v[190:193], v[198:201], v[16:31]
	s_waitcnt lgkmcnt(0)
	v_mfma_f32_32x32x16_bf16 v[0:15], v[194:197], v[198:201], v[0:15]
	s_setprio 0
	s_andn2_b64 vcc, exec, s[90:91]
	s_cbranch_vccnz .LBB0_315

; #define LAS __attribute__((address_space(3)))
; #define S_LOAD(key0) do { st0 = *(const u32x4*)(kg + (size_t)(key0) * 1024); st1 = *(const u32x4*)(kg + (size_t)((key0) + 64) * 1024); st2 = *(const u32x4*)(vg + (size_t)(key0) * 1024); st3 = *(const u32x4*)(vg + (size_t)((key0) + 64) * 1024); } while (0)
; __device__ __forceinline__ void sb_unit(const Frame& F, int b, int hd, int qi, int dry) {
;     ...
;     for (int it = 0; it < nt; ++it) {
;         const bool meta = (it > jmax);
;         const int key0 = meta ? 0 : NMETA + 128 * (jmax - it);
;         if (it + 1 < nt) { const int nk = (it + 1 > jmax) ? 0 : NMETA + 128 * (jmax - it - 1); S_LOAD(nk); }
;         if (!dead && (meta || key0 < tqw + 31)) {
;             const LAS unsigned char* kb = lds + kra + (it & 1) * SK_BUF;
;             const LAS unsigned char* vb = lds + vra + (it & 1) * SV_BUF;
;     ...
;             float run = C;
;             if (!meta && key0 + 96 < tqw + 31) SB_HALF(96);
.LBB0_337:
	s_xor_b64 s[0:1], s[0:1], -1
	s_andn2_b64 vcc, exec, s[0:1]
	s_mov_b64 s[0:1], -1
	s_cbranch_vccnz .LBB0_350
	s_add_i32 s35, s33, 0xffffff10
	s_cmp_gt_u32 s36, s29
	s_cselect_b64 s[18:19], -1, 0
	s_and_b64 s[0:1], s[18:19], exec
	s_cselect_b32 s35, 0, s35
	s_cmp_lt_i32 s35, s30
	s_cselect_b64 s[0:1], -1, 0
	s_or_b64 s[0:1], s[18:19], s[0:1]
	s_andn2_b64 vcc, exec, s[0:1]
	s_mov_b64 s[0:1], 0
	s_cbranch_vccnz .LBB0_350
	s_and_b32 s0, s36, 1
	s_mul_i32 s36, s0, 0x4800
	s_mul_i32 s37, s0, 0x6000
	s_or_b32 s0, s35, 0x41
	s_cmp_ge_i32 s0, s26
	s_cselect_b64 s[0:1], -1, 0
	s_or_b64 s[0:1], s[18:19], s[0:1]
	s_and_b64 vcc, exec, s[0:1]
	v_add_u32_e32 v129, s36, v118
	v_or_b32_e32 v127, s35, v205
	v_add_u32_e32 v128, s37, v119
	s_cbranch_vccnz .LBB0_341
	ds_read_b128 v[32:35], v129 offset:13824
	ds_read_b128 v[80:83], v129 offset:13856
	v_exp_f32_e32 v135, v125
	v_sub_u32_e32 v134, v115, v127
	v_cmp_lt_i32_e32 vcc, 0, v134
	s_waitcnt lgkmcnt(1)
	v_mfma_f32_32x32x16_bf16 v[32:47], v[32:35], v[48:51], 0
	v_cmp_lt_i32_e64 s[0:1], 27, v134
	s_waitcnt lgkmcnt(0)
	v_mfma_f32_32x32x16_bf16 v[32:47], v[80:83], v[52:55], v[32:47]
	ds_read_b128 v[80:83], v129 offset:13888
	ds_read_b128 v[130:133], v129 offset:13920
	s_waitcnt lgkmcnt(1)
	v_mfma_f32_32x32x16_bf16 v[32:47], v[80:83], v[56:59], v[32:47]
	ds_read_b64_tr_b16 v[92:93], v128 offset:55296
	ds_read_b64_tr_b16 v[94:95], v128 offset:56832
	ds_read_b64_tr_b16 v[90:91], v128 offset:56896
	ds_read_b64_tr_b16 v[88:89], v128 offset:55360
	ds_read_b64_tr_b16 v[84:85], v128 offset:58368
	ds_read_b64_tr_b16 v[86:87], v128 offset:59904
	ds_read_b64_tr_b16 v[82:83], v128 offset:59968
	ds_read_b64_tr_b16 v[80:81], v128 offset:58432
	s_waitcnt lgkmcnt(8)
	v_mfma_f32_32x32x16_bf16 v[32:47], v[130:133], v[60:63], v[32:47]
	s_nop 11
	v_max_f32_e64 v32, -v32, -v32
	v_max_f32_e64 v33, -v33, -v33
	v_min_f32_e32 v32, 0x42fc0000, v32
	v_max_f32_e64 v34, -v34, -v34
	v_min_f32_e32 v33, 0x42fc0000, v33
	v_exp_f32_e32 v32, v32
	v_min_f32_e32 v34, 0x42fc0000, v34
	v_exp_f32_e32 v33, v33
	v_max_f32_e64 v35, -v35, -v35
	v_exp_f32_e32 v34, v34
	v_min_f32_e32 v35, 0x42fc0000, v35
	v_exp_f32_e32 v130, v35
	v_add_f32_e32 v35, 1.0, v32
	v_add_f32_e32 v131, 1.0, v33
	v_rcp_f32_e32 v35, v35
	v_max_f32_e64 v36, -v36, -v36
	v_add_f32_e32 v132, 1.0, v34
	v_rcp_f32_e32 v131, v131
	v_min_f32_e32 v36, 0x42fc0000, v36
	v_rcp_f32_e32 v132, v132
	v_exp_f32_e32 v36, v36
	v_add_f32_e32 v133, 1.0, v130
	v_rcp_f32_e32 v136, v133
	v_mul_f32_e32 v32, v32, v35
	v_mul_f32_e32 v133, v135, v35
	v_mul_f32_e32 v33, v33, v131
	v_mul_f32_e32 v137, v135, v131
	v_cndmask_b32_e32 v35, 1.0, v32, vcc
	v_cndmask_b32_e32 v138, 0, v133, vcc
	v_cmp_lt_i32_e32 vcc, 1, v134
	v_mul_f32_e32 v34, v34, v132
	v_mul_f32_e32 v32, v135, v132
	v_cndmask_b32_e32 v131, 1.0, v33, vcc
	v_cndmask_b32_e32 v137, 0, v137, vcc
	v_cmp_lt_i32_e32 vcc, 2, v134
	v_max_f32_e64 v39, -v39, -v39
	v_min_f32_e32 v39, 0x42fc0000, v39
	v_cndmask_b32_e32 v33, 1.0, v34, vcc
	v_add_f32_e32 v34, 1.0, v36
	v_rcp_f32_e32 v34, v34
	v_cndmask_b32_e32 v139, 0, v32, vcc
	v_mul_f32_e32 v32, v130, v136
	v_cmp_lt_i32_e32 vcc, 3, v134
	v_exp_f32_e32 v39, v39
	v_max_f32_e64 v42, -v42, -v42
	v_cndmask_b32_e32 v133, 1.0, v32, vcc
	v_mul_f32_e32 v32, v135, v136
	v_cndmask_b32_e32 v136, 0, v32, vcc
	v_mul_f32_e32 v32, v36, v34
	v_max_f32_e64 v36, -v37, -v37
	v_min_f32_e32 v36, 0x42fc0000, v36
	v_exp_f32_e32 v36, v36
	v_cmp_lt_i32_e32 vcc, 8, v134
	v_mul_f32_e32 v34, v135, v34
	v_max_f32_e64 v37, -v38, -v38
	v_cndmask_b32_e32 v140, 0, v34, vcc
	v_add_f32_e32 v34, 1.0, v36
	v_rcp_f32_e32 v34, v34
	v_min_f32_e32 v37, 0x42fc0000, v37
	v_exp_f32_e32 v37, v37
	v_cndmask_b32_e32 v32, 1.0, v32, vcc
	v_mul_f32_e32 v36, v36, v34
	v_cmp_lt_i32_e32 vcc, 9, v134
	v_mul_f32_e32 v34, v135, v34
	v_min_f32_e32 v42, 0x42fc0000, v42
	v_cndmask_b32_e32 v38, 1.0, v36, vcc
	v_add_f32_e32 v36, 1.0, v37
	v_rcp_f32_e32 v36, v36
	v_cndmask_b32_e32 v141, 0, v34, vcc
	v_cmp_lt_i32_e32 vcc, 10, v134
	v_exp_f32_e32 v42, v42
	v_mul_f32_e32 v34, v37, v36
	v_add_f32_e32 v37, 1.0, v39
	v_rcp_f32_e32 v37, v37
	v_cndmask_b32_e32 v142, 1.0, v34, vcc
	v_mul_f32_e32 v34, v135, v36
	v_cndmask_b32_e32 v143, 0, v34, vcc
	v_mul_f32_e32 v34, v39, v37
	v_max_f32_e64 v36, -v40, -v40
	v_cmp_lt_i32_e32 vcc, 11, v134
	v_min_f32_e32 v36, 0x42fc0000, v36
	v_exp_f32_e32 v36, v36
	v_cndmask_b32_e32 v39, 1.0, v34, vcc
	v_mul_f32_e32 v34, v135, v37
	v_max_f32_e64 v37, -v41, -v41
	v_min_f32_e32 v37, 0x42fc0000, v37
	v_exp_f32_e32 v37, v37
	v_cndmask_b32_e32 v40, 0, v34, vcc
	v_add_f32_e32 v34, 1.0, v36
	v_rcp_f32_e32 v34, v34
	v_add_f32_e32 v41, 1.0, v37
	v_rcp_f32_e32 v41, v41
	v_cmp_lt_i32_e32 vcc, 16, v134
	v_mul_f32_e32 v36, v36, v34
	v_mul_f32_e32 v34, v135, v34
	v_cndmask_b32_e32 v144, 0, v34, vcc
	v_mul_f32_e32 v34, v37, v41
	v_add_f32_e32 v37, 1.0, v42
	v_rcp_f32_e32 v37, v37
	v_cndmask_b32_e32 v36, 1.0, v36, vcc
	v_cmp_lt_i32_e32 vcc, 17, v134
	v_max_f32_e64 v45, -v45, -v45
	v_min_f32_e32 v45, 0x42fc0000, v45
	v_cndmask_b32_e32 v145, 1.0, v34, vcc
	v_mul_f32_e32 v34, v135, v41
	v_cndmask_b32_e32 v41, 0, v34, vcc
	v_mul_f32_e32 v34, v42, v37
	v_max_f32_e64 v42, -v43, -v43
	v_cmp_lt_i32_e32 vcc, 18, v134
	v_min_f32_e32 v42, 0x42fc0000, v42
	v_exp_f32_e32 v42, v42
	v_cndmask_b32_e32 v43, 1.0, v34, vcc
	v_mul_f32_e32 v34, v135, v37
	v_max_f32_e64 v37, -v44, -v44
	v_min_f32_e32 v37, 0x42fc0000, v37
	v_exp_f32_e32 v37, v37
	v_cndmask_b32_e32 v146, 0, v34, vcc
	v_add_f32_e32 v34, 1.0, v42
	v_rcp_f32_e32 v34, v34
	v_add_f32_e32 v44, 1.0, v37
	v_max_f32_e64 v46, -v46, -v46
	v_max_f32_e64 v47, -v47, -v47
	v_rcp_f32_e32 v44, v44
	v_exp_f32_e32 v45, v45
	v_min_f32_e32 v46, 0x42fc0000, v46
	v_min_f32_e32 v47, 0x42fc0000, v47
	v_exp_f32_e32 v46, v46
	v_exp_f32_e32 v47, v47
	v_mul_f32_e32 v42, v42, v34
	v_cmp_lt_i32_e32 vcc, 19, v134
	v_mul_f32_e32 v34, v135, v34
	v_add_f32_e32 v130, 1.0, v46
	v_cndmask_b32_e32 v147, 0, v34, vcc
	v_mul_f32_e32 v34, v37, v44
	v_add_f32_e32 v37, 1.0, v45
	v_rcp_f32_e32 v37, v37
	v_add_f32_e32 v132, 1.0, v47
	v_rcp_f32_e32 v130, v130
	v_rcp_f32_e32 v132, v132
	v_cndmask_b32_e32 v42, 1.0, v42, vcc
	v_cmp_lt_i32_e32 vcc, 24, v134
	v_mul_f32_e32 v44, v135, v44
	v_mul_f32_e32 v45, v45, v37
	v_cndmask_b32_e32 v34, 1.0, v34, vcc
	v_cndmask_b32_e32 v44, 0, v44, vcc
	v_cmp_lt_i32_e32 vcc, 25, v134
	v_mul_f32_e32 v37, v135, v37
	v_mul_f32_e32 v46, v46, v130
	v_cndmask_b32_e32 v45, 1.0, v45, vcc
	v_cndmask_b32_e32 v37, 0, v37, vcc
	v_cmp_lt_i32_e32 vcc, 26, v134
	v_mul_f32_e32 v47, v47, v132
	v_cndmask_b32_e64 v47, 1.0, v47, s[0:1]
	v_cndmask_b32_e32 v46, 1.0, v46, vcc
	v_mul_f32_e32 v34, v34, v45
	v_mul_f32_e32 v134, v46, v47
	v_mul_f32_e32 v134, v34, v134
	v_mov_b32_e32 v148, v134
	v_mov_b32_e32 v240, v134
	s_nop 1
	v_permlane32_swap_b32_e32 v148, v240
	v_cndmask_b32_e64 v148, v148, v240, s[2:3]
	v_mul_f32_e32 v34, v135, v130
	v_cndmask_b32_e32 v149, 0, v34, vcc
	v_mul_f32_e32 v34, v135, v132
	v_cndmask_b32_e64 v34, 0, v34, s[0:1]
	s_waitcnt lgkmcnt(0)
; __device__ __forceinline__ void sb_unit(const Frame& F, int b, int hd, int qi, int dry) {
;     ...
;             float run = C;
;             if (!meta && key0 + 96 < tqw + 31) SB_HALF(96);
;             if (!meta && key0 + 64 < tqw + 31 && __any(run >= SB_DEAD)) SB_HALF(64);
;             if (!meta && key0 + 32 < tqw + 31 && __any(run >= SB_DEAD)) SB_HALF(32);
	v_cndmask_b32_e64 v130, 1.0, v148, s[2:3]
	v_mul_f32_e32 v135, v34, v130
	v_mul_f32_e32 v34, v36, v145
	v_mul_f32_e32 v36, v43, v42
	v_mul_f32_e32 v36, v34, v36
	v_mul_f32_e32 v32, v32, v38
	v_mul_f32_e32 v34, v142, v39
	v_mov_b32_e32 v150, v36
	v_mov_b32_e32 v240, v36
	s_nop 1
	v_permlane32_swap_b32_e32 v150, v240
	v_cndmask_b32_e64 v150, v150, v240, s[2:3]
	v_mul_f32_e32 v34, v32, v34
	v_mul_f32_e32 v47, v47, v130
	v_mov_b32_e32 v130, v34
	v_mov_b32_e32 v240, v34
	s_nop 1
	v_permlane32_swap_b32_e32 v130, v240
	v_cndmask_b32_e64 v130, v130, v240, s[2:3]
	v_mul_f32_e32 v46, v46, v47
	v_mul_f32_e32 v32, v134, v148
	s_waitcnt lgkmcnt(1)
	v_mul_f32_e32 v132, v36, v150
	v_mul_f32_e32 v45, v45, v46
	v_mul_f32_e32 v46, v37, v46
	s_waitcnt lgkmcnt(0)
	v_cndmask_b32_e64 v134, 1.0, v130, s[2:3]
	v_pk_mul_f32 v[36:37], v[32:33], v[132:133]
	v_pk_mul_f32 v[34:35], v[34:35], v[130:131]
	v_mul_f32_e32 v132, v36, v134
	v_mul_f32_e32 v134, v39, v132
	v_mul_f32_e32 v142, v142, v134
	v_mul_f32_e32 v148, v38, v142
	v_pk_mul_f32 v[38:39], v[34:35], v[36:37]
	v_mov_b32_e32 v130, v39
	v_mov_b32_e32 v240, v39
	s_nop 1
	v_permlane32_swap_b32_e32 v130, v240
	v_cndmask_b32_e64 v130, v130, v240, s[2:3]
	v_mul_f32_e32 v37, v40, v132
	v_mul_f32_e32 v40, v143, v134
	v_mul_f32_e32 v36, v141, v142
	v_mul_f32_e32 v132, v140, v148
	s_waitcnt lgkmcnt(0)
	v_cndmask_b32_e64 v34, 1.0, v130, s[2:3]
	v_mul_f32_e32 v34, v38, v34
	v_mul_f32_e32 v35, v133, v34
	v_mul_f32_e32 v33, v33, v35
	v_mul_f32_e32 v131, v131, v33
	v_mul_f32_e32 v133, v136, v34
	v_mul_f32_e32 v35, v139, v35
	v_mul_f32_e32 v33, v137, v33
	v_mul_f32_e32 v34, v138, v131
	v_cvt_pk_bf16_f32 v34, v34, v33
	v_cvt_pk_bf16_f32 v35, v35, v133
	v_cvt_pk_bf16_f32 v36, v132, v36
	v_cvt_pk_bf16_f32 v37, v40, v37
	v_cndmask_b32_e64 v33, 1.0, v150, s[2:3]
	v_mul_f32_e32 v32, v32, v33
	v_mfma_f32_32x32x16_bf16 v[16:31], v[92:95], v[34:37], v[16:31]
	v_mul_f32_e32 v33, v42, v32
	v_mul_f32_e32 v42, v43, v33
	v_mul_f32_e32 v43, v145, v42
	v_mul_f32_e32 v47, v149, v47
	v_mul_f32_e32 v40, v44, v45
	v_mul_f32_e32 v44, v147, v32
	v_mul_f32_e32 v33, v146, v33
	v_mfma_f32_32x32x16_bf16 v[0:15], v[88:91], v[34:37], v[0:15]
	v_mul_f32_e32 v32, v41, v42
	v_mul_f32_e32 v34, v144, v43
	v_cvt_pk_bf16_f32 v32, v34, v32
	v_cvt_pk_bf16_f32 v33, v33, v44
	v_cvt_pk_bf16_f32 v34, v40, v46
	v_cvt_pk_bf16_f32 v35, v47, v135
	v_mul_f32_e32 v36, v39, v130
	v_mul_f32_e32 v36, v38, v36
	v_mfma_f32_32x32x16_bf16 v[16:31], v[84:87], v[32:35], v[16:31]
	v_log_f32_e32 v36, v36
	s_nop 0
	v_add_f32_e32 v125, v125, v36
	v_mfma_f32_32x32x16_bf16 v[0:15], v[80:83], v[32:35], v[0:15]
.LBB0_341:
	s_or_b32 s0, s35, 33
	s_cmp_ge_i32 s0, s26
	s_cselect_b64 s[0:1], -1, 0
	s_or_b64 s[0:1], s[18:19], s[0:1]
	s_and_b64 vcc, exec, s[0:1]
	s_cbranch_vccnz .LBB0_344
	v_cmp_le_f32_e32 vcc, s22, v125
	s_cbranch_vccz .LBB0_344
	ds_read_b128 v[32:35], v129 offset:9216
	ds_read_b128 v[80:83], v129 offset:9248
	v_exp_f32_e32 v135, v125
	v_sub_u32_e32 v134, v124, v127
	v_cmp_lt_i32_e32 vcc, 0, v134
	s_waitcnt lgkmcnt(1)
	v_mfma_f32_32x32x16_bf16 v[32:47], v[32:35], v[48:51], 0
	v_cmp_lt_i32_e64 s[0:1], 27, v134
	s_waitcnt lgkmcnt(0)
	v_mfma_f32_32x32x16_bf16 v[32:47], v[80:83], v[52:55], v[32:47]
	ds_read_b128 v[80:83], v129 offset:9280
	ds_read_b128 v[130:133], v129 offset:9312
	s_waitcnt lgkmcnt(1)
	v_mfma_f32_32x32x16_bf16 v[32:47], v[80:83], v[56:59], v[32:47]
	ds_read_b64_tr_b16 v[92:93], v128 offset:49152
	ds_read_b64_tr_b16 v[94:95], v128 offset:50688
	ds_read_b64_tr_b16 v[90:91], v128 offset:50752
	ds_read_b64_tr_b16 v[88:89], v128 offset:49216
	ds_read_b64_tr_b16 v[84:85], v128 offset:52224
	ds_read_b64_tr_b16 v[86:87], v128 offset:53760
	ds_read_b64_tr_b16 v[82:83], v128 offset:53824
	ds_read_b64_tr_b16 v[80:81], v128 offset:52288
	s_waitcnt lgkmcnt(8)
	v_mfma_f32_32x32x16_bf16 v[32:47], v[130:133], v[60:63], v[32:47]
	s_nop 11
	v_max_f32_e64 v32, -v32, -v32
	v_max_f32_e64 v33, -v33, -v33
	v_min_f32_e32 v32, 0x42fc0000, v32
	v_max_f32_e64 v34, -v34, -v34
	v_min_f32_e32 v33, 0x42fc0000, v33
	v_exp_f32_e32 v32, v32
	v_min_f32_e32 v34, 0x42fc0000, v34
	v_exp_f32_e32 v33, v33
	v_max_f32_e64 v35, -v35, -v35
	v_exp_f32_e32 v34, v34
	v_min_f32_e32 v35, 0x42fc0000, v35
	v_exp_f32_e32 v130, v35
	v_add_f32_e32 v35, 1.0, v32
	v_add_f32_e32 v131, 1.0, v33
	v_rcp_f32_e32 v35, v35
	v_max_f32_e64 v36, -v36, -v36
	v_add_f32_e32 v132, 1.0, v34
	v_rcp_f32_e32 v131, v131
	v_min_f32_e32 v36, 0x42fc0000, v36
	v_rcp_f32_e32 v132, v132
	v_exp_f32_e32 v36, v36
	v_add_f32_e32 v133, 1.0, v130
	v_rcp_f32_e32 v136, v133
	v_mul_f32_e32 v32, v32, v35
	v_mul_f32_e32 v133, v135, v35
	v_mul_f32_e32 v33, v33, v131
	v_mul_f32_e32 v137, v135, v131
	v_cndmask_b32_e32 v35, 1.0, v32, vcc
	v_cndmask_b32_e32 v138, 0, v133, vcc
	v_cmp_lt_i32_e32 vcc, 1, v134
	v_mul_f32_e32 v34, v34, v132
	v_mul_f32_e32 v32, v135, v132
	v_cndmask_b32_e32 v131, 1.0, v33, vcc
	v_cndmask_b32_e32 v137, 0, v137, vcc
	v_cmp_lt_i32_e32 vcc, 2, v134
	v_max_f32_e64 v39, -v39, -v39
	v_min_f32_e32 v39, 0x42fc0000, v39
	v_cndmask_b32_e32 v33, 1.0, v34, vcc
	v_add_f32_e32 v34, 1.0, v36
	v_rcp_f32_e32 v34, v34
	v_cndmask_b32_e32 v139, 0, v32, vcc
	v_mul_f32_e32 v32, v130, v136
	v_cmp_lt_i32_e32 vcc, 3, v134
	v_exp_f32_e32 v39, v39
	v_max_f32_e64 v42, -v42, -v42
	v_cndmask_b32_e32 v133, 1.0, v32, vcc
	v_mul_f32_e32 v32, v135, v136
	v_cndmask_b32_e32 v136, 0, v32, vcc
	v_mul_f32_e32 v32, v36, v34
	v_max_f32_e64 v36, -v37, -v37
	v_min_f32_e32 v36, 0x42fc0000, v36
	v_exp_f32_e32 v36, v36
	v_cmp_lt_i32_e32 vcc, 8, v134
	v_mul_f32_e32 v34, v135, v34
	v_max_f32_e64 v37, -v38, -v38
	v_cndmask_b32_e32 v140, 0, v34, vcc
	v_add_f32_e32 v34, 1.0, v36
	v_rcp_f32_e32 v34, v34
	v_min_f32_e32 v37, 0x42fc0000, v37
	v_exp_f32_e32 v37, v37
	v_cndmask_b32_e32 v32, 1.0, v32, vcc
	v_mul_f32_e32 v36, v36, v34
	v_cmp_lt_i32_e32 vcc, 9, v134
	v_mul_f32_e32 v34, v135, v34
	v_min_f32_e32 v42, 0x42fc0000, v42
	v_cndmask_b32_e32 v38, 1.0, v36, vcc
	v_add_f32_e32 v36, 1.0, v37
	v_rcp_f32_e32 v36, v36
	v_cndmask_b32_e32 v141, 0, v34, vcc
	v_cmp_lt_i32_e32 vcc, 10, v134
	v_exp_f32_e32 v42, v42
	v_mul_f32_e32 v34, v37, v36
	v_add_f32_e32 v37, 1.0, v39
	v_rcp_f32_e32 v37, v37
	v_cndmask_b32_e32 v142, 1.0, v34, vcc
	v_mul_f32_e32 v34, v135, v36
	v_cndmask_b32_e32 v143, 0, v34, vcc
	v_mul_f32_e32 v34, v39, v37
	v_max_f32_e64 v36, -v40, -v40
	v_cmp_lt_i32_e32 vcc, 11, v134
	v_min_f32_e32 v36, 0x42fc0000, v36
	v_exp_f32_e32 v36, v36
	v_cndmask_b32_e32 v39, 1.0, v34, vcc
	v_mul_f32_e32 v34, v135, v37
	v_max_f32_e64 v37, -v41, -v41
	v_min_f32_e32 v37, 0x42fc0000, v37
	v_exp_f32_e32 v37, v37
	v_cndmask_b32_e32 v40, 0, v34, vcc
	v_add_f32_e32 v34, 1.0, v36
	v_rcp_f32_e32 v34, v34
	v_add_f32_e32 v41, 1.0, v37
	v_rcp_f32_e32 v41, v41
	v_cmp_lt_i32_e32 vcc, 16, v134
	v_mul_f32_e32 v36, v36, v34
	v_mul_f32_e32 v34, v135, v34
	v_cndmask_b32_e32 v144, 0, v34, vcc
	v_mul_f32_e32 v34, v37, v41
	v_add_f32_e32 v37, 1.0, v42
	v_rcp_f32_e32 v37, v37
	v_cndmask_b32_e32 v36, 1.0, v36, vcc
	v_cmp_lt_i32_e32 vcc, 17, v134
	v_max_f32_e64 v45, -v45, -v45
	v_min_f32_e32 v45, 0x42fc0000, v45
	v_cndmask_b32_e32 v145, 1.0, v34, vcc
	v_mul_f32_e32 v34, v135, v41
	v_cndmask_b32_e32 v41, 0, v34, vcc
	v_mul_f32_e32 v34, v42, v37
	v_max_f32_e64 v42, -v43, -v43
	v_cmp_lt_i32_e32 vcc, 18, v134
	v_min_f32_e32 v42, 0x42fc0000, v42
	v_exp_f32_e32 v42, v42
	v_cndmask_b32_e32 v43, 1.0, v34, vcc
	v_mul_f32_e32 v34, v135, v37
	v_max_f32_e64 v37, -v44, -v44
	v_min_f32_e32 v37, 0x42fc0000, v37
	v_exp_f32_e32 v37, v37
	v_cndmask_b32_e32 v146, 0, v34, vcc
	v_add_f32_e32 v34, 1.0, v42
	v_rcp_f32_e32 v34, v34
	v_add_f32_e32 v44, 1.0, v37
	v_max_f32_e64 v46, -v46, -v46
	v_max_f32_e64 v47, -v47, -v47
	v_rcp_f32_e32 v44, v44
	v_exp_f32_e32 v45, v45
	v_min_f32_e32 v46, 0x42fc0000, v46
	v_min_f32_e32 v47, 0x42fc0000, v47
	v_exp_f32_e32 v46, v46
	v_exp_f32_e32 v47, v47
	v_mul_f32_e32 v42, v42, v34
	v_cmp_lt_i32_e32 vcc, 19, v134
	v_mul_f32_e32 v34, v135, v34
	v_add_f32_e32 v130, 1.0, v46
	v_cndmask_b32_e32 v147, 0, v34, vcc
	v_mul_f32_e32 v34, v37, v44
	v_add_f32_e32 v37, 1.0, v45
	v_rcp_f32_e32 v37, v37
	v_add_f32_e32 v132, 1.0, v47
	v_rcp_f32_e32 v130, v130
	v_rcp_f32_e32 v132, v132
	v_cndmask_b32_e32 v42, 1.0, v42, vcc
	v_cmp_lt_i32_e32 vcc, 24, v134
	v_mul_f32_e32 v44, v135, v44
	v_mul_f32_e32 v45, v45, v37
	v_cndmask_b32_e32 v34, 1.0, v34, vcc
	v_cndmask_b32_e32 v44, 0, v44, vcc
	v_cmp_lt_i32_e32 vcc, 25, v134
	v_mul_f32_e32 v37, v135, v37
	v_mul_f32_e32 v46, v46, v130
	v_cndmask_b32_e32 v45, 1.0, v45, vcc
	v_cndmask_b32_e32 v37, 0, v37, vcc
	v_cmp_lt_i32_e32 vcc, 26, v134
	v_mul_f32_e32 v47, v47, v132
	v_cndmask_b32_e64 v47, 1.0, v47, s[0:1]
	v_cndmask_b32_e32 v46, 1.0, v46, vcc
	v_mul_f32_e32 v34, v34, v45
	v_mul_f32_e32 v134, v46, v47
	v_mul_f32_e32 v134, v34, v134
	v_mov_b32_e32 v148, v134
	v_mov_b32_e32 v240, v134
	s_nop 1
	v_permlane32_swap_b32_e32 v148, v240
	v_cndmask_b32_e64 v148, v148, v240, s[2:3]
	v_mul_f32_e32 v34, v135, v130
	v_cndmask_b32_e32 v149, 0, v34, vcc
	v_mul_f32_e32 v34, v135, v132
	v_cndmask_b32_e64 v34, 0, v34, s[0:1]
	s_waitcnt lgkmcnt(0)
	v_cndmask_b32_e64 v130, 1.0, v148, s[2:3]
	v_mul_f32_e32 v135, v34, v130
	v_mul_f32_e32 v34, v36, v145
	v_mul_f32_e32 v36, v43, v42
	v_mul_f32_e32 v36, v34, v36
	v_mul_f32_e32 v32, v32, v38
	v_mul_f32_e32 v34, v142, v39
	v_mov_b32_e32 v150, v36
	v_mov_b32_e32 v240, v36
	s_nop 1
	v_permlane32_swap_b32_e32 v150, v240
	v_cndmask_b32_e64 v150, v150, v240, s[2:3]
	v_mul_f32_e32 v34, v32, v34
	v_mul_f32_e32 v47, v47, v130
	v_mov_b32_e32 v130, v34
	v_mov_b32_e32 v240, v34
	s_nop 1
	v_permlane32_swap_b32_e32 v130, v240
	v_cndmask_b32_e64 v130, v130, v240, s[2:3]
	v_mul_f32_e32 v46, v46, v47
	v_mul_f32_e32 v32, v134, v148
	s_waitcnt lgkmcnt(1)
	v_mul_f32_e32 v132, v36, v150
	v_mul_f32_e32 v45, v45, v46
	v_mul_f32_e32 v46, v37, v46
	s_waitcnt lgkmcnt(0)
	v_cndmask_b32_e64 v134, 1.0, v130, s[2:3]
	v_pk_mul_f32 v[36:37], v[32:33], v[132:133]
	v_pk_mul_f32 v[34:35], v[34:35], v[130:131]
	v_mul_f32_e32 v132, v36, v134
	v_mul_f32_e32 v134, v39, v132
	v_mul_f32_e32 v142, v142, v134
	v_mul_f32_e32 v148, v38, v142
	v_pk_mul_f32 v[38:39], v[34:35], v[36:37]
	v_mov_b32_e32 v130, v39
	v_mov_b32_e32 v240, v39
	s_nop 1
	v_permlane32_swap_b32_e32 v130, v240
	v_cndmask_b32_e64 v130, v130, v240, s[2:3]
	v_mul_f32_e32 v37, v40, v132
	v_mul_f32_e32 v40, v143, v134
	v_mul_f32_e32 v36, v141, v142
	v_mul_f32_e32 v132, v140, v148
	s_waitcnt lgkmcnt(0)
	v_cndmask_b32_e64 v34, 1.0, v130, s[2:3]
	v_mul_f32_e32 v34, v38, v34
	v_mul_f32_e32 v35, v133, v34
	v_mul_f32_e32 v33, v33, v35
	v_mul_f32_e32 v131, v131, v33
	v_mul_f32_e32 v133, v136, v34
	v_mul_f32_e32 v35, v139, v35
	v_mul_f32_e32 v33, v137, v33
	v_mul_f32_e32 v34, v138, v131
	v_cvt_pk_bf16_f32 v34, v34, v33
	v_cvt_pk_bf16_f32 v35, v35, v133
	v_cvt_pk_bf16_f32 v36, v132, v36
	v_cvt_pk_bf16_f32 v37, v40, v37
	v_cndmask_b32_e64 v33, 1.0, v150, s[2:3]
	v_mul_f32_e32 v32, v32, v33
	v_mfma_f32_32x32x16_bf16 v[16:31], v[92:95], v[34:37], v[16:31]
	v_mul_f32_e32 v33, v42, v32
	v_mul_f32_e32 v42, v43, v33
	v_mul_f32_e32 v43, v145, v42
	v_mul_f32_e32 v47, v149, v47
	v_mul_f32_e32 v40, v44, v45
	v_mul_f32_e32 v44, v147, v32
	v_mul_f32_e32 v33, v146, v33
	v_mfma_f32_32x32x16_bf16 v[0:15], v[88:91], v[34:37], v[0:15]
	v_mul_f32_e32 v32, v41, v42
	v_mul_f32_e32 v34, v144, v43
	v_cvt_pk_bf16_f32 v32, v34, v32
	v_cvt_pk_bf16_f32 v33, v33, v44
	v_cvt_pk_bf16_f32 v34, v40, v46
	v_cvt_pk_bf16_f32 v35, v47, v135
	v_mul_f32_e32 v36, v39, v130
	v_mul_f32_e32 v36, v38, v36
	v_mfma_f32_32x32x16_bf16 v[16:31], v[84:87], v[32:35], v[16:31]
	v_log_f32_e32 v36, v36
	s_nop 0
	v_add_f32_e32 v125, v125, v36
	v_mfma_f32_32x32x16_bf16 v[0:15], v[80:83], v[32:35], v[0:15]
; __device__ __forceinline__ void sb_unit(const Frame& F, int b, int hd, int qi, int dry) {
;     ...
;             float run = C;
;             if (!meta && key0 + 96 < tqw + 31) SB_HALF(96);
;             if (!meta && key0 + 64 < tqw + 31 && __any(run >= SB_DEAD)) SB_HALF(64);
;             if (!meta && key0 + 32 < tqw + 31 && __any(run >= SB_DEAD)) SB_HALF(32);
.LBB0_344:
	s_or_b32 s0, s35, 1
	s_cmp_ge_i32 s0, s26
	s_cselect_b64 s[0:1], -1, 0
	s_or_b64 s[0:1], s[18:19], s[0:1]
	s_and_b64 vcc, exec, s[0:1]
	s_cbranch_vccnz .LBB0_347
	v_cmp_le_f32_e32 vcc, s22, v125
	s_cbranch_vccz .LBB0_347
	ds_read_b128 v[32:35], v129 offset:4608
	ds_read_b128 v[80:83], v129 offset:4640
	v_exp_f32_e32 v135, v125
	v_sub_u32_e32 v134, v126, v127
	v_cmp_lt_i32_e32 vcc, 0, v134
	s_waitcnt lgkmcnt(1)
	v_mfma_f32_32x32x16_bf16 v[32:47], v[32:35], v[48:51], 0
	v_cmp_lt_i32_e64 s[0:1], 27, v134
	s_waitcnt lgkmcnt(0)
	v_mfma_f32_32x32x16_bf16 v[32:47], v[80:83], v[52:55], v[32:47]
	ds_read_b128 v[80:83], v129 offset:4672
	ds_read_b128 v[130:133], v129 offset:4704
	s_waitcnt lgkmcnt(1)
	v_mfma_f32_32x32x16_bf16 v[32:47], v[80:83], v[56:59], v[32:47]
	ds_read_b64_tr_b16 v[92:93], v128 offset:43008
	ds_read_b64_tr_b16 v[94:95], v128 offset:44544
	ds_read_b64_tr_b16 v[90:91], v128 offset:44608
	ds_read_b64_tr_b16 v[88:89], v128 offset:43072
	ds_read_b64_tr_b16 v[84:85], v128 offset:46080
	ds_read_b64_tr_b16 v[86:87], v128 offset:47616
	ds_read_b64_tr_b16 v[82:83], v128 offset:47680
	ds_read_b64_tr_b16 v[80:81], v128 offset:46144
	s_waitcnt lgkmcnt(8)
	v_mfma_f32_32x32x16_bf16 v[32:47], v[130:133], v[60:63], v[32:47]
	s_nop 11
	v_max_f32_e64 v32, -v32, -v32
	v_max_f32_e64 v33, -v33, -v33
	v_min_f32_e32 v32, 0x42fc0000, v32
	v_max_f32_e64 v34, -v34, -v34
	v_min_f32_e32 v33, 0x42fc0000, v33
	v_exp_f32_e32 v32, v32
	v_min_f32_e32 v34, 0x42fc0000, v34
	v_exp_f32_e32 v33, v33
	v_max_f32_e64 v35, -v35, -v35
	v_exp_f32_e32 v34, v34
	v_min_f32_e32 v35, 0x42fc0000, v35
	v_exp_f32_e32 v130, v35
	v_add_f32_e32 v35, 1.0, v32
	v_add_f32_e32 v131, 1.0, v33
	v_rcp_f32_e32 v35, v35
	v_max_f32_e64 v36, -v36, -v36
	v_add_f32_e32 v132, 1.0, v34
	v_rcp_f32_e32 v131, v131
	v_min_f32_e32 v36, 0x42fc0000, v36
	v_rcp_f32_e32 v132, v132
	v_exp_f32_e32 v36, v36
	v_add_f32_e32 v133, 1.0, v130
	v_rcp_f32_e32 v136, v133
	v_mul_f32_e32 v32, v32, v35
	v_mul_f32_e32 v133, v135, v35
	v_mul_f32_e32 v33, v33, v131
	v_mul_f32_e32 v137, v135, v131
	v_cndmask_b32_e32 v35, 1.0, v32, vcc
	v_cndmask_b32_e32 v138, 0, v133, vcc
	v_cmp_lt_i32_e32 vcc, 1, v134
	v_mul_f32_e32 v34, v34, v132
	v_mul_f32_e32 v32, v135, v132
	v_cndmask_b32_e32 v131, 1.0, v33, vcc
	v_cndmask_b32_e32 v137, 0, v137, vcc
	v_cmp_lt_i32_e32 vcc, 2, v134
	v_max_f32_e64 v39, -v39, -v39
	v_min_f32_e32 v39, 0x42fc0000, v39
	v_cndmask_b32_e32 v33, 1.0, v34, vcc
	v_add_f32_e32 v34, 1.0, v36
	v_rcp_f32_e32 v34, v34
	v_cndmask_b32_e32 v139, 0, v32, vcc
	v_mul_f32_e32 v32, v130, v136
	v_cmp_lt_i32_e32 vcc, 3, v134
	v_exp_f32_e32 v39, v39
	v_max_f32_e64 v42, -v42, -v42
	v_cndmask_b32_e32 v133, 1.0, v32, vcc
	v_mul_f32_e32 v32, v135, v136
	v_cndmask_b32_e32 v136, 0, v32, vcc
	v_mul_f32_e32 v32, v36, v34
	v_max_f32_e64 v36, -v37, -v37
	v_min_f32_e32 v36, 0x42fc0000, v36
	v_exp_f32_e32 v36, v36
	v_cmp_lt_i32_e32 vcc, 8, v134
	v_mul_f32_e32 v34, v135, v34
	v_max_f32_e64 v37, -v38, -v38
	v_cndmask_b32_e32 v140, 0, v34, vcc
	v_add_f32_e32 v34, 1.0, v36
	v_rcp_f32_e32 v34, v34
	v_min_f32_e32 v37, 0x42fc0000, v37
	v_exp_f32_e32 v37, v37
	v_cndmask_b32_e32 v32, 1.0, v32, vcc
	v_mul_f32_e32 v36, v36, v34
	v_cmp_lt_i32_e32 vcc, 9, v134
	v_mul_f32_e32 v34, v135, v34
	v_min_f32_e32 v42, 0x42fc0000, v42
	v_cndmask_b32_e32 v38, 1.0, v36, vcc
	v_add_f32_e32 v36, 1.0, v37
	v_rcp_f32_e32 v36, v36
	v_cndmask_b32_e32 v141, 0, v34, vcc
	v_cmp_lt_i32_e32 vcc, 10, v134
	v_exp_f32_e32 v42, v42
	v_mul_f32_e32 v34, v37, v36
	v_add_f32_e32 v37, 1.0, v39
	v_rcp_f32_e32 v37, v37
	v_cndmask_b32_e32 v142, 1.0, v34, vcc
	v_mul_f32_e32 v34, v135, v36
	v_cndmask_b32_e32 v143, 0, v34, vcc
	v_mul_f32_e32 v34, v39, v37
	v_max_f32_e64 v36, -v40, -v40
	v_cmp_lt_i32_e32 vcc, 11, v134
	v_min_f32_e32 v36, 0x42fc0000, v36
	v_exp_f32_e32 v36, v36
	v_cndmask_b32_e32 v39, 1.0, v34, vcc
	v_mul_f32_e32 v34, v135, v37
	v_max_f32_e64 v37, -v41, -v41
	v_min_f32_e32 v37, 0x42fc0000, v37
	v_exp_f32_e32 v37, v37
	v_cndmask_b32_e32 v40, 0, v34, vcc
	v_add_f32_e32 v34, 1.0, v36
	v_rcp_f32_e32 v34, v34
	v_add_f32_e32 v41, 1.0, v37
	v_rcp_f32_e32 v41, v41
	v_cmp_lt_i32_e32 vcc, 16, v134
	v_mul_f32_e32 v36, v36, v34
	v_mul_f32_e32 v34, v135, v34
	v_cndmask_b32_e32 v144, 0, v34, vcc
	v_mul_f32_e32 v34, v37, v41
	v_add_f32_e32 v37, 1.0, v42
	v_rcp_f32_e32 v37, v37
	v_cndmask_b32_e32 v36, 1.0, v36, vcc
	v_cmp_lt_i32_e32 vcc, 17, v134
	v_max_f32_e64 v45, -v45, -v45
	v_min_f32_e32 v45, 0x42fc0000, v45
	v_cndmask_b32_e32 v145, 1.0, v34, vcc
	v_mul_f32_e32 v34, v135, v41
	v_cndmask_b32_e32 v41, 0, v34, vcc
	v_mul_f32_e32 v34, v42, v37
	v_max_f32_e64 v42, -v43, -v43
	v_cmp_lt_i32_e32 vcc, 18, v134
	v_min_f32_e32 v42, 0x42fc0000, v42
	v_exp_f32_e32 v42, v42
	v_cndmask_b32_e32 v43, 1.0, v34, vcc
	v_mul_f32_e32 v34, v135, v37
	v_max_f32_e64 v37, -v44, -v44
	v_min_f32_e32 v37, 0x42fc0000, v37
	v_exp_f32_e32 v37, v37
	v_cndmask_b32_e32 v146, 0, v34, vcc
	v_add_f32_e32 v34, 1.0, v42
	v_rcp_f32_e32 v34, v34
	v_add_f32_e32 v44, 1.0, v37
	v_max_f32_e64 v46, -v46, -v46
	v_max_f32_e64 v47, -v47, -v47
	v_rcp_f32_e32 v44, v44
	v_exp_f32_e32 v45, v45
	v_min_f32_e32 v46, 0x42fc0000, v46
	v_min_f32_e32 v47, 0x42fc0000, v47
	v_exp_f32_e32 v46, v46
	v_exp_f32_e32 v47, v47
	v_mul_f32_e32 v42, v42, v34
	v_cmp_lt_i32_e32 vcc, 19, v134
	v_mul_f32_e32 v34, v135, v34
	v_add_f32_e32 v130, 1.0, v46
	v_cndmask_b32_e32 v147, 0, v34, vcc
	v_mul_f32_e32 v34, v37, v44
	v_add_f32_e32 v37, 1.0, v45
	v_rcp_f32_e32 v37, v37
	v_add_f32_e32 v132, 1.0, v47
	v_rcp_f32_e32 v130, v130
	v_rcp_f32_e32 v132, v132
	v_cndmask_b32_e32 v42, 1.0, v42, vcc
	v_cmp_lt_i32_e32 vcc, 24, v134
	v_mul_f32_e32 v44, v135, v44
	v_mul_f32_e32 v45, v45, v37
	v_cndmask_b32_e32 v34, 1.0, v34, vcc
	v_cndmask_b32_e32 v44, 0, v44, vcc
	v_cmp_lt_i32_e32 vcc, 25, v134
	v_mul_f32_e32 v37, v135, v37
	v_mul_f32_e32 v46, v46, v130
	v_cndmask_b32_e32 v45, 1.0, v45, vcc
	v_cndmask_b32_e32 v37, 0, v37, vcc
	v_cmp_lt_i32_e32 vcc, 26, v134
	v_mul_f32_e32 v47, v47, v132
	v_cndmask_b32_e64 v47, 1.0, v47, s[0:1]
	v_cndmask_b32_e32 v46, 1.0, v46, vcc
	v_mul_f32_e32 v34, v34, v45
	v_mul_f32_e32 v134, v46, v47
	v_mul_f32_e32 v134, v34, v134
	v_mov_b32_e32 v148, v134
	v_mov_b32_e32 v240, v134
	s_nop 1
	v_permlane32_swap_b32_e32 v148, v240
	v_cndmask_b32_e64 v148, v148, v240, s[2:3]
	v_mul_f32_e32 v34, v135, v130
	v_cndmask_b32_e32 v149, 0, v34, vcc
	v_mul_f32_e32 v34, v135, v132
	v_cndmask_b32_e64 v34, 0, v34, s[0:1]
	s_waitcnt lgkmcnt(0)
; __device__ __forceinline__ void sb_unit(const Frame& F, int b, int hd, int qi, int dry) {
;     ...
;             float run = C;
;             if (!meta && key0 + 96 < tqw + 31) SB_HALF(96);
;             if (!meta && key0 + 64 < tqw + 31 && __any(run >= SB_DEAD)) SB_HALF(64);
;             if (!meta && key0 + 32 < tqw + 31 && __any(run >= SB_DEAD)) SB_HALF(32);
;             if (__any(run >= SB_DEAD)) SB_HALF(0);
	v_cndmask_b32_e64 v130, 1.0, v148, s[2:3]
	v_mul_f32_e32 v135, v34, v130
	v_mul_f32_e32 v34, v36, v145
	v_mul_f32_e32 v36, v43, v42
	v_mul_f32_e32 v36, v34, v36
	v_mul_f32_e32 v32, v32, v38
	v_mul_f32_e32 v34, v142, v39
	v_mov_b32_e32 v150, v36
	v_mov_b32_e32 v240, v36
	s_nop 1
	v_permlane32_swap_b32_e32 v150, v240
	v_cndmask_b32_e64 v150, v150, v240, s[2:3]
	v_mul_f32_e32 v34, v32, v34
	v_mul_f32_e32 v47, v47, v130
	v_mov_b32_e32 v130, v34
	v_mov_b32_e32 v240, v34
	s_nop 1
	v_permlane32_swap_b32_e32 v130, v240
	v_cndmask_b32_e64 v130, v130, v240, s[2:3]
	v_mul_f32_e32 v46, v46, v47
	v_mul_f32_e32 v32, v134, v148
	s_waitcnt lgkmcnt(1)
	v_mul_f32_e32 v132, v36, v150
	v_mul_f32_e32 v45, v45, v46
	v_mul_f32_e32 v46, v37, v46
	s_waitcnt lgkmcnt(0)
	v_cndmask_b32_e64 v134, 1.0, v130, s[2:3]
	v_pk_mul_f32 v[36:37], v[32:33], v[132:133]
	v_pk_mul_f32 v[34:35], v[34:35], v[130:131]
	v_mul_f32_e32 v132, v36, v134
	v_mul_f32_e32 v134, v39, v132
	v_mul_f32_e32 v142, v142, v134
	v_mul_f32_e32 v148, v38, v142
	v_pk_mul_f32 v[38:39], v[34:35], v[36:37]
	v_mov_b32_e32 v130, v39
	v_mov_b32_e32 v240, v39
	s_nop 1
	v_permlane32_swap_b32_e32 v130, v240
	v_cndmask_b32_e64 v130, v130, v240, s[2:3]
	v_mul_f32_e32 v37, v40, v132
	v_mul_f32_e32 v40, v143, v134
	v_mul_f32_e32 v36, v141, v142
	v_mul_f32_e32 v132, v140, v148
	s_waitcnt lgkmcnt(0)
	v_cndmask_b32_e64 v34, 1.0, v130, s[2:3]
	v_mul_f32_e32 v34, v38, v34
	v_mul_f32_e32 v35, v133, v34
	v_mul_f32_e32 v33, v33, v35
	v_mul_f32_e32 v131, v131, v33
	v_mul_f32_e32 v133, v136, v34
	v_mul_f32_e32 v35, v139, v35
	v_mul_f32_e32 v33, v137, v33
	v_mul_f32_e32 v34, v138, v131
	v_cvt_pk_bf16_f32 v34, v34, v33
	v_cvt_pk_bf16_f32 v35, v35, v133
	v_cvt_pk_bf16_f32 v36, v132, v36
	v_cvt_pk_bf16_f32 v37, v40, v37
	v_cndmask_b32_e64 v33, 1.0, v150, s[2:3]
	v_mul_f32_e32 v32, v32, v33
	v_mfma_f32_32x32x16_bf16 v[16:31], v[92:95], v[34:37], v[16:31]
	v_mul_f32_e32 v33, v42, v32
	v_mul_f32_e32 v42, v43, v33
	v_mul_f32_e32 v43, v145, v42
	v_mul_f32_e32 v47, v149, v47
	v_mul_f32_e32 v40, v44, v45
	v_mul_f32_e32 v44, v147, v32
	v_mul_f32_e32 v33, v146, v33
	v_mfma_f32_32x32x16_bf16 v[0:15], v[88:91], v[34:37], v[0:15]
	v_mul_f32_e32 v32, v41, v42
	v_mul_f32_e32 v34, v144, v43
	v_cvt_pk_bf16_f32 v32, v34, v32
	v_cvt_pk_bf16_f32 v33, v33, v44
	v_cvt_pk_bf16_f32 v34, v40, v46
	v_cvt_pk_bf16_f32 v35, v47, v135
	v_mul_f32_e32 v36, v39, v130
	v_mul_f32_e32 v36, v38, v36
	v_mfma_f32_32x32x16_bf16 v[16:31], v[84:87], v[32:35], v[16:31]
	v_log_f32_e32 v36, v36
	s_nop 0
	v_add_f32_e32 v125, v125, v36
	v_mfma_f32_32x32x16_bf16 v[0:15], v[80:83], v[32:35], v[0:15]
.LBB0_347:
	v_cmp_le_f32_e32 vcc, s22, v125
	s_cbranch_vccz .LBB0_349
	ds_read_b128 v[32:35], v129
	ds_read_b128 v[80:83], v129 offset:32
	s_waitcnt lgkmcnt(1)
	v_mfma_f32_32x32x16_bf16 v[32:47], v[32:35], v[48:51], 0
	s_waitcnt lgkmcnt(0)
	v_mfma_f32_32x32x16_bf16 v[32:47], v[80:83], v[52:55], v[32:47]
	ds_read_b128 v[80:83], v129 offset:64
	ds_read_b128 v[130:133], v129 offset:96
	v_cndmask_b32_e64 v129, v114, 16, s[18:19]
	v_sub_u32_e32 v127, v129, v127
	v_cmp_lt_i32_e32 vcc, 0, v127
	v_cmp_lt_i32_e64 s[0:1], 27, v127
	s_waitcnt lgkmcnt(1)
	v_mfma_f32_32x32x16_bf16 v[32:47], v[80:83], v[56:59], v[32:47]
	ds_read_b64_tr_b16 v[92:93], v128 offset:36864
	ds_read_b64_tr_b16 v[94:95], v128 offset:38400
	ds_read_b64_tr_b16 v[90:91], v128 offset:38464
	ds_read_b64_tr_b16 v[88:89], v128 offset:36928
	ds_read_b64_tr_b16 v[84:85], v128 offset:39936
	ds_read_b64_tr_b16 v[86:87], v128 offset:41472
	ds_read_b64_tr_b16 v[82:83], v128 offset:41536
	ds_read_b64_tr_b16 v[80:81], v128 offset:40000
	v_exp_f32_e32 v128, v125
	s_waitcnt lgkmcnt(8)
	v_mfma_f32_32x32x16_bf16 v[32:47], v[130:133], v[60:63], v[32:47]
	s_nop 11
	v_max_f32_e64 v32, -v32, -v32
	v_max_f32_e64 v33, -v33, -v33
	v_min_f32_e32 v32, 0x42fc0000, v32
	v_max_f32_e64 v34, -v34, -v34
	v_min_f32_e32 v33, 0x42fc0000, v33
	v_exp_f32_e32 v32, v32
	v_min_f32_e32 v34, 0x42fc0000, v34
	v_exp_f32_e32 v33, v33
	v_max_f32_e64 v35, -v35, -v35
	v_exp_f32_e32 v34, v34
	v_min_f32_e32 v35, 0x42fc0000, v35
	v_exp_f32_e32 v130, v35
	v_add_f32_e32 v35, 1.0, v32
	v_add_f32_e32 v129, 1.0, v33
	v_rcp_f32_e32 v35, v35
	v_add_f32_e32 v131, 1.0, v34
	v_rcp_f32_e32 v129, v129
	v_rcp_f32_e32 v131, v131
	v_add_f32_e32 v132, 1.0, v130
	v_max_f32_e64 v36, -v36, -v36
	v_rcp_f32_e32 v132, v132
	v_mul_f32_e32 v32, v32, v35
	v_mul_f32_e32 v133, v128, v35
	v_min_f32_e32 v36, 0x42fc0000, v36
	v_mul_f32_e32 v33, v33, v129
	v_mul_f32_e32 v134, v128, v129
	v_cndmask_b32_e32 v35, 1.0, v32, vcc
	v_cndmask_b32_e32 v133, 0, v133, vcc
	v_cmp_lt_i32_e32 vcc, 1, v127
	v_mul_f32_e32 v34, v34, v131
	v_exp_f32_e32 v32, v36
	v_cndmask_b32_e32 v129, 1.0, v33, vcc
	v_cndmask_b32_e32 v134, 0, v134, vcc
	v_cmp_lt_i32_e32 vcc, 2, v127
	v_add_f32_e32 v36, 1.0, v32
	v_rcp_f32_e32 v36, v36
	v_cndmask_b32_e32 v33, 1.0, v34, vcc
	v_mul_f32_e32 v34, v128, v131
	v_cndmask_b32_e32 v135, 0, v34, vcc
	v_mul_f32_e32 v34, v130, v132
	v_cmp_lt_i32_e32 vcc, 3, v127
	v_mul_f32_e32 v32, v32, v36
	v_mul_f32_e32 v36, v128, v36
	v_cndmask_b32_e32 v131, 1.0, v34, vcc
	v_mul_f32_e32 v34, v128, v132
	v_cndmask_b32_e32 v132, 0, v34, vcc
	v_max_f32_e64 v34, -v37, -v37
	v_min_f32_e32 v34, 0x42fc0000, v34
	v_exp_f32_e32 v34, v34
	v_cmp_lt_i32_e32 vcc, 8, v127
	v_max_f32_e64 v37, -v38, -v38
	v_min_f32_e32 v37, 0x42fc0000, v37
	v_cndmask_b32_e32 v136, 0, v36, vcc
	v_add_f32_e32 v36, 1.0, v34
	v_rcp_f32_e32 v36, v36
	v_exp_f32_e32 v37, v37
	v_cndmask_b32_e32 v32, 1.0, v32, vcc
	v_cmp_lt_i32_e32 vcc, 9, v127
	v_mul_f32_e32 v34, v34, v36
	v_max_f32_e64 v39, -v39, -v39
	v_cndmask_b32_e32 v38, 1.0, v34, vcc
	v_add_f32_e32 v34, 1.0, v37
	v_min_f32_e32 v39, 0x42fc0000, v39
	v_rcp_f32_e32 v34, v34
	v_exp_f32_e32 v39, v39
	v_mul_f32_e32 v36, v128, v36
	v_cndmask_b32_e32 v137, 0, v36, vcc
	v_mul_f32_e32 v36, v37, v34
	v_add_f32_e32 v37, 1.0, v39
	v_rcp_f32_e32 v37, v37
	v_cmp_lt_i32_e32 vcc, 10, v127
	v_mul_f32_e32 v34, v128, v34
	v_max_f32_e64 v42, -v42, -v42
	v_cndmask_b32_e32 v138, 1.0, v36, vcc
	v_cndmask_b32_e32 v139, 0, v34, vcc
	v_mul_f32_e32 v34, v39, v37
	v_max_f32_e64 v36, -v40, -v40
	v_cmp_lt_i32_e32 vcc, 11, v127
	v_min_f32_e32 v36, 0x42fc0000, v36
	v_exp_f32_e32 v36, v36
	v_cndmask_b32_e32 v39, 1.0, v34, vcc
	v_mul_f32_e32 v34, v128, v37
	v_max_f32_e64 v37, -v41, -v41
	v_min_f32_e32 v37, 0x42fc0000, v37
	v_exp_f32_e32 v37, v37
	v_cndmask_b32_e32 v40, 0, v34, vcc
	v_add_f32_e32 v34, 1.0, v36
	v_rcp_f32_e32 v34, v34
	v_add_f32_e32 v41, 1.0, v37
	v_min_f32_e32 v42, 0x42fc0000, v42
	v_rcp_f32_e32 v41, v41
	v_exp_f32_e32 v42, v42
	v_mul_f32_e32 v36, v36, v34
	v_cmp_lt_i32_e32 vcc, 16, v127
	v_mul_f32_e32 v34, v128, v34
	v_max_f32_e64 v45, -v45, -v45
	v_cndmask_b32_e32 v140, 0, v34, vcc
	v_mul_f32_e32 v34, v37, v41
	v_add_f32_e32 v37, 1.0, v42
	v_rcp_f32_e32 v37, v37
	v_cndmask_b32_e32 v36, 1.0, v36, vcc
	v_cmp_lt_i32_e32 vcc, 17, v127
	v_min_f32_e32 v45, 0x42fc0000, v45
	v_max_f32_e64 v46, -v46, -v46
	v_cndmask_b32_e32 v141, 1.0, v34, vcc
	v_mul_f32_e32 v34, v128, v41
	v_cndmask_b32_e32 v41, 0, v34, vcc
	v_mul_f32_e32 v34, v42, v37
	v_max_f32_e64 v42, -v43, -v43
	v_cmp_lt_i32_e32 vcc, 18, v127
	v_min_f32_e32 v42, 0x42fc0000, v42
	v_exp_f32_e32 v42, v42
	v_cndmask_b32_e32 v43, 1.0, v34, vcc
	v_mul_f32_e32 v34, v128, v37
	v_max_f32_e64 v37, -v44, -v44
	v_min_f32_e32 v37, 0x42fc0000, v37
	v_exp_f32_e32 v37, v37
	v_cndmask_b32_e32 v142, 0, v34, vcc
	v_add_f32_e32 v34, 1.0, v42
	v_rcp_f32_e32 v34, v34
	v_add_f32_e32 v44, 1.0, v37
	v_max_f32_e64 v47, -v47, -v47
	v_rcp_f32_e32 v44, v44
	v_exp_f32_e32 v45, v45
	v_min_f32_e32 v46, 0x42fc0000, v46
	v_min_f32_e32 v47, 0x42fc0000, v47
	v_exp_f32_e32 v46, v46
	v_exp_f32_e32 v47, v47
	v_mul_f32_e32 v42, v42, v34
	v_cmp_lt_i32_e32 vcc, 19, v127
	v_mul_f32_e32 v34, v128, v34
	v_add_f32_e32 v130, 1.0, v46
	v_cndmask_b32_e32 v143, 0, v34, vcc
	v_mul_f32_e32 v34, v37, v44
	v_add_f32_e32 v37, 1.0, v45
	v_rcp_f32_e32 v37, v37
	v_add_f32_e32 v144, 1.0, v47
	v_rcp_f32_e32 v130, v130
	v_rcp_f32_e32 v144, v144
	v_cndmask_b32_e32 v42, 1.0, v42, vcc
	v_cmp_lt_i32_e32 vcc, 24, v127
	v_mul_f32_e32 v44, v128, v44
	v_mul_f32_e32 v45, v45, v37
	v_cndmask_b32_e32 v34, 1.0, v34, vcc
	v_cndmask_b32_e32 v44, 0, v44, vcc
	v_cmp_lt_i32_e32 vcc, 25, v127
	v_mul_f32_e32 v37, v128, v37
	v_mul_f32_e32 v46, v46, v130
	v_cndmask_b32_e32 v45, 1.0, v45, vcc
	v_cndmask_b32_e32 v37, 0, v37, vcc
	v_cmp_lt_i32_e32 vcc, 26, v127
	v_mul_f32_e32 v47, v47, v144
	v_cndmask_b32_e64 v47, 1.0, v47, s[0:1]
	v_cndmask_b32_e32 v46, 1.0, v46, vcc
	v_mul_f32_e32 v34, v34, v45
	v_mul_f32_e32 v127, v46, v47
	v_mul_f32_e32 v127, v34, v127
	v_mov_b32_e32 v145, v127
	v_mov_b32_e32 v240, v127
	s_nop 1
	v_permlane32_swap_b32_e32 v145, v240
	v_cndmask_b32_e64 v145, v145, v240, s[2:3]
	v_mul_f32_e32 v34, v128, v130
	v_cndmask_b32_e32 v130, 0, v34, vcc
	v_mul_f32_e32 v34, v128, v144
	v_cndmask_b32_e64 v34, 0, v34, s[0:1]
	s_waitcnt lgkmcnt(0)
	v_cndmask_b32_e64 v128, 1.0, v145, s[2:3]
	v_mul_f32_e32 v144, v34, v128
	v_mul_f32_e32 v34, v36, v141
	v_mul_f32_e32 v36, v43, v42
	v_mul_f32_e32 v36, v34, v36
	v_mul_f32_e32 v32, v32, v38
	v_mul_f32_e32 v34, v138, v39
	v_mov_b32_e32 v146, v36
	v_mov_b32_e32 v240, v36
	s_nop 1
	v_permlane32_swap_b32_e32 v146, v240
	v_cndmask_b32_e64 v146, v146, v240, s[2:3]
	v_mul_f32_e32 v34, v32, v34
	v_mul_f32_e32 v47, v47, v128
	v_mov_b32_e32 v128, v34
	v_mov_b32_e32 v240, v34
	s_nop 1
	v_permlane32_swap_b32_e32 v128, v240
	v_cndmask_b32_e64 v128, v128, v240, s[2:3]
	v_mul_f32_e32 v46, v46, v47
	v_mul_f32_e32 v47, v130, v47
	v_mul_f32_e32 v32, v127, v145
	s_waitcnt lgkmcnt(1)
	v_mul_f32_e32 v130, v36, v146
	v_mul_f32_e32 v45, v45, v46
	v_mul_f32_e32 v46, v37, v46
	s_waitcnt lgkmcnt(0)
	v_cndmask_b32_e64 v127, 1.0, v128, s[2:3]
	v_pk_mul_f32 v[36:37], v[32:33], v[130:131]
	v_pk_mul_f32 v[34:35], v[34:35], v[128:129]
	v_mul_f32_e32 v127, v36, v127
	v_mul_f32_e32 v130, v39, v127
	v_mul_f32_e32 v138, v138, v130
	v_mul_f32_e32 v145, v38, v138
	v_pk_mul_f32 v[38:39], v[34:35], v[36:37]
	v_mov_b32_e32 v128, v39
	v_mov_b32_e32 v240, v39
	s_nop 1
	v_permlane32_swap_b32_e32 v128, v240
	v_cndmask_b32_e64 v128, v128, v240, s[2:3]
	v_mul_f32_e32 v37, v40, v127
	v_mul_f32_e32 v40, v139, v130
	v_mul_f32_e32 v36, v137, v138
	v_mul_f32_e32 v127, v136, v145
	s_waitcnt lgkmcnt(0)
	v_cndmask_b32_e64 v34, 1.0, v128, s[2:3]
	v_mul_f32_e32 v34, v38, v34
	v_mul_f32_e32 v35, v131, v34
	v_mul_f32_e32 v33, v33, v35
	v_mul_f32_e32 v129, v129, v33
	v_mul_f32_e32 v130, v132, v34
	v_mul_f32_e32 v35, v135, v35
	v_mul_f32_e32 v33, v134, v33
	v_mul_f32_e32 v34, v133, v129
	v_cvt_pk_bf16_f32 v34, v34, v33
	v_cvt_pk_bf16_f32 v35, v35, v130
	v_cvt_pk_bf16_f32 v36, v127, v36
	v_cvt_pk_bf16_f32 v37, v40, v37
	v_cndmask_b32_e64 v33, 1.0, v146, s[2:3]
	v_mul_f32_e32 v32, v32, v33
	v_mfma_f32_32x32x16_bf16 v[16:31], v[92:95], v[34:37], v[16:31]
	v_mul_f32_e32 v33, v42, v32
	v_mul_f32_e32 v42, v43, v33
	v_mul_f32_e32 v43, v141, v42
	v_mul_f32_e32 v40, v44, v45
	v_mul_f32_e32 v44, v143, v32
	v_mul_f32_e32 v33, v142, v33
	v_mul_f32_e32 v32, v41, v42
	v_mfma_f32_32x32x16_bf16 v[0:15], v[88:91], v[34:37], v[0:15]
	v_mul_f32_e32 v34, v140, v43
	v_cvt_pk_bf16_f32 v32, v34, v32
	v_cvt_pk_bf16_f32 v33, v33, v44
	v_cvt_pk_bf16_f32 v34, v40, v46
	v_cvt_pk_bf16_f32 v35, v47, v144
	v_mul_f32_e32 v36, v39, v128
	v_mul_f32_e32 v36, v38, v36
	v_mfma_f32_32x32x16_bf16 v[16:31], v[84:87], v[32:35], v[16:31]
	v_log_f32_e32 v36, v36
	s_nop 0
	v_add_f32_e32 v125, v125, v36
	v_mfma_f32_32x32x16_bf16 v[0:15], v[80:83], v[32:35], v[0:15]

; #define LAS __attribute__((address_space(3)))
; #define S_LOAD(key0) do { st0 = *(const u32x4*)(kg + (size_t)(key0) * 1024); st1 = *(const u32x4*)(kg + (size_t)((key0) + 64) * 1024); st2 = *(const u32x4*)(vg + (size_t)(key0) * 1024); st3 = *(const u32x4*)(vg + (size_t)((key0) + 64) * 1024); } while (0)
; __device__ __forceinline__ void sb_unit(const Frame& F, int b, int hd, int qi, int dry) {
;     ...
;     for (int it = 0; it < nt; ++it) {
;         const bool meta = (it > jmax);
;         const int key0 = meta ? 0 : NMETA + 128 * (jmax - it);
;         if (it + 1 < nt) { const int nk = (it + 1 > jmax) ? 0 : NMETA + 128 * (jmax - it - 1); S_LOAD(nk); }
;         if (!dead && (meta || key0 < tqw + 31)) {
;             const LAS unsigned char* kb = lds + kra + (it & 1) * SK_BUF;
;             const LAS unsigned char* vb = lds + vra + (it & 1) * SV_BUF;
;     ...
;             float run = C;
;             if (!meta && key0 + 96 < tqw + 31) SB_HALF(96);
.LBB0_360:
	s_xor_b64 s[0:1], s[0:1], -1
	s_andn2_b64 vcc, exec, s[0:1]
	s_mov_b64 s[0:1], -1
	s_cbranch_vccnz .LBB0_373
	s_add_i32 s34, s31, 0xffffff10
	s_cmp_gt_u32 s35, s27
	s_cselect_b64 s[18:19], -1, 0
	s_and_b64 s[0:1], s[18:19], exec
	s_cselect_b32 s34, 0, s34
	s_cmp_lt_i32 s34, s29
	s_cselect_b64 s[0:1], -1, 0
	s_or_b64 s[0:1], s[18:19], s[0:1]
	s_andn2_b64 vcc, exec, s[0:1]
	s_mov_b64 s[0:1], 0
	s_cbranch_vccnz .LBB0_373
	s_and_b32 s0, s35, 1
	s_mul_i32 s35, s0, 0x4800
	s_mul_i32 s36, s0, 0x6000
	s_or_b32 s0, s34, 0x41
	s_cmp_ge_i32 s0, s25
	s_cselect_b64 s[0:1], -1, 0
	s_or_b64 s[0:1], s[18:19], s[0:1]
	s_and_b64 vcc, exec, s[0:1]
	v_add_u32_e32 v129, s35, v118
	v_or_b32_e32 v127, s34, v205
	v_add_u32_e32 v128, s36, v119
	s_cbranch_vccnz .LBB0_364
	ds_read_b128 v[32:35], v129 offset:13824
	ds_read_b128 v[80:83], v129 offset:13856
	v_exp_f32_e32 v135, v126
	v_sub_u32_e32 v134, v115, v127
	v_cmp_lt_i32_e32 vcc, 0, v134
	s_waitcnt lgkmcnt(1)
	v_mfma_f32_32x32x16_bf16 v[32:47], v[32:35], v[48:51], 0
	v_cmp_lt_i32_e64 s[0:1], 27, v134
	s_waitcnt lgkmcnt(0)
	v_mfma_f32_32x32x16_bf16 v[32:47], v[80:83], v[52:55], v[32:47]
	ds_read_b128 v[80:83], v129 offset:13888
	ds_read_b128 v[130:133], v129 offset:13920
	s_waitcnt lgkmcnt(1)
	v_mfma_f32_32x32x16_bf16 v[32:47], v[80:83], v[56:59], v[32:47]
	ds_read_b64_tr_b16 v[92:93], v128 offset:55296
	ds_read_b64_tr_b16 v[94:95], v128 offset:56832
	ds_read_b64_tr_b16 v[90:91], v128 offset:56896
	ds_read_b64_tr_b16 v[88:89], v128 offset:55360
	ds_read_b64_tr_b16 v[84:85], v128 offset:58368
	ds_read_b64_tr_b16 v[86:87], v128 offset:59904
	ds_read_b64_tr_b16 v[82:83], v128 offset:59968
	ds_read_b64_tr_b16 v[80:81], v128 offset:58432
	s_waitcnt lgkmcnt(8)
	v_mfma_f32_32x32x16_bf16 v[32:47], v[130:133], v[60:63], v[32:47]
	s_nop 11
	v_max_f32_e64 v32, -v32, -v32
	v_max_f32_e64 v33, -v33, -v33
	v_min_f32_e32 v32, 0x42fc0000, v32
	v_max_f32_e64 v34, -v34, -v34
	v_min_f32_e32 v33, 0x42fc0000, v33
	v_exp_f32_e32 v32, v32
	v_min_f32_e32 v34, 0x42fc0000, v34
	v_exp_f32_e32 v33, v33
	v_max_f32_e64 v35, -v35, -v35
	v_exp_f32_e32 v34, v34
	v_min_f32_e32 v35, 0x42fc0000, v35
	v_exp_f32_e32 v130, v35
	v_add_f32_e32 v35, 1.0, v32
	v_add_f32_e32 v131, 1.0, v33
	v_rcp_f32_e32 v35, v35
	v_max_f32_e64 v36, -v36, -v36
	v_add_f32_e32 v132, 1.0, v34
	v_rcp_f32_e32 v131, v131
	v_min_f32_e32 v36, 0x42fc0000, v36
	v_rcp_f32_e32 v132, v132
	v_exp_f32_e32 v36, v36
	v_add_f32_e32 v133, 1.0, v130
	v_rcp_f32_e32 v136, v133
	v_mul_f32_e32 v32, v32, v35
	v_mul_f32_e32 v133, v135, v35
	v_mul_f32_e32 v33, v33, v131
	v_mul_f32_e32 v137, v135, v131
	v_cndmask_b32_e32 v35, 1.0, v32, vcc
	v_cndmask_b32_e32 v138, 0, v133, vcc
	v_cmp_lt_i32_e32 vcc, 1, v134
	v_mul_f32_e32 v34, v34, v132
	v_mul_f32_e32 v32, v135, v132
	v_cndmask_b32_e32 v131, 1.0, v33, vcc
	v_cndmask_b32_e32 v137, 0, v137, vcc
	v_cmp_lt_i32_e32 vcc, 2, v134
	v_max_f32_e64 v39, -v39, -v39
	v_min_f32_e32 v39, 0x42fc0000, v39
	v_cndmask_b32_e32 v33, 1.0, v34, vcc
	v_add_f32_e32 v34, 1.0, v36
	v_rcp_f32_e32 v34, v34
	v_cndmask_b32_e32 v139, 0, v32, vcc
	v_mul_f32_e32 v32, v130, v136
	v_cmp_lt_i32_e32 vcc, 3, v134
	v_exp_f32_e32 v39, v39
	v_max_f32_e64 v42, -v42, -v42
	v_cndmask_b32_e32 v133, 1.0, v32, vcc
	v_mul_f32_e32 v32, v135, v136
	v_cndmask_b32_e32 v136, 0, v32, vcc
	v_mul_f32_e32 v32, v36, v34
	v_max_f32_e64 v36, -v37, -v37
	v_min_f32_e32 v36, 0x42fc0000, v36
	v_exp_f32_e32 v36, v36
	v_cmp_lt_i32_e32 vcc, 8, v134
	v_mul_f32_e32 v34, v135, v34
	v_max_f32_e64 v37, -v38, -v38
	v_cndmask_b32_e32 v140, 0, v34, vcc
	v_add_f32_e32 v34, 1.0, v36
	v_rcp_f32_e32 v34, v34
	v_min_f32_e32 v37, 0x42fc0000, v37
	v_exp_f32_e32 v37, v37
	v_cndmask_b32_e32 v32, 1.0, v32, vcc
	v_mul_f32_e32 v36, v36, v34
	v_cmp_lt_i32_e32 vcc, 9, v134
	v_mul_f32_e32 v34, v135, v34
	v_min_f32_e32 v42, 0x42fc0000, v42
	v_cndmask_b32_e32 v38, 1.0, v36, vcc
	v_add_f32_e32 v36, 1.0, v37
	v_rcp_f32_e32 v36, v36
	v_cndmask_b32_e32 v141, 0, v34, vcc
	v_cmp_lt_i32_e32 vcc, 10, v134
	v_exp_f32_e32 v42, v42
	v_mul_f32_e32 v34, v37, v36
	v_add_f32_e32 v37, 1.0, v39
	v_rcp_f32_e32 v37, v37
	v_cndmask_b32_e32 v142, 1.0, v34, vcc
	v_mul_f32_e32 v34, v135, v36
	v_cndmask_b32_e32 v143, 0, v34, vcc
	v_mul_f32_e32 v34, v39, v37
	v_max_f32_e64 v36, -v40, -v40
	v_cmp_lt_i32_e32 vcc, 11, v134
	v_min_f32_e32 v36, 0x42fc0000, v36
	v_exp_f32_e32 v36, v36
	v_cndmask_b32_e32 v39, 1.0, v34, vcc
	v_mul_f32_e32 v34, v135, v37
	v_max_f32_e64 v37, -v41, -v41
	v_min_f32_e32 v37, 0x42fc0000, v37
	v_exp_f32_e32 v37, v37
	v_cndmask_b32_e32 v40, 0, v34, vcc
	v_add_f32_e32 v34, 1.0, v36
	v_rcp_f32_e32 v34, v34
	v_add_f32_e32 v41, 1.0, v37
	v_rcp_f32_e32 v41, v41
	v_cmp_lt_i32_e32 vcc, 16, v134
	v_mul_f32_e32 v36, v36, v34
	v_mul_f32_e32 v34, v135, v34
	v_cndmask_b32_e32 v144, 0, v34, vcc
	v_mul_f32_e32 v34, v37, v41
	v_add_f32_e32 v37, 1.0, v42
	v_rcp_f32_e32 v37, v37
	v_cndmask_b32_e32 v36, 1.0, v36, vcc
	v_cmp_lt_i32_e32 vcc, 17, v134
	v_max_f32_e64 v45, -v45, -v45
	v_min_f32_e32 v45, 0x42fc0000, v45
	v_cndmask_b32_e32 v145, 1.0, v34, vcc
	v_mul_f32_e32 v34, v135, v41
	v_cndmask_b32_e32 v41, 0, v34, vcc
	v_mul_f32_e32 v34, v42, v37
	v_max_f32_e64 v42, -v43, -v43
	v_cmp_lt_i32_e32 vcc, 18, v134
	v_min_f32_e32 v42, 0x42fc0000, v42
	v_exp_f32_e32 v42, v42
	v_cndmask_b32_e32 v43, 1.0, v34, vcc
	v_mul_f32_e32 v34, v135, v37
	v_max_f32_e64 v37, -v44, -v44
	v_min_f32_e32 v37, 0x42fc0000, v37
	v_exp_f32_e32 v37, v37
	v_cndmask_b32_e32 v146, 0, v34, vcc
	v_add_f32_e32 v34, 1.0, v42
	v_rcp_f32_e32 v34, v34
	v_add_f32_e32 v44, 1.0, v37
	v_max_f32_e64 v46, -v46, -v46
	v_max_f32_e64 v47, -v47, -v47
	v_rcp_f32_e32 v44, v44
	v_exp_f32_e32 v45, v45
	v_min_f32_e32 v46, 0x42fc0000, v46
	v_min_f32_e32 v47, 0x42fc0000, v47
	v_exp_f32_e32 v46, v46
	v_exp_f32_e32 v47, v47
	v_mul_f32_e32 v42, v42, v34
	v_cmp_lt_i32_e32 vcc, 19, v134
	v_mul_f32_e32 v34, v135, v34
	v_add_f32_e32 v130, 1.0, v46
	v_cndmask_b32_e32 v147, 0, v34, vcc
	v_mul_f32_e32 v34, v37, v44
	v_add_f32_e32 v37, 1.0, v45
	v_rcp_f32_e32 v37, v37
	v_add_f32_e32 v132, 1.0, v47
	v_rcp_f32_e32 v130, v130
	v_rcp_f32_e32 v132, v132
	v_cndmask_b32_e32 v42, 1.0, v42, vcc
	v_cmp_lt_i32_e32 vcc, 24, v134
	v_mul_f32_e32 v44, v135, v44
	v_mul_f32_e32 v45, v45, v37
	v_cndmask_b32_e32 v34, 1.0, v34, vcc
	v_cndmask_b32_e32 v44, 0, v44, vcc
	v_cmp_lt_i32_e32 vcc, 25, v134
	v_mul_f32_e32 v37, v135, v37
	v_mul_f32_e32 v46, v46, v130
	v_cndmask_b32_e32 v45, 1.0, v45, vcc
	v_cndmask_b32_e32 v37, 0, v37, vcc
	v_cmp_lt_i32_e32 vcc, 26, v134
	v_mul_f32_e32 v47, v47, v132
	v_cndmask_b32_e64 v47, 1.0, v47, s[0:1]
	v_cndmask_b32_e32 v46, 1.0, v46, vcc
	v_mul_f32_e32 v34, v34, v45
	v_mul_f32_e32 v134, v46, v47
	v_mul_f32_e32 v134, v34, v134
	v_mov_b32_e32 v148, v134
	v_mov_b32_e32 v240, v134
	s_nop 1
	v_permlane32_swap_b32_e32 v148, v240
	v_cndmask_b32_e64 v148, v148, v240, s[2:3]
	v_mul_f32_e32 v34, v135, v130
	v_cndmask_b32_e32 v149, 0, v34, vcc
	v_mul_f32_e32 v34, v135, v132
	v_cndmask_b32_e64 v34, 0, v34, s[0:1]
	s_waitcnt lgkmcnt(0)
; __device__ __forceinline__ void sb_unit(const Frame& F, int b, int hd, int qi, int dry) {
;     ...
;             float run = C;
;             if (!meta && key0 + 96 < tqw + 31) SB_HALF(96);
;             if (!meta && key0 + 64 < tqw + 31 && __any(run >= SB_DEAD)) SB_HALF(64);
;             if (!meta && key0 + 32 < tqw + 31 && __any(run >= SB_DEAD)) SB_HALF(32);
	v_cndmask_b32_e64 v130, 1.0, v148, s[2:3]
	v_mul_f32_e32 v135, v34, v130
	v_mul_f32_e32 v34, v36, v145
	v_mul_f32_e32 v36, v43, v42
	v_mul_f32_e32 v36, v34, v36
	v_mul_f32_e32 v32, v32, v38
	v_mul_f32_e32 v34, v142, v39
	v_mov_b32_e32 v150, v36
	v_mov_b32_e32 v240, v36
	s_nop 1
	v_permlane32_swap_b32_e32 v150, v240
	v_cndmask_b32_e64 v150, v150, v240, s[2:3]
	v_mul_f32_e32 v34, v32, v34
	v_mul_f32_e32 v47, v47, v130
	v_mov_b32_e32 v130, v34
	v_mov_b32_e32 v240, v34
	s_nop 1
	v_permlane32_swap_b32_e32 v130, v240
	v_cndmask_b32_e64 v130, v130, v240, s[2:3]
	v_mul_f32_e32 v46, v46, v47
	v_mul_f32_e32 v32, v134, v148
	s_waitcnt lgkmcnt(1)
	v_mul_f32_e32 v132, v36, v150
	v_mul_f32_e32 v45, v45, v46
	v_mul_f32_e32 v46, v37, v46
	s_waitcnt lgkmcnt(0)
	v_cndmask_b32_e64 v134, 1.0, v130, s[2:3]
	v_pk_mul_f32 v[36:37], v[32:33], v[132:133]
	v_pk_mul_f32 v[34:35], v[34:35], v[130:131]
	v_mul_f32_e32 v132, v36, v134
	v_mul_f32_e32 v134, v39, v132
	v_mul_f32_e32 v142, v142, v134
	v_mul_f32_e32 v148, v38, v142
	v_pk_mul_f32 v[38:39], v[34:35], v[36:37]
	v_mov_b32_e32 v130, v39
	v_mov_b32_e32 v240, v39
	s_nop 1
	v_permlane32_swap_b32_e32 v130, v240
	v_cndmask_b32_e64 v130, v130, v240, s[2:3]
	v_mul_f32_e32 v37, v40, v132
	v_mul_f32_e32 v40, v143, v134
	v_mul_f32_e32 v36, v141, v142
	v_mul_f32_e32 v132, v140, v148
	s_waitcnt lgkmcnt(0)
	v_cndmask_b32_e64 v34, 1.0, v130, s[2:3]
	v_mul_f32_e32 v34, v38, v34
	v_mul_f32_e32 v35, v133, v34
	v_mul_f32_e32 v33, v33, v35
	v_mul_f32_e32 v131, v131, v33
	v_mul_f32_e32 v133, v136, v34
	v_mul_f32_e32 v35, v139, v35
	v_mul_f32_e32 v33, v137, v33
	v_mul_f32_e32 v34, v138, v131
	v_cvt_pk_bf16_f32 v34, v34, v33
	v_cvt_pk_bf16_f32 v35, v35, v133
	v_cvt_pk_bf16_f32 v36, v132, v36
	v_cvt_pk_bf16_f32 v37, v40, v37
	v_cndmask_b32_e64 v33, 1.0, v150, s[2:3]
	v_mul_f32_e32 v32, v32, v33
	v_mfma_f32_32x32x16_bf16 v[0:15], v[92:95], v[34:37], v[0:15]
	v_mul_f32_e32 v33, v42, v32
	v_mul_f32_e32 v42, v43, v33
	v_mul_f32_e32 v43, v145, v42
	v_mul_f32_e32 v47, v149, v47
	v_mul_f32_e32 v40, v44, v45
	v_mul_f32_e32 v44, v147, v32
	v_mul_f32_e32 v33, v146, v33
	v_mfma_f32_32x32x16_bf16 v[16:31], v[88:91], v[34:37], v[16:31]
	v_mul_f32_e32 v32, v41, v42
	v_mul_f32_e32 v34, v144, v43
	v_cvt_pk_bf16_f32 v32, v34, v32
	v_cvt_pk_bf16_f32 v33, v33, v44
	v_cvt_pk_bf16_f32 v34, v40, v46
	v_cvt_pk_bf16_f32 v35, v47, v135
	v_mul_f32_e32 v36, v39, v130
	v_mul_f32_e32 v36, v38, v36
	v_mfma_f32_32x32x16_bf16 v[0:15], v[84:87], v[32:35], v[0:15]
	v_log_f32_e32 v36, v36
	s_nop 0
	v_add_f32_e32 v126, v126, v36
	v_mfma_f32_32x32x16_bf16 v[16:31], v[80:83], v[32:35], v[16:31]
.LBB0_364:
	s_or_b32 s0, s34, 33
	s_cmp_ge_i32 s0, s25
	s_cselect_b64 s[0:1], -1, 0
	s_or_b64 s[0:1], s[18:19], s[0:1]
	s_and_b64 vcc, exec, s[0:1]
	s_cbranch_vccnz .LBB0_367
	v_cmp_le_f32_e32 vcc, s22, v126
	s_cbranch_vccz .LBB0_367
	ds_read_b128 v[32:35], v129 offset:9216
	ds_read_b128 v[80:83], v129 offset:9248
	v_exp_f32_e32 v135, v126
	v_sub_u32_e32 v134, v124, v127
	v_cmp_lt_i32_e32 vcc, 0, v134
	s_waitcnt lgkmcnt(1)
	v_mfma_f32_32x32x16_bf16 v[32:47], v[32:35], v[48:51], 0
	v_cmp_lt_i32_e64 s[0:1], 27, v134
	s_waitcnt lgkmcnt(0)
	v_mfma_f32_32x32x16_bf16 v[32:47], v[80:83], v[52:55], v[32:47]
	ds_read_b128 v[80:83], v129 offset:9280
	ds_read_b128 v[130:133], v129 offset:9312
	s_waitcnt lgkmcnt(1)
	v_mfma_f32_32x32x16_bf16 v[32:47], v[80:83], v[56:59], v[32:47]
	ds_read_b64_tr_b16 v[92:93], v128 offset:49152
	ds_read_b64_tr_b16 v[94:95], v128 offset:50688
	ds_read_b64_tr_b16 v[90:91], v128 offset:50752
	ds_read_b64_tr_b16 v[88:89], v128 offset:49216
	ds_read_b64_tr_b16 v[84:85], v128 offset:52224
	ds_read_b64_tr_b16 v[86:87], v128 offset:53760
	ds_read_b64_tr_b16 v[82:83], v128 offset:53824
	ds_read_b64_tr_b16 v[80:81], v128 offset:52288
	s_waitcnt lgkmcnt(8)
	v_mfma_f32_32x32x16_bf16 v[32:47], v[130:133], v[60:63], v[32:47]
	s_nop 11
	v_max_f32_e64 v32, -v32, -v32
	v_max_f32_e64 v33, -v33, -v33
	v_min_f32_e32 v32, 0x42fc0000, v32
	v_max_f32_e64 v34, -v34, -v34
	v_min_f32_e32 v33, 0x42fc0000, v33
	v_exp_f32_e32 v32, v32
	v_min_f32_e32 v34, 0x42fc0000, v34
	v_exp_f32_e32 v33, v33
	v_max_f32_e64 v35, -v35, -v35
	v_exp_f32_e32 v34, v34
	v_min_f32_e32 v35, 0x42fc0000, v35
	v_exp_f32_e32 v130, v35
	v_add_f32_e32 v35, 1.0, v32
	v_add_f32_e32 v131, 1.0, v33
	v_rcp_f32_e32 v35, v35
	v_max_f32_e64 v36, -v36, -v36
	v_add_f32_e32 v132, 1.0, v34
	v_rcp_f32_e32 v131, v131
	v_min_f32_e32 v36, 0x42fc0000, v36
	v_rcp_f32_e32 v132, v132
	v_exp_f32_e32 v36, v36
	v_add_f32_e32 v133, 1.0, v130
	v_rcp_f32_e32 v136, v133
	v_mul_f32_e32 v32, v32, v35
	v_mul_f32_e32 v133, v135, v35
	v_mul_f32_e32 v33, v33, v131
	v_mul_f32_e32 v137, v135, v131
	v_cndmask_b32_e32 v35, 1.0, v32, vcc
	v_cndmask_b32_e32 v138, 0, v133, vcc
	v_cmp_lt_i32_e32 vcc, 1, v134
	v_mul_f32_e32 v34, v34, v132
	v_mul_f32_e32 v32, v135, v132
	v_cndmask_b32_e32 v131, 1.0, v33, vcc
	v_cndmask_b32_e32 v137, 0, v137, vcc
	v_cmp_lt_i32_e32 vcc, 2, v134
	v_max_f32_e64 v39, -v39, -v39
	v_min_f32_e32 v39, 0x42fc0000, v39
	v_cndmask_b32_e32 v33, 1.0, v34, vcc
	v_add_f32_e32 v34, 1.0, v36
	v_rcp_f32_e32 v34, v34
	v_cndmask_b32_e32 v139, 0, v32, vcc
	v_mul_f32_e32 v32, v130, v136
	v_cmp_lt_i32_e32 vcc, 3, v134
	v_exp_f32_e32 v39, v39
	v_max_f32_e64 v42, -v42, -v42
	v_cndmask_b32_e32 v133, 1.0, v32, vcc
	v_mul_f32_e32 v32, v135, v136
	v_cndmask_b32_e32 v136, 0, v32, vcc
	v_mul_f32_e32 v32, v36, v34
	v_max_f32_e64 v36, -v37, -v37
	v_min_f32_e32 v36, 0x42fc0000, v36
	v_exp_f32_e32 v36, v36
	v_cmp_lt_i32_e32 vcc, 8, v134
	v_mul_f32_e32 v34, v135, v34
	v_max_f32_e64 v37, -v38, -v38
	v_cndmask_b32_e32 v140, 0, v34, vcc
	v_add_f32_e32 v34, 1.0, v36
	v_rcp_f32_e32 v34, v34
	v_min_f32_e32 v37, 0x42fc0000, v37
	v_exp_f32_e32 v37, v37
	v_cndmask_b32_e32 v32, 1.0, v32, vcc
	v_mul_f32_e32 v36, v36, v34
	v_cmp_lt_i32_e32 vcc, 9, v134
	v_mul_f32_e32 v34, v135, v34
	v_min_f32_e32 v42, 0x42fc0000, v42
	v_cndmask_b32_e32 v38, 1.0, v36, vcc
	v_add_f32_e32 v36, 1.0, v37
	v_rcp_f32_e32 v36, v36
	v_cndmask_b32_e32 v141, 0, v34, vcc
	v_cmp_lt_i32_e32 vcc, 10, v134
	v_exp_f32_e32 v42, v42
	v_mul_f32_e32 v34, v37, v36
	v_add_f32_e32 v37, 1.0, v39
	v_rcp_f32_e32 v37, v37
	v_cndmask_b32_e32 v142, 1.0, v34, vcc
	v_mul_f32_e32 v34, v135, v36
	v_cndmask_b32_e32 v143, 0, v34, vcc
	v_mul_f32_e32 v34, v39, v37
	v_max_f32_e64 v36, -v40, -v40
	v_cmp_lt_i32_e32 vcc, 11, v134
	v_min_f32_e32 v36, 0x42fc0000, v36
	v_exp_f32_e32 v36, v36
	v_cndmask_b32_e32 v39, 1.0, v34, vcc
	v_mul_f32_e32 v34, v135, v37
	v_max_f32_e64 v37, -v41, -v41
	v_min_f32_e32 v37, 0x42fc0000, v37
	v_exp_f32_e32 v37, v37
	v_cndmask_b32_e32 v40, 0, v34, vcc
	v_add_f32_e32 v34, 1.0, v36
	v_rcp_f32_e32 v34, v34
	v_add_f32_e32 v41, 1.0, v37
	v_rcp_f32_e32 v41, v41
	v_cmp_lt_i32_e32 vcc, 16, v134
	v_mul_f32_e32 v36, v36, v34
	v_mul_f32_e32 v34, v135, v34
	v_cndmask_b32_e32 v144, 0, v34, vcc
	v_mul_f32_e32 v34, v37, v41
	v_add_f32_e32 v37, 1.0, v42
	v_rcp_f32_e32 v37, v37
	v_cndmask_b32_e32 v36, 1.0, v36, vcc
	v_cmp_lt_i32_e32 vcc, 17, v134
	v_max_f32_e64 v45, -v45, -v45
	v_min_f32_e32 v45, 0x42fc0000, v45
	v_cndmask_b32_e32 v145, 1.0, v34, vcc
	v_mul_f32_e32 v34, v135, v41
	v_cndmask_b32_e32 v41, 0, v34, vcc
	v_mul_f32_e32 v34, v42, v37
	v_max_f32_e64 v42, -v43, -v43
	v_cmp_lt_i32_e32 vcc, 18, v134
	v_min_f32_e32 v42, 0x42fc0000, v42
	v_exp_f32_e32 v42, v42
	v_cndmask_b32_e32 v43, 1.0, v34, vcc
	v_mul_f32_e32 v34, v135, v37
	v_max_f32_e64 v37, -v44, -v44
	v_min_f32_e32 v37, 0x42fc0000, v37
	v_exp_f32_e32 v37, v37
	v_cndmask_b32_e32 v146, 0, v34, vcc
	v_add_f32_e32 v34, 1.0, v42
	v_rcp_f32_e32 v34, v34
	v_add_f32_e32 v44, 1.0, v37
	v_max_f32_e64 v46, -v46, -v46
	v_max_f32_e64 v47, -v47, -v47
	v_rcp_f32_e32 v44, v44
	v_exp_f32_e32 v45, v45
	v_min_f32_e32 v46, 0x42fc0000, v46
	v_min_f32_e32 v47, 0x42fc0000, v47
	v_exp_f32_e32 v46, v46
	v_exp_f32_e32 v47, v47
	v_mul_f32_e32 v42, v42, v34
	v_cmp_lt_i32_e32 vcc, 19, v134
	v_mul_f32_e32 v34, v135, v34
	v_add_f32_e32 v130, 1.0, v46
	v_cndmask_b32_e32 v147, 0, v34, vcc
	v_mul_f32_e32 v34, v37, v44
	v_add_f32_e32 v37, 1.0, v45
	v_rcp_f32_e32 v37, v37
	v_add_f32_e32 v132, 1.0, v47
	v_rcp_f32_e32 v130, v130
	v_rcp_f32_e32 v132, v132
	v_cndmask_b32_e32 v42, 1.0, v42, vcc
	v_cmp_lt_i32_e32 vcc, 24, v134
	v_mul_f32_e32 v44, v135, v44
	v_mul_f32_e32 v45, v45, v37
	v_cndmask_b32_e32 v34, 1.0, v34, vcc
	v_cndmask_b32_e32 v44, 0, v44, vcc
	v_cmp_lt_i32_e32 vcc, 25, v134
	v_mul_f32_e32 v37, v135, v37
	v_mul_f32_e32 v46, v46, v130
	v_cndmask_b32_e32 v45, 1.0, v45, vcc
	v_cndmask_b32_e32 v37, 0, v37, vcc
	v_cmp_lt_i32_e32 vcc, 26, v134
	v_mul_f32_e32 v47, v47, v132
	v_cndmask_b32_e64 v47, 1.0, v47, s[0:1]
	v_cndmask_b32_e32 v46, 1.0, v46, vcc
	v_mul_f32_e32 v34, v34, v45
	v_mul_f32_e32 v134, v46, v47
	v_mul_f32_e32 v134, v34, v134
	v_mov_b32_e32 v148, v134
	v_mov_b32_e32 v240, v134
	s_nop 1
	v_permlane32_swap_b32_e32 v148, v240
	v_cndmask_b32_e64 v148, v148, v240, s[2:3]
	v_mul_f32_e32 v34, v135, v130
	v_cndmask_b32_e32 v149, 0, v34, vcc
	v_mul_f32_e32 v34, v135, v132
	v_cndmask_b32_e64 v34, 0, v34, s[0:1]
	s_waitcnt lgkmcnt(0)
	v_cndmask_b32_e64 v130, 1.0, v148, s[2:3]
	v_mul_f32_e32 v135, v34, v130
	v_mul_f32_e32 v34, v36, v145
	v_mul_f32_e32 v36, v43, v42
	v_mul_f32_e32 v36, v34, v36
	v_mul_f32_e32 v32, v32, v38
	v_mul_f32_e32 v34, v142, v39
	v_mov_b32_e32 v150, v36
	v_mov_b32_e32 v240, v36
	s_nop 1
	v_permlane32_swap_b32_e32 v150, v240
	v_cndmask_b32_e64 v150, v150, v240, s[2:3]
	v_mul_f32_e32 v34, v32, v34
	v_mul_f32_e32 v47, v47, v130
	v_mov_b32_e32 v130, v34
	v_mov_b32_e32 v240, v34
	s_nop 1
	v_permlane32_swap_b32_e32 v130, v240
	v_cndmask_b32_e64 v130, v130, v240, s[2:3]
	v_mul_f32_e32 v46, v46, v47
	v_mul_f32_e32 v32, v134, v148
	s_waitcnt lgkmcnt(1)
	v_mul_f32_e32 v132, v36, v150
	v_mul_f32_e32 v45, v45, v46
	v_mul_f32_e32 v46, v37, v46
	s_waitcnt lgkmcnt(0)
	v_cndmask_b32_e64 v134, 1.0, v130, s[2:3]
	v_pk_mul_f32 v[36:37], v[32:33], v[132:133]
	v_pk_mul_f32 v[34:35], v[34:35], v[130:131]
	v_mul_f32_e32 v132, v36, v134
	v_mul_f32_e32 v134, v39, v132
	v_mul_f32_e32 v142, v142, v134
	v_mul_f32_e32 v148, v38, v142
	v_pk_mul_f32 v[38:39], v[34:35], v[36:37]
	v_mov_b32_e32 v130, v39
	v_mov_b32_e32 v240, v39
	s_nop 1
	v_permlane32_swap_b32_e32 v130, v240
	v_cndmask_b32_e64 v130, v130, v240, s[2:3]
	v_mul_f32_e32 v37, v40, v132
	v_mul_f32_e32 v40, v143, v134
	v_mul_f32_e32 v36, v141, v142
	v_mul_f32_e32 v132, v140, v148
	s_waitcnt lgkmcnt(0)
	v_cndmask_b32_e64 v34, 1.0, v130, s[2:3]
	v_mul_f32_e32 v34, v38, v34
	v_mul_f32_e32 v35, v133, v34
	v_mul_f32_e32 v33, v33, v35
	v_mul_f32_e32 v131, v131, v33
	v_mul_f32_e32 v133, v136, v34
	v_mul_f32_e32 v35, v139, v35
	v_mul_f32_e32 v33, v137, v33
	v_mul_f32_e32 v34, v138, v131
	v_cvt_pk_bf16_f32 v34, v34, v33
	v_cvt_pk_bf16_f32 v35, v35, v133
	v_cvt_pk_bf16_f32 v36, v132, v36
	v_cvt_pk_bf16_f32 v37, v40, v37
	v_cndmask_b32_e64 v33, 1.0, v150, s[2:3]
	v_mul_f32_e32 v32, v32, v33
	v_mfma_f32_32x32x16_bf16 v[0:15], v[92:95], v[34:37], v[0:15]
	v_mul_f32_e32 v33, v42, v32
	v_mul_f32_e32 v42, v43, v33
	v_mul_f32_e32 v43, v145, v42
	v_mul_f32_e32 v47, v149, v47
	v_mul_f32_e32 v40, v44, v45
	v_mul_f32_e32 v44, v147, v32
	v_mul_f32_e32 v33, v146, v33
	v_mfma_f32_32x32x16_bf16 v[16:31], v[88:91], v[34:37], v[16:31]
	v_mul_f32_e32 v32, v41, v42
	v_mul_f32_e32 v34, v144, v43
	v_cvt_pk_bf16_f32 v32, v34, v32
	v_cvt_pk_bf16_f32 v33, v33, v44
	v_cvt_pk_bf16_f32 v34, v40, v46
	v_cvt_pk_bf16_f32 v35, v47, v135
	v_mul_f32_e32 v36, v39, v130
	v_mul_f32_e32 v36, v38, v36
	v_mfma_f32_32x32x16_bf16 v[0:15], v[84:87], v[32:35], v[0:15]
	v_log_f32_e32 v36, v36
	s_nop 0
	v_add_f32_e32 v126, v126, v36
	v_mfma_f32_32x32x16_bf16 v[16:31], v[80:83], v[32:35], v[16:31]
; __device__ __forceinline__ void sb_unit(const Frame& F, int b, int hd, int qi, int dry) {
;     ...
;             float run = C;
;             if (!meta && key0 + 96 < tqw + 31) SB_HALF(96);
;             if (!meta && key0 + 64 < tqw + 31 && __any(run >= SB_DEAD)) SB_HALF(64);
;             if (!meta && key0 + 32 < tqw + 31 && __any(run >= SB_DEAD)) SB_HALF(32);
.LBB0_367:
	s_or_b32 s0, s34, 1
	s_cmp_ge_i32 s0, s25
	s_cselect_b64 s[0:1], -1, 0
	s_or_b64 s[0:1], s[18:19], s[0:1]
	s_and_b64 vcc, exec, s[0:1]
	s_cbranch_vccnz .LBB0_370
	v_cmp_le_f32_e32 vcc, s22, v126
	s_cbranch_vccz .LBB0_370
	ds_read_b128 v[32:35], v129 offset:4608
	ds_read_b128 v[80:83], v129 offset:4640
	v_exp_f32_e32 v135, v126
	v_sub_u32_e32 v134, v125, v127
	v_cmp_lt_i32_e32 vcc, 0, v134
	s_waitcnt lgkmcnt(1)
	v_mfma_f32_32x32x16_bf16 v[32:47], v[32:35], v[48:51], 0
	v_cmp_lt_i32_e64 s[0:1], 27, v134
	s_waitcnt lgkmcnt(0)
	v_mfma_f32_32x32x16_bf16 v[32:47], v[80:83], v[52:55], v[32:47]
	ds_read_b128 v[80:83], v129 offset:4672
	ds_read_b128 v[130:133], v129 offset:4704
	s_waitcnt lgkmcnt(1)
	v_mfma_f32_32x32x16_bf16 v[32:47], v[80:83], v[56:59], v[32:47]
	ds_read_b64_tr_b16 v[92:93], v128 offset:43008
	ds_read_b64_tr_b16 v[94:95], v128 offset:44544
	ds_read_b64_tr_b16 v[90:91], v128 offset:44608
	ds_read_b64_tr_b16 v[88:89], v128 offset:43072
	ds_read_b64_tr_b16 v[84:85], v128 offset:46080
	ds_read_b64_tr_b16 v[86:87], v128 offset:47616
	ds_read_b64_tr_b16 v[82:83], v128 offset:47680
	ds_read_b64_tr_b16 v[80:81], v128 offset:46144
	s_waitcnt lgkmcnt(8)
	v_mfma_f32_32x32x16_bf16 v[32:47], v[130:133], v[60:63], v[32:47]
	s_nop 11
	v_max_f32_e64 v32, -v32, -v32
	v_max_f32_e64 v33, -v33, -v33
	v_min_f32_e32 v32, 0x42fc0000, v32
	v_max_f32_e64 v34, -v34, -v34
	v_min_f32_e32 v33, 0x42fc0000, v33
	v_exp_f32_e32 v32, v32
	v_min_f32_e32 v34, 0x42fc0000, v34
	v_exp_f32_e32 v33, v33
	v_max_f32_e64 v35, -v35, -v35
	v_exp_f32_e32 v34, v34
	v_min_f32_e32 v35, 0x42fc0000, v35
	v_exp_f32_e32 v130, v35
	v_add_f32_e32 v35, 1.0, v32
	v_add_f32_e32 v131, 1.0, v33
	v_rcp_f32_e32 v35, v35
	v_max_f32_e64 v36, -v36, -v36
	v_add_f32_e32 v132, 1.0, v34
	v_rcp_f32_e32 v131, v131
	v_min_f32_e32 v36, 0x42fc0000, v36
	v_rcp_f32_e32 v132, v132
	v_exp_f32_e32 v36, v36
	v_add_f32_e32 v133, 1.0, v130
	v_rcp_f32_e32 v136, v133
	v_mul_f32_e32 v32, v32, v35
	v_mul_f32_e32 v133, v135, v35
	v_mul_f32_e32 v33, v33, v131
	v_mul_f32_e32 v137, v135, v131
	v_cndmask_b32_e32 v35, 1.0, v32, vcc
	v_cndmask_b32_e32 v138, 0, v133, vcc
	v_cmp_lt_i32_e32 vcc, 1, v134
	v_mul_f32_e32 v34, v34, v132
	v_mul_f32_e32 v32, v135, v132
	v_cndmask_b32_e32 v131, 1.0, v33, vcc
	v_cndmask_b32_e32 v137, 0, v137, vcc
	v_cmp_lt_i32_e32 vcc, 2, v134
	v_max_f32_e64 v39, -v39, -v39
	v_min_f32_e32 v39, 0x42fc0000, v39
	v_cndmask_b32_e32 v33, 1.0, v34, vcc
	v_add_f32_e32 v34, 1.0, v36
	v_rcp_f32_e32 v34, v34
	v_cndmask_b32_e32 v139, 0, v32, vcc
	v_mul_f32_e32 v32, v130, v136
	v_cmp_lt_i32_e32 vcc, 3, v134
	v_exp_f32_e32 v39, v39
	v_max_f32_e64 v42, -v42, -v42
	v_cndmask_b32_e32 v133, 1.0, v32, vcc
	v_mul_f32_e32 v32, v135, v136
	v_cndmask_b32_e32 v136, 0, v32, vcc
	v_mul_f32_e32 v32, v36, v34
	v_max_f32_e64 v36, -v37, -v37
	v_min_f32_e32 v36, 0x42fc0000, v36
	v_exp_f32_e32 v36, v36
	v_cmp_lt_i32_e32 vcc, 8, v134
	v_mul_f32_e32 v34, v135, v34
	v_max_f32_e64 v37, -v38, -v38
	v_cndmask_b32_e32 v140, 0, v34, vcc
	v_add_f32_e32 v34, 1.0, v36
	v_rcp_f32_e32 v34, v34
	v_min_f32_e32 v37, 0x42fc0000, v37
	v_exp_f32_e32 v37, v37
	v_cndmask_b32_e32 v32, 1.0, v32, vcc
	v_mul_f32_e32 v36, v36, v34
	v_cmp_lt_i32_e32 vcc, 9, v134
	v_mul_f32_e32 v34, v135, v34
	v_min_f32_e32 v42, 0x42fc0000, v42
	v_cndmask_b32_e32 v38, 1.0, v36, vcc
	v_add_f32_e32 v36, 1.0, v37
	v_rcp_f32_e32 v36, v36
	v_cndmask_b32_e32 v141, 0, v34, vcc
	v_cmp_lt_i32_e32 vcc, 10, v134
	v_exp_f32_e32 v42, v42
	v_mul_f32_e32 v34, v37, v36
	v_add_f32_e32 v37, 1.0, v39
	v_rcp_f32_e32 v37, v37
	v_cndmask_b32_e32 v142, 1.0, v34, vcc
	v_mul_f32_e32 v34, v135, v36
	v_cndmask_b32_e32 v143, 0, v34, vcc
	v_mul_f32_e32 v34, v39, v37
	v_max_f32_e64 v36, -v40, -v40
	v_cmp_lt_i32_e32 vcc, 11, v134
	v_min_f32_e32 v36, 0x42fc0000, v36
	v_exp_f32_e32 v36, v36
	v_cndmask_b32_e32 v39, 1.0, v34, vcc
	v_mul_f32_e32 v34, v135, v37
	v_max_f32_e64 v37, -v41, -v41
	v_min_f32_e32 v37, 0x42fc0000, v37
	v_exp_f32_e32 v37, v37
	v_cndmask_b32_e32 v40, 0, v34, vcc
	v_add_f32_e32 v34, 1.0, v36
	v_rcp_f32_e32 v34, v34
	v_add_f32_e32 v41, 1.0, v37
	v_rcp_f32_e32 v41, v41
	v_cmp_lt_i32_e32 vcc, 16, v134
	v_mul_f32_e32 v36, v36, v34
	v_mul_f32_e32 v34, v135, v34
	v_cndmask_b32_e32 v144, 0, v34, vcc
	v_mul_f32_e32 v34, v37, v41
	v_add_f32_e32 v37, 1.0, v42
	v_rcp_f32_e32 v37, v37
	v_cndmask_b32_e32 v36, 1.0, v36, vcc
	v_cmp_lt_i32_e32 vcc, 17, v134
	v_max_f32_e64 v45, -v45, -v45
	v_min_f32_e32 v45, 0x42fc0000, v45
	v_cndmask_b32_e32 v145, 1.0, v34, vcc
	v_mul_f32_e32 v34, v135, v41
	v_cndmask_b32_e32 v41, 0, v34, vcc
	v_mul_f32_e32 v34, v42, v37
	v_max_f32_e64 v42, -v43, -v43
	v_cmp_lt_i32_e32 vcc, 18, v134
	v_min_f32_e32 v42, 0x42fc0000, v42
	v_exp_f32_e32 v42, v42
	v_cndmask_b32_e32 v43, 1.0, v34, vcc
	v_mul_f32_e32 v34, v135, v37
	v_max_f32_e64 v37, -v44, -v44
	v_min_f32_e32 v37, 0x42fc0000, v37
	v_exp_f32_e32 v37, v37
	v_cndmask_b32_e32 v146, 0, v34, vcc
	v_add_f32_e32 v34, 1.0, v42
	v_rcp_f32_e32 v34, v34
	v_add_f32_e32 v44, 1.0, v37
	v_max_f32_e64 v46, -v46, -v46
	v_max_f32_e64 v47, -v47, -v47
	v_rcp_f32_e32 v44, v44
	v_exp_f32_e32 v45, v45
	v_min_f32_e32 v46, 0x42fc0000, v46
	v_min_f32_e32 v47, 0x42fc0000, v47
	v_exp_f32_e32 v46, v46
	v_exp_f32_e32 v47, v47
	v_mul_f32_e32 v42, v42, v34
	v_cmp_lt_i32_e32 vcc, 19, v134
	v_mul_f32_e32 v34, v135, v34
	v_add_f32_e32 v130, 1.0, v46
	v_cndmask_b32_e32 v147, 0, v34, vcc
	v_mul_f32_e32 v34, v37, v44
	v_add_f32_e32 v37, 1.0, v45
	v_rcp_f32_e32 v37, v37
	v_add_f32_e32 v132, 1.0, v47
	v_rcp_f32_e32 v130, v130
	v_rcp_f32_e32 v132, v132
	v_cndmask_b32_e32 v42, 1.0, v42, vcc
	v_cmp_lt_i32_e32 vcc, 24, v134
	v_mul_f32_e32 v44, v135, v44
	v_mul_f32_e32 v45, v45, v37
	v_cndmask_b32_e32 v34, 1.0, v34, vcc
	v_cndmask_b32_e32 v44, 0, v44, vcc
	v_cmp_lt_i32_e32 vcc, 25, v134
	v_mul_f32_e32 v37, v135, v37
	v_mul_f32_e32 v46, v46, v130
	v_cndmask_b32_e32 v45, 1.0, v45, vcc
	v_cndmask_b32_e32 v37, 0, v37, vcc
	v_cmp_lt_i32_e32 vcc, 26, v134
	v_mul_f32_e32 v47, v47, v132
	v_cndmask_b32_e64 v47, 1.0, v47, s[0:1]
	v_cndmask_b32_e32 v46, 1.0, v46, vcc
	v_mul_f32_e32 v34, v34, v45
	v_mul_f32_e32 v134, v46, v47
	v_mul_f32_e32 v134, v34, v134
	v_mov_b32_e32 v148, v134
	v_mov_b32_e32 v240, v134
	s_nop 1
	v_permlane32_swap_b32_e32 v148, v240
	v_cndmask_b32_e64 v148, v148, v240, s[2:3]
	v_mul_f32_e32 v34, v135, v130
	v_cndmask_b32_e32 v149, 0, v34, vcc
	v_mul_f32_e32 v34, v135, v132
	v_cndmask_b32_e64 v34, 0, v34, s[0:1]
	s_waitcnt lgkmcnt(0)
; __device__ __forceinline__ void sb_unit(const Frame& F, int b, int hd, int qi, int dry) {
;     ...
;             float run = C;
;             if (!meta && key0 + 96 < tqw + 31) SB_HALF(96);
;             if (!meta && key0 + 64 < tqw + 31 && __any(run >= SB_DEAD)) SB_HALF(64);
;             if (!meta && key0 + 32 < tqw + 31 && __any(run >= SB_DEAD)) SB_HALF(32);
;             if (__any(run >= SB_DEAD)) SB_HALF(0);
	v_cndmask_b32_e64 v130, 1.0, v148, s[2:3]
	v_mul_f32_e32 v135, v34, v130
	v_mul_f32_e32 v34, v36, v145
	v_mul_f32_e32 v36, v43, v42
	v_mul_f32_e32 v36, v34, v36
	v_mul_f32_e32 v32, v32, v38
	v_mul_f32_e32 v34, v142, v39
	v_mov_b32_e32 v150, v36
	v_mov_b32_e32 v240, v36
	s_nop 1
	v_permlane32_swap_b32_e32 v150, v240
	v_cndmask_b32_e64 v150, v150, v240, s[2:3]
	v_mul_f32_e32 v34, v32, v34
	v_mul_f32_e32 v47, v47, v130
	v_mov_b32_e32 v130, v34
	v_mov_b32_e32 v240, v34
	s_nop 1
	v_permlane32_swap_b32_e32 v130, v240
	v_cndmask_b32_e64 v130, v130, v240, s[2:3]
	v_mul_f32_e32 v46, v46, v47
	v_mul_f32_e32 v32, v134, v148
	s_waitcnt lgkmcnt(1)
	v_mul_f32_e32 v132, v36, v150
	v_mul_f32_e32 v45, v45, v46
	v_mul_f32_e32 v46, v37, v46
	s_waitcnt lgkmcnt(0)
	v_cndmask_b32_e64 v134, 1.0, v130, s[2:3]
	v_pk_mul_f32 v[36:37], v[32:33], v[132:133]
	v_pk_mul_f32 v[34:35], v[34:35], v[130:131]
	v_mul_f32_e32 v132, v36, v134
	v_mul_f32_e32 v134, v39, v132
	v_mul_f32_e32 v142, v142, v134
	v_mul_f32_e32 v148, v38, v142
	v_pk_mul_f32 v[38:39], v[34:35], v[36:37]
	v_mov_b32_e32 v130, v39
	v_mov_b32_e32 v240, v39
	s_nop 1
	v_permlane32_swap_b32_e32 v130, v240
	v_cndmask_b32_e64 v130, v130, v240, s[2:3]
	v_mul_f32_e32 v37, v40, v132
	v_mul_f32_e32 v40, v143, v134
	v_mul_f32_e32 v36, v141, v142
	v_mul_f32_e32 v132, v140, v148
	s_waitcnt lgkmcnt(0)
	v_cndmask_b32_e64 v34, 1.0, v130, s[2:3]
	v_mul_f32_e32 v34, v38, v34
	v_mul_f32_e32 v35, v133, v34
	v_mul_f32_e32 v33, v33, v35
	v_mul_f32_e32 v131, v131, v33
	v_mul_f32_e32 v133, v136, v34
	v_mul_f32_e32 v35, v139, v35
	v_mul_f32_e32 v33, v137, v33
	v_mul_f32_e32 v34, v138, v131
	v_cvt_pk_bf16_f32 v34, v34, v33
	v_cvt_pk_bf16_f32 v35, v35, v133
	v_cvt_pk_bf16_f32 v36, v132, v36
	v_cvt_pk_bf16_f32 v37, v40, v37
	v_cndmask_b32_e64 v33, 1.0, v150, s[2:3]
	v_mul_f32_e32 v32, v32, v33
	v_mfma_f32_32x32x16_bf16 v[0:15], v[92:95], v[34:37], v[0:15]
	v_mul_f32_e32 v33, v42, v32
	v_mul_f32_e32 v42, v43, v33
	v_mul_f32_e32 v43, v145, v42
	v_mul_f32_e32 v47, v149, v47
	v_mul_f32_e32 v40, v44, v45
	v_mul_f32_e32 v44, v147, v32
	v_mul_f32_e32 v33, v146, v33
	v_mfma_f32_32x32x16_bf16 v[16:31], v[88:91], v[34:37], v[16:31]
	v_mul_f32_e32 v32, v41, v42
	v_mul_f32_e32 v34, v144, v43
	v_cvt_pk_bf16_f32 v32, v34, v32
	v_cvt_pk_bf16_f32 v33, v33, v44
	v_cvt_pk_bf16_f32 v34, v40, v46
	v_cvt_pk_bf16_f32 v35, v47, v135
	v_mul_f32_e32 v36, v39, v130
	v_mul_f32_e32 v36, v38, v36
	v_mfma_f32_32x32x16_bf16 v[0:15], v[84:87], v[32:35], v[0:15]
	v_log_f32_e32 v36, v36
	s_nop 0
	v_add_f32_e32 v126, v126, v36
	v_mfma_f32_32x32x16_bf16 v[16:31], v[80:83], v[32:35], v[16:31]
.LBB0_370:
	v_cmp_le_f32_e32 vcc, s22, v126
	s_cbranch_vccz .LBB0_372
	ds_read_b128 v[32:35], v129
	ds_read_b128 v[80:83], v129 offset:32
	s_waitcnt lgkmcnt(1)
	v_mfma_f32_32x32x16_bf16 v[32:47], v[32:35], v[48:51], 0
	s_waitcnt lgkmcnt(0)
	v_mfma_f32_32x32x16_bf16 v[32:47], v[80:83], v[52:55], v[32:47]
	ds_read_b128 v[80:83], v129 offset:64
	ds_read_b128 v[130:133], v129 offset:96
	v_cndmask_b32_e64 v129, v114, 16, s[18:19]
	v_sub_u32_e32 v127, v129, v127
	v_cmp_lt_i32_e32 vcc, 0, v127
	v_cmp_lt_i32_e64 s[0:1], 27, v127
	s_waitcnt lgkmcnt(1)
	v_mfma_f32_32x32x16_bf16 v[32:47], v[80:83], v[56:59], v[32:47]
	ds_read_b64_tr_b16 v[92:93], v128 offset:36864
	ds_read_b64_tr_b16 v[94:95], v128 offset:38400
	ds_read_b64_tr_b16 v[90:91], v128 offset:38464
	ds_read_b64_tr_b16 v[88:89], v128 offset:36928
	ds_read_b64_tr_b16 v[84:85], v128 offset:39936
	ds_read_b64_tr_b16 v[86:87], v128 offset:41472
	ds_read_b64_tr_b16 v[82:83], v128 offset:41536
	ds_read_b64_tr_b16 v[80:81], v128 offset:40000
	v_exp_f32_e32 v128, v126
	s_waitcnt lgkmcnt(8)
	v_mfma_f32_32x32x16_bf16 v[32:47], v[130:133], v[60:63], v[32:47]
	s_nop 11
	v_max_f32_e64 v32, -v32, -v32
	v_max_f32_e64 v33, -v33, -v33
	v_min_f32_e32 v32, 0x42fc0000, v32
	v_max_f32_e64 v34, -v34, -v34
	v_min_f32_e32 v33, 0x42fc0000, v33
	v_exp_f32_e32 v32, v32
	v_min_f32_e32 v34, 0x42fc0000, v34
	v_exp_f32_e32 v33, v33
	v_max_f32_e64 v35, -v35, -v35
	v_exp_f32_e32 v34, v34
	v_min_f32_e32 v35, 0x42fc0000, v35
	v_exp_f32_e32 v130, v35
	v_add_f32_e32 v35, 1.0, v32
	v_add_f32_e32 v129, 1.0, v33
	v_rcp_f32_e32 v35, v35
	v_add_f32_e32 v131, 1.0, v34
	v_rcp_f32_e32 v129, v129
	v_rcp_f32_e32 v131, v131
	v_add_f32_e32 v132, 1.0, v130
	v_max_f32_e64 v36, -v36, -v36
	v_rcp_f32_e32 v132, v132
	v_mul_f32_e32 v32, v32, v35
	v_mul_f32_e32 v133, v128, v35
	v_min_f32_e32 v36, 0x42fc0000, v36
	v_mul_f32_e32 v33, v33, v129
	v_mul_f32_e32 v134, v128, v129
	v_cndmask_b32_e32 v35, 1.0, v32, vcc
	v_cndmask_b32_e32 v133, 0, v133, vcc
	v_cmp_lt_i32_e32 vcc, 1, v127
	v_mul_f32_e32 v34, v34, v131
	v_exp_f32_e32 v32, v36
	v_cndmask_b32_e32 v129, 1.0, v33, vcc
	v_cndmask_b32_e32 v134, 0, v134, vcc
	v_cmp_lt_i32_e32 vcc, 2, v127
	v_add_f32_e32 v36, 1.0, v32
	v_rcp_f32_e32 v36, v36
	v_cndmask_b32_e32 v33, 1.0, v34, vcc
	v_mul_f32_e32 v34, v128, v131
	v_cndmask_b32_e32 v135, 0, v34, vcc
	v_mul_f32_e32 v34, v130, v132
	v_cmp_lt_i32_e32 vcc, 3, v127
	v_mul_f32_e32 v32, v32, v36
	v_mul_f32_e32 v36, v128, v36
	v_cndmask_b32_e32 v131, 1.0, v34, vcc
	v_mul_f32_e32 v34, v128, v132
	v_cndmask_b32_e32 v132, 0, v34, vcc
	v_max_f32_e64 v34, -v37, -v37
	v_min_f32_e32 v34, 0x42fc0000, v34
	v_exp_f32_e32 v34, v34
	v_cmp_lt_i32_e32 vcc, 8, v127
	v_max_f32_e64 v37, -v38, -v38
	v_min_f32_e32 v37, 0x42fc0000, v37
	v_cndmask_b32_e32 v136, 0, v36, vcc
	v_add_f32_e32 v36, 1.0, v34
	v_rcp_f32_e32 v36, v36
	v_exp_f32_e32 v37, v37
	v_cndmask_b32_e32 v32, 1.0, v32, vcc
	v_cmp_lt_i32_e32 vcc, 9, v127
	v_mul_f32_e32 v34, v34, v36
	v_max_f32_e64 v39, -v39, -v39
	v_cndmask_b32_e32 v38, 1.0, v34, vcc
; __device__ __forceinline__ void sb_unit(const Frame& F, int b, int hd, int qi, int dry) {
;     ...
;             if (__any(run >= SB_DEAD)) SB_HALF(0);
	v_add_f32_e32 v34, 1.0, v37
	v_min_f32_e32 v39, 0x42fc0000, v39
	v_rcp_f32_e32 v34, v34
	v_exp_f32_e32 v39, v39
	v_mul_f32_e32 v36, v128, v36
	v_cndmask_b32_e32 v137, 0, v36, vcc
	v_mul_f32_e32 v36, v37, v34
	v_add_f32_e32 v37, 1.0, v39
	v_rcp_f32_e32 v37, v37
	v_cmp_lt_i32_e32 vcc, 10, v127
	v_mul_f32_e32 v34, v128, v34
	v_max_f32_e64 v42, -v42, -v42
	v_cndmask_b32_e32 v138, 1.0, v36, vcc
	v_cndmask_b32_e32 v139, 0, v34, vcc
	v_mul_f32_e32 v34, v39, v37
	v_max_f32_e64 v36, -v40, -v40
	v_cmp_lt_i32_e32 vcc, 11, v127
	v_min_f32_e32 v36, 0x42fc0000, v36
	v_exp_f32_e32 v36, v36
	v_cndmask_b32_e32 v39, 1.0, v34, vcc
	v_mul_f32_e32 v34, v128, v37
	v_max_f32_e64 v37, -v41, -v41
	v_min_f32_e32 v37, 0x42fc0000, v37
	v_exp_f32_e32 v37, v37
	v_cndmask_b32_e32 v40, 0, v34, vcc
	v_add_f32_e32 v34, 1.0, v36
	v_rcp_f32_e32 v34, v34
	v_add_f32_e32 v41, 1.0, v37
	v_min_f32_e32 v42, 0x42fc0000, v42
	v_rcp_f32_e32 v41, v41
	v_exp_f32_e32 v42, v42
	v_mul_f32_e32 v36, v36, v34
	v_cmp_lt_i32_e32 vcc, 16, v127
	v_mul_f32_e32 v34, v128, v34
	v_max_f32_e64 v45, -v45, -v45
	v_cndmask_b32_e32 v140, 0, v34, vcc
	v_mul_f32_e32 v34, v37, v41
	v_add_f32_e32 v37, 1.0, v42
	v_rcp_f32_e32 v37, v37
	v_cndmask_b32_e32 v36, 1.0, v36, vcc
	v_cmp_lt_i32_e32 vcc, 17, v127
	v_min_f32_e32 v45, 0x42fc0000, v45
	v_max_f32_e64 v46, -v46, -v46
	v_cndmask_b32_e32 v141, 1.0, v34, vcc
	v_mul_f32_e32 v34, v128, v41
	v_cndmask_b32_e32 v41, 0, v34, vcc
	v_mul_f32_e32 v34, v42, v37
	v_max_f32_e64 v42, -v43, -v43
	v_cmp_lt_i32_e32 vcc, 18, v127
	v_min_f32_e32 v42, 0x42fc0000, v42
	v_exp_f32_e32 v42, v42
	v_cndmask_b32_e32 v43, 1.0, v34, vcc
	v_mul_f32_e32 v34, v128, v37
	v_max_f32_e64 v37, -v44, -v44
	v_min_f32_e32 v37, 0x42fc0000, v37
	v_exp_f32_e32 v37, v37
	v_cndmask_b32_e32 v142, 0, v34, vcc
	v_add_f32_e32 v34, 1.0, v42
	v_rcp_f32_e32 v34, v34
	v_add_f32_e32 v44, 1.0, v37
	v_max_f32_e64 v47, -v47, -v47
	v_rcp_f32_e32 v44, v44
	v_exp_f32_e32 v45, v45
	v_min_f32_e32 v46, 0x42fc0000, v46
	v_min_f32_e32 v47, 0x42fc0000, v47
	v_exp_f32_e32 v46, v46
	v_exp_f32_e32 v47, v47
	v_mul_f32_e32 v42, v42, v34
	v_cmp_lt_i32_e32 vcc, 19, v127
	v_mul_f32_e32 v34, v128, v34
	v_add_f32_e32 v130, 1.0, v46
	v_cndmask_b32_e32 v143, 0, v34, vcc
	v_mul_f32_e32 v34, v37, v44
	v_add_f32_e32 v37, 1.0, v45
	v_rcp_f32_e32 v37, v37
	v_add_f32_e32 v144, 1.0, v47
	v_rcp_f32_e32 v130, v130
	v_rcp_f32_e32 v144, v144
	v_cndmask_b32_e32 v42, 1.0, v42, vcc
	v_cmp_lt_i32_e32 vcc, 24, v127
	v_mul_f32_e32 v44, v128, v44
	v_mul_f32_e32 v45, v45, v37
	v_cndmask_b32_e32 v34, 1.0, v34, vcc
	v_cndmask_b32_e32 v44, 0, v44, vcc
	v_cmp_lt_i32_e32 vcc, 25, v127
	v_mul_f32_e32 v37, v128, v37
	v_mul_f32_e32 v46, v46, v130
	v_cndmask_b32_e32 v45, 1.0, v45, vcc
	v_cndmask_b32_e32 v37, 0, v37, vcc
	v_cmp_lt_i32_e32 vcc, 26, v127
	v_mul_f32_e32 v47, v47, v144
	v_cndmask_b32_e64 v47, 1.0, v47, s[0:1]
	v_cndmask_b32_e32 v46, 1.0, v46, vcc
	v_mul_f32_e32 v34, v34, v45
	v_mul_f32_e32 v127, v46, v47
	v_mul_f32_e32 v127, v34, v127
	v_mov_b32_e32 v145, v127
	v_mov_b32_e32 v240, v127
	s_nop 1
	v_permlane32_swap_b32_e32 v145, v240
	v_cndmask_b32_e64 v145, v145, v240, s[2:3]
	v_mul_f32_e32 v34, v128, v130
	v_cndmask_b32_e32 v130, 0, v34, vcc
	v_mul_f32_e32 v34, v128, v144
	v_cndmask_b32_e64 v34, 0, v34, s[0:1]
	s_waitcnt lgkmcnt(0)
	v_cndmask_b32_e64 v128, 1.0, v145, s[2:3]
	v_mul_f32_e32 v144, v34, v128
	v_mul_f32_e32 v34, v36, v141
	v_mul_f32_e32 v36, v43, v42
	v_mul_f32_e32 v36, v34, v36
	v_mul_f32_e32 v32, v32, v38
	v_mul_f32_e32 v34, v138, v39
	v_mov_b32_e32 v146, v36
	v_mov_b32_e32 v240, v36
	s_nop 1
	v_permlane32_swap_b32_e32 v146, v240
	v_cndmask_b32_e64 v146, v146, v240, s[2:3]
	v_mul_f32_e32 v34, v32, v34
	v_mul_f32_e32 v47, v47, v128
	v_mov_b32_e32 v128, v34
	v_mov_b32_e32 v240, v34
	s_nop 1
	v_permlane32_swap_b32_e32 v128, v240
	v_cndmask_b32_e64 v128, v128, v240, s[2:3]
	v_mul_f32_e32 v46, v46, v47
	v_mul_f32_e32 v47, v130, v47
	v_mul_f32_e32 v32, v127, v145
	s_waitcnt lgkmcnt(1)
	v_mul_f32_e32 v130, v36, v146
	v_mul_f32_e32 v45, v45, v46
	v_mul_f32_e32 v46, v37, v46
	s_waitcnt lgkmcnt(0)
	v_cndmask_b32_e64 v127, 1.0, v128, s[2:3]
	v_pk_mul_f32 v[36:37], v[32:33], v[130:131]
	v_pk_mul_f32 v[34:35], v[34:35], v[128:129]
	v_mul_f32_e32 v127, v36, v127
	v_mul_f32_e32 v130, v39, v127
	v_mul_f32_e32 v138, v138, v130
	v_mul_f32_e32 v145, v38, v138
	v_pk_mul_f32 v[38:39], v[34:35], v[36:37]
	v_mov_b32_e32 v128, v39
	v_mov_b32_e32 v240, v39
	s_nop 1
	v_permlane32_swap_b32_e32 v128, v240
	v_cndmask_b32_e64 v128, v128, v240, s[2:3]
	v_mul_f32_e32 v37, v40, v127
	v_mul_f32_e32 v40, v139, v130
	v_mul_f32_e32 v36, v137, v138
	v_mul_f32_e32 v127, v136, v145
	s_waitcnt lgkmcnt(0)
	v_cndmask_b32_e64 v34, 1.0, v128, s[2:3]
	v_mul_f32_e32 v34, v38, v34
	v_mul_f32_e32 v35, v131, v34
	v_mul_f32_e32 v33, v33, v35
	v_mul_f32_e32 v129, v129, v33
	v_mul_f32_e32 v130, v132, v34
	v_mul_f32_e32 v35, v135, v35
	v_mul_f32_e32 v33, v134, v33
	v_mul_f32_e32 v34, v133, v129
	v_cvt_pk_bf16_f32 v34, v34, v33
	v_cvt_pk_bf16_f32 v35, v35, v130
	v_cvt_pk_bf16_f32 v36, v127, v36
	v_cvt_pk_bf16_f32 v37, v40, v37
	v_cndmask_b32_e64 v33, 1.0, v146, s[2:3]
	v_mul_f32_e32 v32, v32, v33
	v_mfma_f32_32x32x16_bf16 v[0:15], v[92:95], v[34:37], v[0:15]
	v_mul_f32_e32 v33, v42, v32
	v_mul_f32_e32 v42, v43, v33
	v_mul_f32_e32 v43, v141, v42
	v_mul_f32_e32 v40, v44, v45
	v_mul_f32_e32 v44, v143, v32
	v_mul_f32_e32 v33, v142, v33
	v_mul_f32_e32 v32, v41, v42
	v_mfma_f32_32x32x16_bf16 v[16:31], v[88:91], v[34:37], v[16:31]
	v_mul_f32_e32 v34, v140, v43
	v_cvt_pk_bf16_f32 v32, v34, v32
	v_cvt_pk_bf16_f32 v33, v33, v44
	v_cvt_pk_bf16_f32 v34, v40, v46
	v_cvt_pk_bf16_f32 v35, v47, v144
	v_mul_f32_e32 v36, v39, v128
	v_mul_f32_e32 v36, v38, v36
	v_mfma_f32_32x32x16_bf16 v[0:15], v[84:87], v[32:35], v[0:15]
	v_log_f32_e32 v36, v36
	s_nop 0
	v_add_f32_e32 v126, v126, v36
	v_mfma_f32_32x32x16_bf16 v[16:31], v[80:83], v[32:35], v[16:31]

; #define PG8_LAS __attribute__((address_space(3)))
; __device__ __forceinline__ u32x4 pack8(const f32x4& a, const f32x4& b) { u32x4 w; w.x = cvt_pk_bf16(a[0], a[1]); w.y = cvt_pk_bf16(a[2], a[3]); w.z = cvt_pk_bf16(b[0], b[1]); w.w = cvt_pk_bf16(b[2], b[3]); return w; }
; __device__ __forceinline__ void store_rows16(PG8_LAS unsigned char* stg, bf16_t* gbase, size_t ld, int fr, int fq, const u32x4& w0, const u32x4& w1) {
;     *(PG8_LAS u32x4*)(stg + fr * 144 + fq * 16) = w0; *(PG8_LAS u32x4*)(stg + fr * 144 + 64 + fq * 16) = w1;
;     const int lane = fr + 16 * fq;
; #pragma unroll
;     for (int j = 0; j < 2; ++j) { const int c = lane + 64 * j, row = c >> 3, ch = c & 7; const u32x4 v = *(const PG8_LAS u32x4*)(stg + row * 144 + ch * 16); *(u32x4*)(gbase + (size_t)row * ld + ch * 8) = v; }
;     __device__ __forceinline__ void operator()(const f32x4 (&acc)[2][2][4][2], const Unit& u, int wr, int wc, int fr, int fq) const {
;     ...
;             for (int m = 0; m < 4; ++m) { const int R = row0 + ai * HALF + m * 16;
;                 u32x4 wv[2];
; #pragma unroll
;                 for (int bj = 0; bj < 2; ++bj) { f32x4 v0 = acc[ai][bj][m][0], v1 = acc[ai][bj][m][1];
; #pragma unroll
;                     for (int e = 0; e < 4; ++e) { const float a = fmaxf(v0[e], 0.f), b = fmaxf(v1[e], 0.f); v0[e] = a * a; v1[e] = b * b; }
;                     wv[bj] = pack8(v0, v1); }
;                 store_rows16(stg + (wr * 4 + wc) * EPI_STG_WAVE, U + (size_t)(R - fr) * 4096 + col0 - 8 * fq, 4096, fr, fq, wv[0], wv[1]); }
.LBB0_661:
	s_lshl_b32 s11, s18, 8
	v_max_f32_e32 v120, 0, v120
	v_max_f32_e32 v121, 0, v121
	s_add_i32 s18, s11, s38
	v_pk_mul_f32 v[162:163], v[120:121], v[120:121]
	v_lshl_or_b32 v160, s19, 8, v153
	v_max_f32_e32 v122, 0, v122
	s_ashr_i32 s19, s18, 31
	v_max_f32_e32 v124, 0, v124
	v_max_f32_e32 v125, 0, v125
	v_max_f32_e32 v120, 0, v126
	v_max_f32_e32 v121, 0, v127
	v_max_f32_e32 v123, 0, v123
	v_max_f32_e32 v116, 0, v116
	v_max_f32_e32 v112, 0, v112
	v_max_f32_e32 v117, 0, v117
	v_max_f32_e32 v113, 0, v113
	s_lshl_b64 s[20:21], s[18:19], 13
	v_readlane_b32 s22, v254, 32
	v_ashrrev_i32_e32 v161, 31, v160
	v_pk_mul_f32 v[124:125], v[124:125], v[124:125]
	v_pk_mul_f32 v[126:127], v[120:121], v[120:121]
	v_pk_mul_f32 v[164:165], v[122:123], v[122:123]
	v_pk_mul_f32 v[116:117], v[116:117], v[116:117]
	v_pk_mul_f32 v[112:113], v[112:113], v[112:113]
	v_max_f32_e32 v118, 0, v118
	v_max_f32_e32 v114, 0, v114
	v_max_f32_e32 v119, 0, v119
	v_max_f32_e32 v115, 0, v115
	v_readlane_b32 s23, v254, 33
	s_add_u32 s20, s22, s20
	v_cvt_pk_bf16_f32 v120, v124, v125
	v_cvt_pk_bf16_f32 v121, v126, v127
	v_cvt_pk_bf16_f32 v122, v162, v163
	v_cvt_pk_bf16_f32 v123, v164, v165
	v_pk_mul_f32 v[118:119], v[118:119], v[118:119]
	v_pk_mul_f32 v[124:125], v[114:115], v[114:115]
	v_cvt_pk_bf16_f32 v114, v116, v117
	v_cvt_pk_bf16_f32 v116, v112, v113
	s_addc_u32 s21, s23, s21
	v_lshlrev_b64 v[112:113], 1, v[160:161]
	v_cvt_pk_bf16_f32 v115, v118, v119
	v_cvt_pk_bf16_f32 v117, v124, v125
	v_lshl_add_u64 v[118:119], s[20:21], 0, v[112:113]
	ds_write_b128 v157, v[120:123]
	ds_write_b128 v157, v[114:117] offset:64
	v_lshl_add_u64 v[118:119], v[118:119], 0, v[146:147]
	ds_read_b128 v[114:117], v158
	v_lshl_add_u64 v[122:123], v[118:119], 0, v[136:137]
	ds_read_b128 v[118:121], v158 offset:1152
	v_mov_b32_e32 v149, v137
	v_lshl_add_u64 v[124:125], v[122:123], 0, v[148:149]
	v_mov_b32_e32 v151, v137
	s_waitcnt lgkmcnt(0)
	global_store_dwordx4 v[124:125], v[114:117], off
	v_max_f32_e32 v104, 0, v104
	v_max_f32_e32 v105, 0, v105
	v_lshl_add_u64 v[114:115], v[122:123], 0, v[150:151]
	global_store_dwordx4 v[114:115], v[118:121], off
	v_pk_mul_f32 v[114:115], v[104:105], v[104:105]
	v_max_f32_e32 v108, 0, v108
	v_max_f32_e32 v109, 0, v109
	v_max_f32_e32 v106, 0, v106
	v_pk_mul_f32 v[108:109], v[108:109], v[108:109]
	v_max_f32_e32 v104, 0, v110
	v_max_f32_e32 v105, 0, v111
	v_max_f32_e32 v96, 0, v96
	v_max_f32_e32 v97, 0, v97
	v_pk_mul_f32 v[110:111], v[104:105], v[104:105]
	v_cvt_pk_bf16_f32 v104, v108, v109
	v_pk_mul_f32 v[108:109], v[96:97], v[96:97]
	s_or_b32 s20, s18, 16
	v_max_f32_e32 v107, 0, v107
	v_max_f32_e32 v98, 0, v98
	s_ashr_i32 s21, s20, 31
	v_pk_mul_f32 v[116:117], v[106:107], v[106:107]
	v_max_f32_e32 v100, 0, v100
	v_max_f32_e32 v101, 0, v101
	v_max_f32_e32 v96, 0, v102
	v_max_f32_e32 v97, 0, v103
	v_max_f32_e32 v99, 0, v99
	s_lshl_b64 s[20:21], s[20:21], 13
	v_cvt_pk_bf16_f32 v105, v110, v111
	v_cvt_pk_bf16_f32 v106, v114, v115
	v_cvt_pk_bf16_f32 v107, v116, v117
	v_pk_mul_f32 v[100:101], v[100:101], v[100:101]
	v_pk_mul_f32 v[102:103], v[96:97], v[96:97]
	v_pk_mul_f32 v[110:111], v[98:99], v[98:99]
	s_add_u32 s20, s22, s20
	v_cvt_pk_bf16_f32 v96, v100, v101
	v_cvt_pk_bf16_f32 v97, v102, v103
	v_cvt_pk_bf16_f32 v98, v108, v109
	v_cvt_pk_bf16_f32 v99, v110, v111
	s_addc_u32 s21, s23, s21
	ds_write_b128 v157, v[104:107]
	ds_write_b128 v157, v[96:99] offset:64
	v_lshl_add_u64 v[100:101], s[20:21], 0, v[112:113]
	ds_read_b128 v[96:99], v158
	v_lshl_add_u64 v[104:105], v[100:101], 0, v[146:147]
	ds_read_b128 v[100:103], v158 offset:1152
	v_lshl_add_u64 v[104:105], v[104:105], 0, v[136:137]
	v_lshl_add_u64 v[106:107], v[104:105], 0, v[148:149]
	s_waitcnt lgkmcnt(0)
	global_store_dwordx4 v[106:107], v[96:99], off
	v_max_f32_e32 v88, 0, v88
	v_max_f32_e32 v89, 0, v89
	v_lshl_add_u64 v[96:97], v[104:105], 0, v[150:151]
	global_store_dwordx4 v[96:97], v[100:103], off
	v_pk_mul_f32 v[96:97], v[88:89], v[88:89]
	v_max_f32_e32 v92, 0, v92
	v_max_f32_e32 v93, 0, v93
	v_max_f32_e32 v90, 0, v90
	v_pk_mul_f32 v[92:93], v[92:93], v[92:93]
	v_max_f32_e32 v88, 0, v94
	v_max_f32_e32 v89, 0, v95
	v_max_f32_e32 v80, 0, v80
	v_max_f32_e32 v81, 0, v81
	v_pk_mul_f32 v[94:95], v[88:89], v[88:89]
	v_cvt_pk_bf16_f32 v88, v92, v93
	v_pk_mul_f32 v[92:93], v[80:81], v[80:81]
	s_or_b32 s20, s18, 32
	v_max_f32_e32 v91, 0, v91
	v_max_f32_e32 v82, 0, v82
	s_ashr_i32 s21, s20, 31
	v_pk_mul_f32 v[98:99], v[90:91], v[90:91]
	v_max_f32_e32 v84, 0, v84
	v_max_f32_e32 v85, 0, v85
	v_max_f32_e32 v80, 0, v86
	v_max_f32_e32 v81, 0, v87
	v_max_f32_e32 v83, 0, v83
	s_lshl_b64 s[20:21], s[20:21], 13
	v_cvt_pk_bf16_f32 v89, v94, v95
	v_cvt_pk_bf16_f32 v90, v96, v97
	v_cvt_pk_bf16_f32 v91, v98, v99
	v_pk_mul_f32 v[84:85], v[84:85], v[84:85]
	v_pk_mul_f32 v[86:87], v[80:81], v[80:81]
	v_pk_mul_f32 v[94:95], v[82:83], v[82:83]
	s_add_u32 s20, s22, s20
	v_cvt_pk_bf16_f32 v80, v84, v85
	v_cvt_pk_bf16_f32 v81, v86, v87
	v_cvt_pk_bf16_f32 v82, v92, v93
	v_cvt_pk_bf16_f32 v83, v94, v95
	s_addc_u32 s21, s23, s21
	ds_write_b128 v157, v[88:91]
	ds_write_b128 v157, v[80:83] offset:64
	v_lshl_add_u64 v[84:85], s[20:21], 0, v[112:113]
	ds_read_b128 v[80:83], v158
	v_lshl_add_u64 v[88:89], v[84:85], 0, v[146:147]
	ds_read_b128 v[84:87], v158 offset:1152
	v_lshl_add_u64 v[88:89], v[88:89], 0, v[136:137]
	v_lshl_add_u64 v[90:91], v[88:89], 0, v[148:149]
	s_waitcnt lgkmcnt(0)
; #define PG8_LAS __attribute__((address_space(3)))
; __device__ __forceinline__ u32x4 pack8(const f32x4& a, const f32x4& b) { u32x4 w; w.x = cvt_pk_bf16(a[0], a[1]); w.y = cvt_pk_bf16(a[2], a[3]); w.z = cvt_pk_bf16(b[0], b[1]); w.w = cvt_pk_bf16(b[2], b[3]); return w; }
; __device__ __forceinline__ void store_rows16(PG8_LAS unsigned char* stg, bf16_t* gbase, size_t ld, int fr, int fq, const u32x4& w0, const u32x4& w1) {
;     *(PG8_LAS u32x4*)(stg + fr * 144 + fq * 16) = w0; *(PG8_LAS u32x4*)(stg + fr * 144 + 64 + fq * 16) = w1;
;     const int lane = fr + 16 * fq;
; #pragma unroll
;     for (int j = 0; j < 2; ++j) { const int c = lane + 64 * j, row = c >> 3, ch = c & 7; const u32x4 v = *(const PG8_LAS u32x4*)(stg + row * 144 + ch * 16); *(u32x4*)(gbase + (size_t)row * ld + ch * 8) = v; }
;     __device__ __forceinline__ void operator()(const f32x4 (&acc)[2][2][4][2], const Unit& u, int wr, int wc, int fr, int fq) const {
;     ...
;             for (int m = 0; m < 4; ++m) { const int R = row0 + ai * HALF + m * 16;
;                 u32x4 wv[2];
; #pragma unroll
;                 for (int bj = 0; bj < 2; ++bj) { f32x4 v0 = acc[ai][bj][m][0], v1 = acc[ai][bj][m][1];
; #pragma unroll
;                     for (int e = 0; e < 4; ++e) { const float a = fmaxf(v0[e], 0.f), b = fmaxf(v1[e], 0.f); v0[e] = a * a; v1[e] = b * b; }
;                     wv[bj] = pack8(v0, v1); }
;                 store_rows16(stg + (wr * 4 + wc) * EPI_STG_WAVE, U + (size_t)(R - fr) * 4096 + col0 - 8 * fq, 4096, fr, fq, wv[0], wv[1]); }
	global_store_dwordx4 v[90:91], v[80:83], off
	v_max_f32_e32 v72, 0, v72
	v_max_f32_e32 v73, 0, v73
	v_lshl_add_u64 v[80:81], v[88:89], 0, v[150:151]
	global_store_dwordx4 v[80:81], v[84:87], off
	v_pk_mul_f32 v[80:81], v[72:73], v[72:73]
	v_max_f32_e32 v76, 0, v76
	v_max_f32_e32 v77, 0, v77
	v_max_f32_e32 v74, 0, v74
	v_pk_mul_f32 v[76:77], v[76:77], v[76:77]
	v_max_f32_e32 v72, 0, v78
	v_max_f32_e32 v73, 0, v79
	v_max_f32_e32 v64, 0, v64
	v_max_f32_e32 v65, 0, v65
	v_pk_mul_f32 v[78:79], v[72:73], v[72:73]
	v_cvt_pk_bf16_f32 v72, v76, v77
	v_pk_mul_f32 v[76:77], v[64:65], v[64:65]
	s_or_b32 s20, s18, 48
	v_max_f32_e32 v75, 0, v75
	v_max_f32_e32 v66, 0, v66
	s_ashr_i32 s21, s20, 31
	v_pk_mul_f32 v[82:83], v[74:75], v[74:75]
	v_max_f32_e32 v68, 0, v68
	v_max_f32_e32 v69, 0, v69
	v_max_f32_e32 v64, 0, v70
	v_max_f32_e32 v65, 0, v71
	v_max_f32_e32 v67, 0, v67
	s_lshl_b64 s[20:21], s[20:21], 13
	v_cvt_pk_bf16_f32 v73, v78, v79
	v_cvt_pk_bf16_f32 v74, v80, v81
	v_cvt_pk_bf16_f32 v75, v82, v83
	v_pk_mul_f32 v[68:69], v[68:69], v[68:69]
	v_pk_mul_f32 v[70:71], v[64:65], v[64:65]
	v_pk_mul_f32 v[78:79], v[66:67], v[66:67]
	s_add_u32 s20, s22, s20
	v_cvt_pk_bf16_f32 v64, v68, v69
	v_cvt_pk_bf16_f32 v65, v70, v71
	v_cvt_pk_bf16_f32 v66, v76, v77
	v_cvt_pk_bf16_f32 v67, v78, v79
	s_addc_u32 s21, s23, s21
	ds_write_b128 v157, v[72:75]
	ds_write_b128 v157, v[64:67] offset:64
	v_lshl_add_u64 v[68:69], s[20:21], 0, v[112:113]
	ds_read_b128 v[64:67], v158
	v_lshl_add_u64 v[72:73], v[68:69], 0, v[146:147]
	ds_read_b128 v[68:71], v158 offset:1152
	v_lshl_add_u64 v[72:73], v[72:73], 0, v[136:137]
	v_lshl_add_u64 v[74:75], v[72:73], 0, v[148:149]
	s_waitcnt lgkmcnt(0)
	global_store_dwordx4 v[74:75], v[64:67], off
	v_max_f32_e32 v56, 0, v56
	v_max_f32_e32 v57, 0, v57
	v_lshl_add_u64 v[64:65], v[72:73], 0, v[150:151]
	global_store_dwordx4 v[64:65], v[68:71], off
	v_pk_mul_f32 v[64:65], v[56:57], v[56:57]
	v_max_f32_e32 v60, 0, v60
	v_max_f32_e32 v61, 0, v61
	v_max_f32_e32 v58, 0, v58
	v_pk_mul_f32 v[60:61], v[60:61], v[60:61]
	v_max_f32_e32 v56, 0, v62
	v_max_f32_e32 v57, 0, v63
	v_max_f32_e32 v48, 0, v48
	v_max_f32_e32 v49, 0, v49
	s_add_i32 s20, s18, 0x80
	v_pk_mul_f32 v[62:63], v[56:57], v[56:57]
	v_cvt_pk_bf16_f32 v56, v60, v61
	v_pk_mul_f32 v[60:61], v[48:49], v[48:49]
	v_max_f32_e32 v59, 0, v59
	v_max_f32_e32 v50, 0, v50
	s_ashr_i32 s21, s20, 31
	v_pk_mul_f32 v[66:67], v[58:59], v[58:59]
	v_max_f32_e32 v52, 0, v52
	v_max_f32_e32 v53, 0, v53
	v_max_f32_e32 v48, 0, v54
	v_max_f32_e32 v49, 0, v55
	v_max_f32_e32 v51, 0, v51
	s_lshl_b64 s[20:21], s[20:21], 13
	v_cvt_pk_bf16_f32 v57, v62, v63
	v_cvt_pk_bf16_f32 v58, v64, v65
	v_cvt_pk_bf16_f32 v59, v66, v67
	v_pk_mul_f32 v[52:53], v[52:53], v[52:53]
	v_pk_mul_f32 v[54:55], v[48:49], v[48:49]
	v_pk_mul_f32 v[62:63], v[50:51], v[50:51]
	s_add_u32 s20, s22, s20
	v_cvt_pk_bf16_f32 v48, v52, v53
	v_cvt_pk_bf16_f32 v49, v54, v55
	v_cvt_pk_bf16_f32 v50, v60, v61
	v_cvt_pk_bf16_f32 v51, v62, v63
	s_addc_u32 s21, s23, s21
	ds_write_b128 v157, v[56:59]
	ds_write_b128 v157, v[48:51] offset:64
	v_lshl_add_u64 v[52:53], s[20:21], 0, v[112:113]
	ds_read_b128 v[48:51], v158
	v_lshl_add_u64 v[56:57], v[52:53], 0, v[146:147]
	ds_read_b128 v[52:55], v158 offset:1152
	v_lshl_add_u64 v[56:57], v[56:57], 0, v[136:137]
	v_lshl_add_u64 v[58:59], v[56:57], 0, v[148:149]
	s_waitcnt lgkmcnt(0)
	global_store_dwordx4 v[58:59], v[48:51], off
	v_max_f32_e32 v40, 0, v40
	v_max_f32_e32 v41, 0, v41
	v_lshl_add_u64 v[48:49], v[56:57], 0, v[150:151]
	global_store_dwordx4 v[48:49], v[52:55], off
	v_pk_mul_f32 v[48:49], v[40:41], v[40:41]
	v_max_f32_e32 v44, 0, v44
	v_max_f32_e32 v45, 0, v45
	v_max_f32_e32 v42, 0, v42
	v_pk_mul_f32 v[44:45], v[44:45], v[44:45]
	v_max_f32_e32 v40, 0, v46
	v_max_f32_e32 v41, 0, v47
	v_max_f32_e32 v32, 0, v32
	v_max_f32_e32 v33, 0, v33
	v_pk_mul_f32 v[46:47], v[40:41], v[40:41]
	v_cvt_pk_bf16_f32 v40, v44, v45
	v_pk_mul_f32 v[44:45], v[32:33], v[32:33]
	s_add_i32 s20, s18, 0x90
	v_max_f32_e32 v43, 0, v43
	v_max_f32_e32 v34, 0, v34
	s_ashr_i32 s21, s20, 31
	v_pk_mul_f32 v[50:51], v[42:43], v[42:43]
	v_max_f32_e32 v36, 0, v36
	v_max_f32_e32 v37, 0, v37
	v_max_f32_e32 v32, 0, v38
	v_max_f32_e32 v33, 0, v39
	v_max_f32_e32 v35, 0, v35
	s_lshl_b64 s[20:21], s[20:21], 13
	v_cvt_pk_bf16_f32 v41, v46, v47
	v_cvt_pk_bf16_f32 v42, v48, v49
	v_cvt_pk_bf16_f32 v43, v50, v51
	v_pk_mul_f32 v[36:37], v[36:37], v[36:37]
	v_pk_mul_f32 v[38:39], v[32:33], v[32:33]
	v_pk_mul_f32 v[46:47], v[34:35], v[34:35]
	s_add_u32 s20, s22, s20
	v_cvt_pk_bf16_f32 v32, v36, v37
	v_cvt_pk_bf16_f32 v33, v38, v39
	v_cvt_pk_bf16_f32 v34, v44, v45
	v_cvt_pk_bf16_f32 v35, v46, v47
	s_addc_u32 s21, s23, s21
	ds_write_b128 v157, v[40:43]
	ds_write_b128 v157, v[32:35] offset:64
	v_lshl_add_u64 v[36:37], s[20:21], 0, v[112:113]
	ds_read_b128 v[32:35], v158
	v_lshl_add_u64 v[40:41], v[36:37], 0, v[146:147]
	ds_read_b128 v[36:39], v158 offset:1152
	v_lshl_add_u64 v[40:41], v[40:41], 0, v[136:137]
	v_lshl_add_u64 v[42:43], v[40:41], 0, v[148:149]
	s_waitcnt lgkmcnt(0)
; #define PG8_LAS __attribute__((address_space(3)))
; __device__ __forceinline__ u32x4 pack8(const f32x4& a, const f32x4& b) { u32x4 w; w.x = cvt_pk_bf16(a[0], a[1]); w.y = cvt_pk_bf16(a[2], a[3]); w.z = cvt_pk_bf16(b[0], b[1]); w.w = cvt_pk_bf16(b[2], b[3]); return w; }
; __device__ __forceinline__ void store_rows16(PG8_LAS unsigned char* stg, bf16_t* gbase, size_t ld, int fr, int fq, const u32x4& w0, const u32x4& w1) {
;     *(PG8_LAS u32x4*)(stg + fr * 144 + fq * 16) = w0; *(PG8_LAS u32x4*)(stg + fr * 144 + 64 + fq * 16) = w1;
;     const int lane = fr + 16 * fq;
; #pragma unroll
;     for (int j = 0; j < 2; ++j) { const int c = lane + 64 * j, row = c >> 3, ch = c & 7; const u32x4 v = *(const PG8_LAS u32x4*)(stg + row * 144 + ch * 16); *(u32x4*)(gbase + (size_t)row * ld + ch * 8) = v; }
;     __device__ __forceinline__ void operator()(const f32x4 (&acc)[2][2][4][2], const Unit& u, int wr, int wc, int fr, int fq) const {
;     ...
;             for (int m = 0; m < 4; ++m) { const int R = row0 + ai * HALF + m * 16;
;                 u32x4 wv[2];
; #pragma unroll
;                 for (int bj = 0; bj < 2; ++bj) { f32x4 v0 = acc[ai][bj][m][0], v1 = acc[ai][bj][m][1];
; #pragma unroll
;                     for (int e = 0; e < 4; ++e) { const float a = fmaxf(v0[e], 0.f), b = fmaxf(v1[e], 0.f); v0[e] = a * a; v1[e] = b * b; }
;                     wv[bj] = pack8(v0, v1); }
;                 store_rows16(stg + (wr * 4 + wc) * EPI_STG_WAVE, U + (size_t)(R - fr) * 4096 + col0 - 8 * fq, 4096, fr, fq, wv[0], wv[1]); }
	global_store_dwordx4 v[42:43], v[32:35], off
	v_max_f32_e32 v24, 0, v24
	v_max_f32_e32 v25, 0, v25
	v_lshl_add_u64 v[32:33], v[40:41], 0, v[150:151]
	global_store_dwordx4 v[32:33], v[36:39], off
	v_pk_mul_f32 v[32:33], v[24:25], v[24:25]
	v_max_f32_e32 v28, 0, v28
	v_max_f32_e32 v29, 0, v29
	v_max_f32_e32 v26, 0, v26
	v_pk_mul_f32 v[28:29], v[28:29], v[28:29]
	v_max_f32_e32 v24, 0, v30
	v_max_f32_e32 v25, 0, v31
	v_max_f32_e32 v16, 0, v16
	v_max_f32_e32 v17, 0, v17
	v_pk_mul_f32 v[30:31], v[24:25], v[24:25]
	v_cvt_pk_bf16_f32 v24, v28, v29
	v_pk_mul_f32 v[28:29], v[16:17], v[16:17]
	s_add_i32 s20, s18, 0xa0
	v_max_f32_e32 v27, 0, v27
	v_max_f32_e32 v18, 0, v18
	s_ashr_i32 s21, s20, 31
	v_pk_mul_f32 v[34:35], v[26:27], v[26:27]
	v_max_f32_e32 v20, 0, v20
	v_max_f32_e32 v21, 0, v21
	v_max_f32_e32 v16, 0, v22
	v_max_f32_e32 v17, 0, v23
	v_max_f32_e32 v19, 0, v19
	s_lshl_b64 s[20:21], s[20:21], 13
	v_cvt_pk_bf16_f32 v25, v30, v31
	v_cvt_pk_bf16_f32 v26, v32, v33
	v_cvt_pk_bf16_f32 v27, v34, v35
	v_pk_mul_f32 v[20:21], v[20:21], v[20:21]
	v_pk_mul_f32 v[22:23], v[16:17], v[16:17]
	v_pk_mul_f32 v[30:31], v[18:19], v[18:19]
	s_add_u32 s20, s22, s20
	v_cvt_pk_bf16_f32 v16, v20, v21
	v_cvt_pk_bf16_f32 v17, v22, v23
	v_cvt_pk_bf16_f32 v18, v28, v29
	v_cvt_pk_bf16_f32 v19, v30, v31
	s_addc_u32 s21, s23, s21
	ds_write_b128 v157, v[24:27]
	ds_write_b128 v157, v[16:19] offset:64
	v_lshl_add_u64 v[20:21], s[20:21], 0, v[112:113]
	ds_read_b128 v[16:19], v158
	v_lshl_add_u64 v[24:25], v[20:21], 0, v[146:147]
	ds_read_b128 v[20:23], v158 offset:1152
	v_lshl_add_u64 v[24:25], v[24:25], 0, v[136:137]
	v_lshl_add_u64 v[26:27], v[24:25], 0, v[148:149]
	s_waitcnt lgkmcnt(0)
	global_store_dwordx4 v[26:27], v[16:19], off
	v_max_f32_e32 v8, 0, v8
	v_max_f32_e32 v9, 0, v9
	v_lshl_add_u64 v[16:17], v[24:25], 0, v[150:151]
	global_store_dwordx4 v[16:17], v[20:23], off
	v_pk_mul_f32 v[16:17], v[8:9], v[8:9]
	v_max_f32_e32 v12, 0, v12
	v_max_f32_e32 v13, 0, v13
	v_max_f32_e32 v10, 0, v10
	v_pk_mul_f32 v[12:13], v[12:13], v[12:13]
	v_max_f32_e32 v8, 0, v14
	v_max_f32_e32 v9, 0, v15
	v_max_f32_e32 v0, 0, v0
	v_max_f32_e32 v1, 0, v1
	v_pk_mul_f32 v[14:15], v[8:9], v[8:9]
	v_cvt_pk_bf16_f32 v8, v12, v13
	v_pk_mul_f32 v[12:13], v[0:1], v[0:1]
	s_addk_i32 s18, 0xb0
	v_max_f32_e32 v11, 0, v11
	v_max_f32_e32 v2, 0, v2
	s_ashr_i32 s19, s18, 31
	v_pk_mul_f32 v[18:19], v[10:11], v[10:11]
	v_max_f32_e32 v4, 0, v4
	v_max_f32_e32 v5, 0, v5
	v_max_f32_e32 v0, 0, v6
	v_max_f32_e32 v1, 0, v7
	v_max_f32_e32 v3, 0, v3
	s_lshl_b64 s[18:19], s[18:19], 13
	v_cvt_pk_bf16_f32 v9, v14, v15
	v_cvt_pk_bf16_f32 v10, v16, v17
	v_cvt_pk_bf16_f32 v11, v18, v19
	v_pk_mul_f32 v[4:5], v[4:5], v[4:5]
	v_pk_mul_f32 v[6:7], v[0:1], v[0:1]
	v_pk_mul_f32 v[14:15], v[2:3], v[2:3]
	s_add_u32 s18, s22, s18
	v_cvt_pk_bf16_f32 v0, v4, v5
	v_cvt_pk_bf16_f32 v1, v6, v7
	v_cvt_pk_bf16_f32 v2, v12, v13
	v_cvt_pk_bf16_f32 v3, v14, v15
	s_addc_u32 s19, s23, s19
	ds_write_b128 v157, v[8:11]
	ds_write_b128 v157, v[0:3] offset:64
	v_lshl_add_u64 v[4:5], s[18:19], 0, v[112:113]
	ds_read_b128 v[0:3], v158
	v_lshl_add_u64 v[8:9], v[4:5], 0, v[146:147]
	ds_read_b128 v[4:7], v158 offset:1152
	v_lshl_add_u64 v[8:9], v[8:9], 0, v[136:137]
	v_lshl_add_u64 v[10:11], v[8:9], 0, v[148:149]
	s_waitcnt lgkmcnt(0)
	global_store_dwordx4 v[10:11], v[0:3], off
	s_andn2_b64 vcc, exec, s[2:3]
	s_mov_b64 s[2:3], -1
	v_lshl_add_u64 v[0:1], v[8:9], 0, v[150:151]
	global_store_dwordx4 v[0:1], v[4:7], off
	s_cbranch_vccnz .LBB0_650
	s_andn2_b64 vcc, exec, s[4:5]
	s_cbranch_vccnz .LBB0_649
	s_barrier
	s_branch .LBB0_649
